# v061 + GEMM K-loops: first iteration after each tile boundary skips the phase-4 counted wait (older stages waited before the epilogue stores) and waits vmcnt(10) at phase 6 instead; stale vmcnt(0) bef
# baseline (speedup 1.0000x reference)
; #define G_STAGE(bufoff, gbase, voff) do { _Pragma("unroll") for (int _i = 0; _i < 2; ++_i) \
;         __builtin_amdgcn_global_load_lds((const unsigned*)((const char*)(gbase) + (voff)[_i]), (LAS unsigned*)(lds + (bufoff) + ldsw + _i * 8192), 16, 0, 0); } while (0)
; #define G_WAIT_V(n) asm volatile("s_waitcnt vmcnt(" #n ")" ::: "memory")
; #define G_BAR __builtin_amdgcn_s_barrier()
; template <bool PERM, class Dec, class Epi>
; DI void gemm_phase(LAS unsigned char* lds, const int nM, const int nN, const int K, const int lda, const int ldb, const Dec& dec, const Epi& epi, const int vb, const int panel = -1) {
;     ...
;     for (int i = 0; i < 2; ++i) { int R, C; stage_rc(tid * 16 + i * 8192, R, C); const int Rb = PERM ? ((R & ~31) + perm32(R & 31)) : R;
;         voffA[i] = (unsigned)(R * lda + C) * 2u; voffB[i] = (unsigned)(Rb * ldb + C) * 2u; }
;     const size_t kstep = (size_t)(BK * 2);
;     const size_t hstepA = (size_t)HALF * lda * 2, hstepB = (size_t)HALF * ldb * 2;
;     const unsigned ldsw = (unsigned)wid * 1024u;
;     const int aoff = lds_byte(wr * 64 + fr, fq * 8), boff = lds_byte(wc * 32 + fr, fq * 8);
;     ...
;     G_STAGE(G_SB(0, 0), cB, voffB); G_STAGE(G_SA(0, 0), cA, voffA); G_STAGE(G_SB(0, 1), cB + hstepB, voffB); G_STAGE(G_SA(0, 1), cA + hstepA, voffA);
;     if (wr == 1) G_BAR;
;     G_WAIT_V(4); G_BAR;
;     G_STAGE(G_SB(1, 0), cB + kstep, voffB); G_STAGE(G_SA(1, 0), cA + kstep, voffA); G_STAGE(G_SB(1, 1), cB + hstepB + kstep, voffB);
;     G_WAIT_V(6); G_BAR;
.LBB0_178:
	v_mov_b32_e32 v139, v129
	v_lshl_add_u64 v[8:9], s[4:5], 0, v[138:139]
	v_mov_b32_e32 v135, v129
	v_lshl_add_u64 v[10:11], s[4:5], 0, v[134:135]
	v_mov_b32_e32 v141, v129
	s_add_i32 m0, s56, 0x18000
	v_lshl_add_u64 v[8:9], v[8:9], 0, s[30:31]
	v_lshl_add_u64 v[12:13], s[6:7], 0, v[140:141]
	v_mov_b32_e32 v137, v129
	s_waitcnt vmcnt(4)
	s_barrier
	global_load_lds_dwordx4 v[8:9], off
	v_lshl_add_u64 v[8:9], v[10:11], 0, s[30:31]
	s_add_i32 m0, s56, 0x1a000
	s_add_i32 s60, s56, 0x8000
	v_lshl_add_u64 v[14:15], s[6:7], 0, v[136:137]
	global_load_lds_dwordx4 v[8:9], off
	v_lshl_add_u64 v[8:9], v[12:13], 0, s[30:31]
	s_mov_b32 m0, s60
	s_add_i32 s61, s56, 0xa000
	global_load_lds_dwordx4 v[8:9], off
	v_lshl_add_u64 v[8:9], v[14:15], 0, s[30:31]
	s_mov_b32 m0, s61
	s_lshl_b32 s2, s2, 5
	global_load_lds_dwordx4 v[8:9], off
	s_add_i32 m0, s56, 0x1c000
	v_lshl_add_u64 v[8:9], s[28:29], 0, v[138:139]
	global_load_lds_dwordx4 v[8:9], off
	v_lshl_add_u64 v[8:9], s[28:29], 0, v[134:135]
	s_add_i32 m0, s56, 0x1e000
	v_and_b32_e32 v7, 15, v3
	global_load_lds_dwordx4 v[8:9], off
	v_lshrrev_b32_e32 v9, 1, v3
	v_and_b32_e32 v10, 24, v9
	v_lshlrev_b32_e32 v9, 1, v10
	v_lshlrev_b32_e32 v3, 2, v3
	s_and_b32 s22, s2, 0x60
	v_lshl_or_b32 v8, s3, 6, v7
	v_lshl_or_b32 v7, v7, 6, v9
	s_lshl_b32 s3, s3, 13
	v_and_b32_e32 v3, 32, v3
	s_lshl_b32 s2, s22, 7
	v_bitop3_b32 v11, v7, s3, v3 bitop3:0xde
	v_bitop3_b32 v163, v7, s2, v3 bitop3:0xde
	v_lshlrev_b32_e32 v3, 14, v5
	v_and_b32_e32 v3, 0xffff8000, v3
	v_lshl_add_u32 v3, v4, 11, v3
	v_and_b32_e32 v4, 1, v5
	v_ashrrev_i32_e32 v9, 31, v8
	v_lshl_or_b32 v3, v4, 6, v3
	v_lshlrev_b64 v[142:143], 12, v[8:9]
	v_or_b32_e32 v12, 16, v8
	s_mov_b64 s[2:3], 0x80000
	v_lshl_add_u32 v158, v6, 1, v3
	v_lshlrev_b32_e32 v3, 14, v0
	v_ashrrev_i32_e32 v13, 31, v12
	v_lshl_add_u64 v[150:151], v[142:143], 0, s[2:3]
	s_mov_b64 s[2:3], 0x90000
	v_and_b32_e32 v3, 0xffff8000, v3
	s_waitcnt vmcnt(0)
	v_lshlrev_b64 v[144:145], 12, v[12:13]
	v_or_b32_e32 v12, 32, v8
	v_or_b32_e32 v8, 48, v8
	v_lshl_add_u64 v[152:153], v[142:143], 0, s[2:3]
	s_mov_b64 s[2:3], 0xa0000
	v_lshl_add_u32 v1, v1, 11, v3
	v_and_b32_e32 v0, 1, v0
	v_ashrrev_i32_e32 v13, 31, v12
	v_ashrrev_i32_e32 v9, 31, v8
	v_lshl_add_u64 v[154:155], v[142:143], 0, s[2:3]
	s_mov_b64 s[2:3], 0xb0000
	v_lshl_or_b32 v0, v0, 6, v1
	v_lshlrev_b64 v[146:147], 12, v[12:13]
	v_lshlrev_b64 v[148:149], 12, v[8:9]
	v_lshl_add_u64 v[156:157], v[142:143], 0, s[2:3]
	v_mov_b32_e32 v159, v129
	v_lshl_add_u32 v160, v2, 1, v0
	v_mov_b32_e32 v161, v129
	s_mov_b32 s66, 0
	v_add_u32_e32 v164, 0, v11
	s_lshl_b32 s67, s22, 1
	v_lshlrev_b32_e32 v128, 1, v10
	s_mov_b32 s22, s0
	s_mov_b32 s70, s33
	s_mov_b64 s[44:45], s[6:7]
	s_mov_b64 s[46:47], s[4:5]
	s_barrier

; #define G_STAGE(bufoff, gbase, voff) do { _Pragma("unroll") for (int _i = 0; _i < 2; ++_i) \
;         __builtin_amdgcn_global_load_lds((const unsigned*)((const char*)(gbase) + (voff)[_i]), (LAS unsigned*)(lds + (bufoff) + ldsw + _i * 8192), 16, 0, 0); } while (0)
; #define G_LDA(dst, b, h) do { _Pragma("unroll") for (int m = 0; m < 4; ++m) _Pragma("unroll") for (int k = 0; k < 2; ++k) dst[m][k] = *(const LAS bf16x8*)(lds + G_SA(b, h) + aoff + m * 2048 + k * 1024); } while (0)
; #define G_LDB(dst, b, h) do { _Pragma("unroll") for (int n = 0; n < 2; ++n) _Pragma("unroll") for (int k = 0; k < 2; ++k) dst[n][k] = *(const LAS bf16x8*)(lds + G_SB(b, h) + boff + n * 2048 + k * 1024); } while (0)
; #define G_MMA(ai, bj, At, Bt) do { __builtin_amdgcn_s_setprio(1); _Pragma("unroll") for (int m = 0; m < 4; ++m) _Pragma("unroll") for (int n = 0; n < 2; ++n) _Pragma("unroll") for (int k = 0; k < 2; ++k) \
;         acc[ai][bj][m][n] = __builtin_amdgcn_mfma_f32_16x16x32_bf16(Bt[n][k], At[m][k], acc[ai][bj][m][n], 0, 0, 0); __builtin_amdgcn_s_setprio(0); } while (0)
; #define G_WAIT_V(n) asm volatile("s_waitcnt vmcnt(" #n ")" ::: "memory")
; #define G_WAIT_L(n) asm volatile("s_waitcnt lgkmcnt(" #n ")" ::: "memory")
; #define G_BAR __builtin_amdgcn_s_barrier()
; template <bool PERM, class Dec, class Epi>
; DI void gemm_phase(LAS unsigned char* lds, const int nM, const int nN, const int K, const int lda, const int ldb, const Dec& dec, const Epi& epi, const int vb, const int panel = -1) {
;     ...
;             const bool last = (t == nt - 2);
;             const char* a1 = cA + (size_t)(t + 1) * kstep;
;             const char* a2 = last ? nA : cA + (size_t)(t + 2) * kstep; const char* b2 = last ? nB : cB + (size_t)(t + 2) * kstep;
;             const char* a3 = a2 + kstep; const char* b3 = b2 + kstep;
;             G_LDB(B0, 0, 0); G_SCHED; G_LDA(At, 0, 0); G_STAGE(G_SA(1, 1), a1 + hstepA, voffA);
;             G_WAIT_L(8); G_BAR; G_WAIT_L(0); G_MMA(0, 0, At, B0); G_BAR; G_SCHED;
;             G_LDB(B1, 0, 1); G_STAGE(G_SB(0, 0), b2, voffB);
;             G_BAR; G_WAIT_L(0); G_MMA(0, 1, At, B1); G_BAR;
;             G_LDA(At, 0, 1); G_STAGE(G_SA(0, 0), a2, voffA);
;             G_BAR; G_WAIT_L(0); G_MMA(1, 0, At, B0); G_BAR; G_SCHED;
;             G_STAGE(G_SB(0, 1), b2 + hstepB, voffB);
;             G_WAIT_V(6); G_BAR; G_MMA(1, 1, At, B1); G_BAR;
.LBB0_182:
	s_add_u32 s46, s44, 0xfffc0080
	s_addc_u32 s47, s45, -1
	s_add_i32 s64, 0, 0x10000
	v_add_u32_e32 v165, s64, v163
	ds_read_b128 v[166:169], v165
	ds_read_b128 v[170:173], v165 offset:1024
	ds_read_b128 v[174:177], v165 offset:2048
	ds_read_b128 v[178:181], v165 offset:3072
	s_cmp_eq_u32 s79, 12
	s_cselect_b32 s49, s3, s47
	s_cselect_b32 s48, s23, s46
	s_cselect_b32 s47, s35, s77
	s_cselect_b32 s46, s71, s76
	v_lshl_add_u64 v[190:191], s[44:45], 0, v[158:159]
	s_add_i32 m0, s56, 0xc000
	ds_read_b128 v[182:185], v164
	ds_read_b128 v[186:189], v164 offset:1024
	ds_read_b128 v[194:197], v164 offset:2048
	ds_read_b128 v[198:201], v164 offset:3072
	ds_read_b128 v[202:205], v164 offset:4096
	ds_read_b128 v[206:209], v164 offset:5120
	ds_read_b128 v[210:213], v164 offset:6144
	ds_read_b128 v[214:217], v164 offset:7168
	global_load_lds_dwordx4 v[190:191], off
	v_lshl_add_u64 v[190:191], s[44:45], 0, v[160:161]
	s_add_i32 m0, s56, 0xe000
	s_nop 0
	global_load_lds_dwordx4 v[190:191], off
	s_waitcnt lgkmcnt(8)
	s_barrier
	s_waitcnt lgkmcnt(0)
	s_setprio 1
	s_waitcnt lgkmcnt(0)
	v_mfma_f32_16x16x32_bf16 v[124:127], v[166:169], v[182:185], v[124:127]
	v_mfma_f32_16x16x32_bf16 v[120:123], v[174:177], v[182:185], v[120:123]
	v_mfma_f32_16x16x32_bf16 v[116:119], v[166:169], v[194:197], v[116:119]
	v_mfma_f32_16x16x32_bf16 v[112:115], v[174:177], v[194:197], v[112:115]
	v_mfma_f32_16x16x32_bf16 v[100:103], v[166:169], v[202:205], v[100:103]
	v_mfma_f32_16x16x32_bf16 v[96:99], v[174:177], v[202:205], v[96:99]
	v_mfma_f32_16x16x32_bf16 v[84:87], v[166:169], v[210:213], v[84:87]
	v_mfma_f32_16x16x32_bf16 v[80:83], v[174:177], v[210:213], v[80:83]
	v_mfma_f32_16x16x32_bf16 v[124:127], v[170:173], v[186:189], v[124:127]
	v_mfma_f32_16x16x32_bf16 v[120:123], v[178:181], v[186:189], v[120:123]
	v_mfma_f32_16x16x32_bf16 v[116:119], v[170:173], v[198:201], v[116:119]
	v_mfma_f32_16x16x32_bf16 v[112:115], v[178:181], v[198:201], v[112:115]
	v_mfma_f32_16x16x32_bf16 v[100:103], v[170:173], v[206:209], v[100:103]
	v_mfma_f32_16x16x32_bf16 v[96:99], v[178:181], v[206:209], v[96:99]
	v_mfma_f32_16x16x32_bf16 v[84:87], v[170:173], v[214:217], v[84:87]
	v_mfma_f32_16x16x32_bf16 v[80:83], v[178:181], v[214:217], v[80:83]
	s_setprio 0
	s_barrier
	s_add_i32 s68, 0, 0x14000
	s_add_i32 s64, s64, s55
	v_add_u32_e32 v165, s68, v163
	v_lshl_add_u64 v[190:191], s[46:47], 0, v[138:139]
	s_mov_b32 m0, s64
	ds_read_b128 v[218:221], v165
	ds_read_b128 v[222:225], v165 offset:1024
	ds_read_b128 v[226:229], v165 offset:2048
	ds_read_b128 v[230:233], v165 offset:3072
	global_load_lds_dwordx4 v[190:191], off
	v_lshl_add_u64 v[234:235], s[46:47], 0, v[134:135]
	s_add_i32 m0, s64, 0x2000
	s_nop 0
	global_load_lds_dwordx4 v[234:235], off
	s_barrier
	s_waitcnt lgkmcnt(0)
	s_setprio 1
	s_waitcnt lgkmcnt(0)
	v_mfma_f32_16x16x32_bf16 v[108:111], v[218:221], v[182:185], v[108:111]
	v_mfma_f32_16x16x32_bf16 v[104:107], v[226:229], v[182:185], v[104:107]
	v_mfma_f32_16x16x32_bf16 v[92:95], v[218:221], v[194:197], v[92:95]
	v_mfma_f32_16x16x32_bf16 v[88:91], v[226:229], v[194:197], v[88:91]
	v_mfma_f32_16x16x32_bf16 v[76:79], v[218:221], v[202:205], v[76:79]
	v_mfma_f32_16x16x32_bf16 v[72:75], v[226:229], v[202:205], v[72:75]
	v_mfma_f32_16x16x32_bf16 v[68:71], v[218:221], v[210:213], v[68:71]
	v_mfma_f32_16x16x32_bf16 v[64:67], v[226:229], v[210:213], v[64:67]
	v_mfma_f32_16x16x32_bf16 v[108:111], v[222:225], v[186:189], v[108:111]
	v_mfma_f32_16x16x32_bf16 v[104:107], v[230:233], v[186:189], v[104:107]
	v_mfma_f32_16x16x32_bf16 v[92:95], v[222:225], v[198:201], v[92:95]
	v_mfma_f32_16x16x32_bf16 v[88:91], v[230:233], v[198:201], v[88:91]
	v_mfma_f32_16x16x32_bf16 v[76:79], v[222:225], v[206:209], v[76:79]
	v_mfma_f32_16x16x32_bf16 v[72:75], v[230:233], v[206:209], v[72:75]
	v_mfma_f32_16x16x32_bf16 v[68:71], v[222:225], v[214:217], v[68:71]
	v_mfma_f32_16x16x32_bf16 v[64:67], v[230:233], v[214:217], v[64:67]
	s_setprio 0
	s_mov_b32 m0, s56
	v_lshl_add_u64 v[236:237], s[48:49], 0, v[140:141]
	s_barrier
	ds_read_b128 v[182:185], v164 offset:16384
	ds_read_b128 v[186:189], v164 offset:17408
	ds_read_b128 v[194:197], v164 offset:18432
	ds_read_b128 v[198:201], v164 offset:19456
	ds_read_b128 v[202:205], v164 offset:20480
	ds_read_b128 v[206:209], v164 offset:21504
	ds_read_b128 v[210:213], v164 offset:22528
	ds_read_b128 v[214:217], v164 offset:23552
	global_load_lds_dwordx4 v[236:237], off
	v_lshl_add_u64 v[238:239], s[48:49], 0, v[136:137]
	s_mov_b32 m0, s57
	s_nop 0
	global_load_lds_dwordx4 v[238:239], off
	s_barrier
	s_waitcnt lgkmcnt(0)
	s_setprio 1
	s_waitcnt lgkmcnt(0)
	v_mfma_f32_16x16x32_bf16 v[60:63], v[166:169], v[182:185], v[60:63]
	v_mfma_f32_16x16x32_bf16 v[56:59], v[174:177], v[182:185], v[56:59]
	v_mfma_f32_16x16x32_bf16 v[52:55], v[166:169], v[194:197], v[52:55]
	v_mfma_f32_16x16x32_bf16 v[48:51], v[174:177], v[194:197], v[48:51]
	v_mfma_f32_16x16x32_bf16 v[36:39], v[166:169], v[202:205], v[36:39]
	v_mfma_f32_16x16x32_bf16 v[32:35], v[174:177], v[202:205], v[32:35]
	v_mfma_f32_16x16x32_bf16 v[20:23], v[166:169], v[210:213], v[20:23]
	v_mfma_f32_16x16x32_bf16 v[16:19], v[174:177], v[210:213], v[16:19]
	v_mfma_f32_16x16x32_bf16 v[60:63], v[170:173], v[186:189], v[60:63]
	v_mfma_f32_16x16x32_bf16 v[56:59], v[178:181], v[186:189], v[56:59]
	v_mfma_f32_16x16x32_bf16 v[52:55], v[170:173], v[198:201], v[52:55]
	v_mfma_f32_16x16x32_bf16 v[48:51], v[178:181], v[198:201], v[48:51]
	v_mfma_f32_16x16x32_bf16 v[36:39], v[170:173], v[206:209], v[36:39]
	v_mfma_f32_16x16x32_bf16 v[32:35], v[178:181], v[206:209], v[32:35]
	v_mfma_f32_16x16x32_bf16 v[20:23], v[170:173], v[214:217], v[20:23]
	v_mfma_f32_16x16x32_bf16 v[16:19], v[178:181], v[214:217], v[16:19]
	s_setprio 0
	s_barrier
	s_add_u32 s64, s46, 0x40000
	s_addc_u32 s65, s47, 0
	s_add_i32 s68, s68, s55
	v_lshl_add_u64 v[166:167], s[64:65], 0, v[138:139]
	s_mov_b32 m0, s68
	s_nop 0
	global_load_lds_dwordx4 v[166:167], off
	v_lshl_add_u64 v[166:167], s[64:65], 0, v[134:135]
	s_add_i32 m0, s68, 0x2000
	s_nop 0
	global_load_lds_dwordx4 v[166:167], off
	s_cmp_eq_u32 s79, -2
	s_cbranch_scc1 .Lfi4_182
	s_waitcnt vmcnt(6)
; #define G_STAGE(bufoff, gbase, voff) do { _Pragma("unroll") for (int _i = 0; _i < 2; ++_i) \
;         __builtin_amdgcn_global_load_lds((const unsigned*)((const char*)(gbase) + (voff)[_i]), (LAS unsigned*)(lds + (bufoff) + ldsw + _i * 8192), 16, 0, 0); } while (0)
; #define G_LDA(dst, b, h) do { _Pragma("unroll") for (int m = 0; m < 4; ++m) _Pragma("unroll") for (int k = 0; k < 2; ++k) dst[m][k] = *(const LAS bf16x8*)(lds + G_SA(b, h) + aoff + m * 2048 + k * 1024); } while (0)
; #define G_LDB(dst, b, h) do { _Pragma("unroll") for (int n = 0; n < 2; ++n) _Pragma("unroll") for (int k = 0; k < 2; ++k) dst[n][k] = *(const LAS bf16x8*)(lds + G_SB(b, h) + boff + n * 2048 + k * 1024); } while (0)
; #define G_MMA(ai, bj, At, Bt) do { __builtin_amdgcn_s_setprio(1); _Pragma("unroll") for (int m = 0; m < 4; ++m) _Pragma("unroll") for (int n = 0; n < 2; ++n) _Pragma("unroll") for (int k = 0; k < 2; ++k) \
;         acc[ai][bj][m][n] = __builtin_amdgcn_mfma_f32_16x16x32_bf16(Bt[n][k], At[m][k], acc[ai][bj][m][n], 0, 0, 0); __builtin_amdgcn_s_setprio(0); } while (0)
; #define G_WAIT_V(n) asm volatile("s_waitcnt vmcnt(" #n ")" ::: "memory")
; #define G_WAIT_L(n) asm volatile("s_waitcnt lgkmcnt(" #n ")" ::: "memory")
; #define G_BAR __builtin_amdgcn_s_barrier()
; #define G_SCHED __builtin_amdgcn_sched_barrier(0)
; template <bool PERM, class Dec, class Epi>
; DI void gemm_phase(LAS unsigned char* lds, const int nM, const int nN, const int K, const int lda, const int ldb, const Dec& dec, const Epi& epi, const int vb, const int panel = -1) {
;     ...
;             G_WAIT_V(6); G_BAR; G_MMA(1, 1, At, B1); G_BAR;
;             G_LDB(B0, 1, 0); G_SCHED; G_LDA(At, 1, 0); G_STAGE(G_SA(0, 1), a2 + hstepA, voffA);
;             G_WAIT_L(8); G_BAR; G_WAIT_L(0); G_MMA(0, 0, At, B0); G_BAR; G_SCHED;
;             G_LDB(B1, 1, 1); G_STAGE(G_SB(1, 0), b3, voffB);
;             G_BAR; G_WAIT_L(0); G_MMA(0, 1, At, B1); G_BAR;
;             G_LDA(At, 1, 1); G_STAGE(G_SA(1, 0), a3, voffA);
;             G_BAR; G_WAIT_L(0); G_MMA(1, 0, At, B0); G_BAR; G_SCHED;
.Lfi4_182:
	s_barrier
	s_setprio 1
	v_mfma_f32_16x16x32_bf16 v[44:47], v[218:221], v[182:185], v[44:47]
	v_mfma_f32_16x16x32_bf16 v[40:43], v[226:229], v[182:185], v[40:43]
	v_mfma_f32_16x16x32_bf16 v[28:31], v[218:221], v[194:197], v[28:31]
	v_mfma_f32_16x16x32_bf16 v[24:27], v[226:229], v[194:197], v[24:27]
	v_mfma_f32_16x16x32_bf16 v[12:15], v[218:221], v[202:205], v[12:15]
	v_mfma_f32_16x16x32_bf16 v[8:11], v[226:229], v[202:205], v[8:11]
	v_mfma_f32_16x16x32_bf16 v[4:7], v[218:221], v[210:213], v[4:7]
	v_mfma_f32_16x16x32_bf16 v[0:3], v[226:229], v[210:213], v[0:3]
	v_mfma_f32_16x16x32_bf16 v[44:47], v[222:225], v[186:189], v[44:47]
	v_mfma_f32_16x16x32_bf16 v[40:43], v[230:233], v[186:189], v[40:43]
	v_mfma_f32_16x16x32_bf16 v[28:31], v[222:225], v[198:201], v[28:31]
	v_mfma_f32_16x16x32_bf16 v[24:27], v[230:233], v[198:201], v[24:27]
	v_mfma_f32_16x16x32_bf16 v[12:15], v[222:225], v[206:209], v[12:15]
	v_mfma_f32_16x16x32_bf16 v[8:11], v[230:233], v[206:209], v[8:11]
	v_mfma_f32_16x16x32_bf16 v[4:7], v[222:225], v[214:217], v[4:7]
	v_mfma_f32_16x16x32_bf16 v[0:3], v[230:233], v[214:217], v[0:3]
	s_setprio 0
	s_add_i32 s64, 0, 0x18000
	v_add_u32_e32 v165, s64, v163
	s_barrier
	ds_read_b128 v[166:169], v165
	ds_read_b128 v[170:173], v165 offset:1024
	ds_read_b128 v[174:177], v165 offset:2048
	ds_read_b128 v[178:181], v165 offset:3072
	s_add_u32 s48, s48, 0x40000
	s_addc_u32 s49, s49, 0
	s_mov_b32 m0, s58
	v_lshl_add_u64 v[218:219], s[48:49], 0, v[140:141]
	ds_read_b128 v[182:185], v164 offset:32768
	ds_read_b128 v[186:189], v164 offset:33792
	ds_read_b128 v[194:197], v164 offset:34816
	ds_read_b128 v[198:201], v164 offset:35840
	ds_read_b128 v[202:205], v164 offset:36864
	ds_read_b128 v[206:209], v164 offset:37888
	ds_read_b128 v[210:213], v164 offset:38912
	ds_read_b128 v[214:217], v164 offset:39936
	global_load_lds_dwordx4 v[218:219], off
	v_lshl_add_u64 v[218:219], s[48:49], 0, v[136:137]
	s_mov_b32 m0, s59
	s_nop 0
	global_load_lds_dwordx4 v[218:219], off
	s_waitcnt lgkmcnt(8)
	s_barrier
	s_waitcnt lgkmcnt(0)
	s_setprio 1
	s_waitcnt lgkmcnt(0)
	v_mfma_f32_16x16x32_bf16 v[124:127], v[166:169], v[182:185], v[124:127]
	v_mfma_f32_16x16x32_bf16 v[120:123], v[174:177], v[182:185], v[120:123]
	v_mfma_f32_16x16x32_bf16 v[116:119], v[166:169], v[194:197], v[116:119]
	v_mfma_f32_16x16x32_bf16 v[112:115], v[174:177], v[194:197], v[112:115]
	v_mfma_f32_16x16x32_bf16 v[100:103], v[166:169], v[202:205], v[100:103]
	v_mfma_f32_16x16x32_bf16 v[96:99], v[174:177], v[202:205], v[96:99]
	v_mfma_f32_16x16x32_bf16 v[84:87], v[166:169], v[210:213], v[84:87]
	v_mfma_f32_16x16x32_bf16 v[80:83], v[174:177], v[210:213], v[80:83]
	v_mfma_f32_16x16x32_bf16 v[124:127], v[170:173], v[186:189], v[124:127]
	v_mfma_f32_16x16x32_bf16 v[120:123], v[178:181], v[186:189], v[120:123]
	v_mfma_f32_16x16x32_bf16 v[116:119], v[170:173], v[198:201], v[116:119]
	v_mfma_f32_16x16x32_bf16 v[112:115], v[178:181], v[198:201], v[112:115]
	v_mfma_f32_16x16x32_bf16 v[100:103], v[170:173], v[206:209], v[100:103]
	v_mfma_f32_16x16x32_bf16 v[96:99], v[178:181], v[206:209], v[96:99]
	v_mfma_f32_16x16x32_bf16 v[84:87], v[170:173], v[214:217], v[84:87]
	v_mfma_f32_16x16x32_bf16 v[80:83], v[178:181], v[214:217], v[80:83]
	s_setprio 0
	s_barrier
	s_add_i32 s48, 0, 0x1c000
	s_add_i32 s49, s64, s55
	v_add_u32_e32 v165, s48, v163
	v_lshl_add_u64 v[190:191], v[190:191], 0, s[30:31]
	s_mov_b32 m0, s49
	ds_read_b128 v[218:221], v165
	ds_read_b128 v[222:225], v165 offset:1024
	ds_read_b128 v[226:229], v165 offset:2048
	ds_read_b128 v[230:233], v165 offset:3072
	global_load_lds_dwordx4 v[190:191], off
	v_lshl_add_u64 v[190:191], v[234:235], 0, s[30:31]
	s_add_i32 m0, s49, 0x2000
	s_nop 0
	global_load_lds_dwordx4 v[190:191], off
	s_cmp_lg_u32 s79, -2
	s_cbranch_scc1 .Lfi6_182
	s_waitcnt vmcnt(10)
.Lfi6_182:
	s_barrier
	s_waitcnt lgkmcnt(0)
	s_setprio 1
	s_waitcnt lgkmcnt(0)
	v_mfma_f32_16x16x32_bf16 v[108:111], v[218:221], v[182:185], v[108:111]
	v_mfma_f32_16x16x32_bf16 v[104:107], v[226:229], v[182:185], v[104:107]
	v_mfma_f32_16x16x32_bf16 v[92:95], v[218:221], v[194:197], v[92:95]
	v_mfma_f32_16x16x32_bf16 v[88:91], v[226:229], v[194:197], v[88:91]
	v_mfma_f32_16x16x32_bf16 v[76:79], v[218:221], v[202:205], v[76:79]
	v_mfma_f32_16x16x32_bf16 v[72:75], v[226:229], v[202:205], v[72:75]
	v_mfma_f32_16x16x32_bf16 v[68:71], v[218:221], v[210:213], v[68:71]
	v_mfma_f32_16x16x32_bf16 v[64:67], v[226:229], v[210:213], v[64:67]
	v_mfma_f32_16x16x32_bf16 v[108:111], v[222:225], v[186:189], v[108:111]
	v_mfma_f32_16x16x32_bf16 v[104:107], v[230:233], v[186:189], v[104:107]
	v_mfma_f32_16x16x32_bf16 v[92:95], v[222:225], v[198:201], v[92:95]
	v_mfma_f32_16x16x32_bf16 v[88:91], v[230:233], v[198:201], v[88:91]
	v_mfma_f32_16x16x32_bf16 v[76:79], v[222:225], v[206:209], v[76:79]
	v_mfma_f32_16x16x32_bf16 v[72:75], v[230:233], v[206:209], v[72:75]
	v_mfma_f32_16x16x32_bf16 v[68:71], v[222:225], v[214:217], v[68:71]
	v_mfma_f32_16x16x32_bf16 v[64:67], v[230:233], v[214:217], v[64:67]
	s_setprio 0
	s_mov_b32 m0, s60
	v_lshl_add_u64 v[190:191], v[236:237], 0, s[30:31]
	s_barrier
	ds_read_b128 v[182:185], v164 offset:49152
	ds_read_b128 v[186:189], v164 offset:50176
	ds_read_b128 v[194:197], v164 offset:51200
	ds_read_b128 v[198:201], v164 offset:52224
	ds_read_b128 v[202:205], v164 offset:53248
	ds_read_b128 v[206:209], v164 offset:54272
	ds_read_b128 v[210:213], v164 offset:55296
	ds_read_b128 v[214:217], v164 offset:56320
	global_load_lds_dwordx4 v[190:191], off
	v_lshl_add_u64 v[190:191], v[238:239], 0, s[30:31]
	s_mov_b32 m0, s61
	s_nop 0
	global_load_lds_dwordx4 v[190:191], off
	s_barrier
; DI unsigned pk2(float a, float b) { f32x2 v = {a, b}; bf2_t r = __builtin_convertvector(v, bf2_t); return __builtin_bit_cast(unsigned, r); }
; DI float sigm(float x) { return __builtin_amdgcn_rcpf(1.f + __expf(-x)); }
; DI float silu_(float x) { return x * __builtin_amdgcn_rcpf(1.f + __expf(-x)); }
; #define G_STAGE(bufoff, gbase, voff) do { _Pragma("unroll") for (int _i = 0; _i < 2; ++_i) \
;         __builtin_amdgcn_global_load_lds((const unsigned*)((const char*)(gbase) + (voff)[_i]), (LAS unsigned*)(lds + (bufoff) + ldsw + _i * 8192), 16, 0, 0); } while (0)
; #define G_WAIT_V(n) asm volatile("s_waitcnt vmcnt(" #n ")" ::: "memory")
; #define G_WAIT_L(n) asm volatile("s_waitcnt lgkmcnt(" #n ")" ::: "memory")
; template <bool PERM, class Dec, class Epi>
; DI void gemm_phase(LAS unsigned char* lds, const int nM, const int nN, const int K, const int lda, const int ldb, const Dec& dec, const Epi& epi, const int vb, const int panel = -1) {
;     ...
;             G_BAR; G_WAIT_L(0); G_MMA(1, 0, At, B0); G_BAR; G_SCHED;
;             G_STAGE(G_SB(1, 1), b3 + hstepB, voffB);
;             G_WAIT_V(6); G_BAR; G_MMA(1, 1, At, B1); G_BAR;
;         }
;         epi(acc, cpm, cpn, wr, wc, fr, fq);
;         if (!has_next) break;
; template <int ACT>
; DI void epi_bf16(const f32x4 (&acc)[2][2][4][2], bf16_t* O, const int ldc, int wr, int wc, int fr, int fq, const float* ssrow = nullptr) {
; #pragma unroll
;     for (int ai = 0; ai < 2; ++ai)
; #pragma unroll
;         for (int m = 0; m < 4; ++m) {
;             bf16_t* rowp = O + (size_t)(ai * HALF + wr * 64 + m * 16 + fr) * ldc + wc * 32 + 8 * fq;
;             const float rsc = ssrow ? __builtin_amdgcn_rsqf(ssrow[ai * HALF + wr * 64 + m * 16 + fr] * (1.f / 1024.f) + EPS_) : 1.f;
; #pragma unroll
;             for (int bj = 0; bj < 2; ++bj) {
;                 f32x4 v0 = acc[ai][bj][m][0] * rsc, v1 = acc[ai][bj][m][1] * rsc;
;                 if (ACT == 1) {
; #pragma unroll
;                     for (int j = 0; j < 4; ++j) { v0[j] = silu_(v0[j]); v1[j] = silu_(v1[j]); } }
;                 if (ACT == 2) {
; #pragma unroll
;                     for (int j = 0; j < 4; ++j) { v0[j] = sigm(v0[j]); v1[j] = sigm(v1[j]); } }
;                 u32x4 w; w[0] = pk2(v0[0], v0[1]); w[1] = pk2(v0[2], v0[3]); w[2] = pk2(v1[0], v1[1]); w[3] = pk2(v1[2], v1[3]);
;                 *(u32x4*)(rowp + bj * HALF) = w;
;             }
	s_waitcnt lgkmcnt(0)
	s_setprio 1
	s_waitcnt lgkmcnt(0)
	v_mfma_f32_16x16x32_bf16 v[60:63], v[166:169], v[182:185], v[60:63]
	v_mfma_f32_16x16x32_bf16 v[56:59], v[174:177], v[182:185], v[56:59]
	v_mfma_f32_16x16x32_bf16 v[52:55], v[166:169], v[194:197], v[52:55]
	v_mfma_f32_16x16x32_bf16 v[48:51], v[174:177], v[194:197], v[48:51]
	v_mfma_f32_16x16x32_bf16 v[36:39], v[166:169], v[202:205], v[36:39]
	v_mfma_f32_16x16x32_bf16 v[32:35], v[174:177], v[202:205], v[32:35]
	v_mfma_f32_16x16x32_bf16 v[20:23], v[166:169], v[210:213], v[20:23]
	v_mfma_f32_16x16x32_bf16 v[16:19], v[174:177], v[210:213], v[16:19]
	v_mfma_f32_16x16x32_bf16 v[60:63], v[170:173], v[186:189], v[60:63]
	v_mfma_f32_16x16x32_bf16 v[56:59], v[178:181], v[186:189], v[56:59]
	v_mfma_f32_16x16x32_bf16 v[52:55], v[170:173], v[198:201], v[52:55]
	v_mfma_f32_16x16x32_bf16 v[48:51], v[178:181], v[198:201], v[48:51]
	v_mfma_f32_16x16x32_bf16 v[36:39], v[170:173], v[206:209], v[36:39]
	v_mfma_f32_16x16x32_bf16 v[32:35], v[178:181], v[206:209], v[32:35]
	v_mfma_f32_16x16x32_bf16 v[20:23], v[170:173], v[214:217], v[20:23]
	v_mfma_f32_16x16x32_bf16 v[16:19], v[178:181], v[214:217], v[16:19]
	s_setprio 0
	s_barrier
	s_add_u32 s46, s46, 0x40080
	s_addc_u32 s47, s47, 0
	s_add_i32 s48, s48, s55
	v_lshl_add_u64 v[166:167], s[46:47], 0, v[138:139]
	s_mov_b32 m0, s48
	s_nop 0
	global_load_lds_dwordx4 v[166:167], off
	v_lshl_add_u64 v[166:167], s[46:47], 0, v[134:135]
	s_add_i32 m0, s48, 0x2000
	s_nop 0
	global_load_lds_dwordx4 v[166:167], off
	s_waitcnt vmcnt(6)
	s_barrier
	s_setprio 1
	v_mfma_f32_16x16x32_bf16 v[44:47], v[218:221], v[182:185], v[44:47]
	v_mfma_f32_16x16x32_bf16 v[40:43], v[226:229], v[182:185], v[40:43]
	v_mfma_f32_16x16x32_bf16 v[28:31], v[218:221], v[194:197], v[28:31]
	v_mfma_f32_16x16x32_bf16 v[24:27], v[226:229], v[194:197], v[24:27]
	v_mfma_f32_16x16x32_bf16 v[12:15], v[218:221], v[202:205], v[12:15]
	v_mfma_f32_16x16x32_bf16 v[8:11], v[226:229], v[202:205], v[8:11]
	v_mfma_f32_16x16x32_bf16 v[4:7], v[218:221], v[210:213], v[4:7]
	v_mfma_f32_16x16x32_bf16 v[0:3], v[226:229], v[210:213], v[0:3]
	v_mfma_f32_16x16x32_bf16 v[44:47], v[222:225], v[186:189], v[44:47]
	v_mfma_f32_16x16x32_bf16 v[40:43], v[230:233], v[186:189], v[40:43]
	v_mfma_f32_16x16x32_bf16 v[28:31], v[222:225], v[198:201], v[28:31]
	v_mfma_f32_16x16x32_bf16 v[24:27], v[230:233], v[198:201], v[24:27]
	v_mfma_f32_16x16x32_bf16 v[12:15], v[222:225], v[206:209], v[12:15]
	v_mfma_f32_16x16x32_bf16 v[8:11], v[230:233], v[206:209], v[8:11]
	v_mfma_f32_16x16x32_bf16 v[4:7], v[222:225], v[214:217], v[4:7]
	v_mfma_f32_16x16x32_bf16 v[0:3], v[230:233], v[214:217], v[0:3]
	s_setprio 0
	s_add_i32 s79, s79, 2
	s_add_u32 s44, s44, 0x100
	s_addc_u32 s45, s45, 0
	s_add_u32 s76, s76, 0x100
	s_addc_u32 s77, s77, 0
	s_cmp_gt_u32 s79, 13
	s_barrier
	s_cbranch_scc0 .LBB0_182
	s_waitcnt vmcnt(0)
	s_ashr_i32 s23, s22, 31
	s_lshl_b64 s[22:23], s[22:23], 20
	s_add_u32 s3, s86, s22
	s_addc_u32 s35, s87, s23
	s_lshl_b32 s22, s70, 8
	s_ashr_i32 s23, s22, 31
	s_lshl_b64 s[22:23], s[22:23], 1
	s_add_u32 s3, s3, s22
	s_addc_u32 s23, s35, s23
	s_add_u32 s22, s3, s67
	s_addc_u32 s23, s23, 0
	v_lshl_add_u64 v[166:167], s[22:23], 0, v[128:129]
	v_lshl_add_u64 v[168:169], v[166:167], 0, v[142:143]
	v_cvt_pk_bf16_f32 v108, v108, v109
	v_cvt_pk_bf16_f32 v109, v110, v111
	v_cvt_pk_bf16_f32 v110, v104, v105
	v_cvt_pk_bf16_f32 v111, v106, v107
	v_cvt_pk_bf16_f32 v68, v68, v69
	v_cvt_pk_bf16_f32 v69, v70, v71
	v_cvt_pk_bf16_f32 v70, v64, v65
	v_lshl_add_u64 v[64:65], v[166:167], 0, v[150:151]
	v_cvt_pk_bf16_f32 v44, v44, v45
	v_cvt_pk_bf16_f32 v45, v46, v47
	v_cvt_pk_bf16_f32 v46, v40, v41
	v_cvt_pk_bf16_f32 v47, v42, v43
	global_store_dwordx4 v[168:169], v[108:111], off offset:256
	v_cvt_pk_bf16_f32 v92, v92, v93
	v_cvt_pk_bf16_f32 v93, v94, v95
	v_lshl_add_u64 v[108:109], v[166:167], 0, v[144:145]
	v_cvt_pk_bf16_f32 v94, v88, v89
	v_cvt_pk_bf16_f32 v95, v90, v91
	global_store_dwordx4 v[64:65], v[44:47], off offset:256
	v_cvt_pk_bf16_f32 v28, v28, v29
	v_cvt_pk_bf16_f32 v29, v30, v31
	v_lshl_add_u64 v[44:45], v[166:167], 0, v[152:153]
	v_cvt_pk_bf16_f32 v30, v24, v25
	v_cvt_pk_bf16_f32 v31, v26, v27
	global_store_dwordx4 v[108:109], v[92:95], off offset:256
	v_cvt_pk_bf16_f32 v76, v76, v77
	v_cvt_pk_bf16_f32 v77, v78, v79
	v_lshl_add_u64 v[92:93], v[166:167], 0, v[146:147]
	v_cvt_pk_bf16_f32 v78, v72, v73
	v_cvt_pk_bf16_f32 v79, v74, v75
	global_store_dwordx4 v[44:45], v[28:31], off offset:256
	v_cvt_pk_bf16_f32 v12, v12, v13
	v_cvt_pk_bf16_f32 v13, v14, v15
	v_lshl_add_u64 v[28:29], v[166:167], 0, v[154:155]
	v_cvt_pk_bf16_f32 v14, v8, v9
	v_cvt_pk_bf16_f32 v15, v10, v11
	v_cvt_pk_bf16_f32 v124, v124, v125
	v_cvt_pk_bf16_f32 v125, v126, v127
	v_cvt_pk_bf16_f32 v126, v120, v121
	v_cvt_pk_bf16_f32 v127, v122, v123
	v_cvt_pk_bf16_f32 v104, v116, v117
	v_cvt_pk_bf16_f32 v105, v118, v119
	v_cvt_pk_bf16_f32 v106, v112, v113
	v_cvt_pk_bf16_f32 v107, v114, v115
	v_cvt_pk_bf16_f32 v88, v100, v101
	v_cvt_pk_bf16_f32 v89, v102, v103
	v_cvt_pk_bf16_f32 v90, v96, v97
	v_cvt_pk_bf16_f32 v91, v98, v99
	global_store_dwordx4 v[92:93], v[76:79], off offset:256
	v_cvt_pk_bf16_f32 v72, v84, v85
	v_cvt_pk_bf16_f32 v73, v86, v87
	v_lshl_add_u64 v[76:77], v[166:167], 0, v[148:149]
	v_cvt_pk_bf16_f32 v74, v80, v81
	v_cvt_pk_bf16_f32 v75, v82, v83
	v_cvt_pk_bf16_f32 v71, v66, v67
	v_cvt_pk_bf16_f32 v60, v60, v61
	v_cvt_pk_bf16_f32 v61, v62, v63
	v_cvt_pk_bf16_f32 v62, v56, v57
	v_cvt_pk_bf16_f32 v63, v58, v59
	v_cvt_pk_bf16_f32 v40, v52, v53
	v_cvt_pk_bf16_f32 v41, v54, v55
	v_cvt_pk_bf16_f32 v42, v48, v49
	v_cvt_pk_bf16_f32 v43, v50, v51
	v_cvt_pk_bf16_f32 v24, v36, v37
	v_cvt_pk_bf16_f32 v25, v38, v39
	v_cvt_pk_bf16_f32 v26, v32, v33
	v_cvt_pk_bf16_f32 v27, v34, v35
	global_store_dwordx4 v[28:29], v[12:15], off offset:256
	v_cvt_pk_bf16_f32 v8, v20, v21
	v_cvt_pk_bf16_f32 v9, v22, v23
	v_lshl_add_u64 v[12:13], v[166:167], 0, v[156:157]
	v_cvt_pk_bf16_f32 v10, v16, v17
	v_cvt_pk_bf16_f32 v11, v18, v19
	v_cvt_pk_bf16_f32 v4, v4, v5
	v_cvt_pk_bf16_f32 v5, v6, v7
	v_cvt_pk_bf16_f32 v6, v0, v1
	v_cvt_pk_bf16_f32 v7, v2, v3
	s_and_b64 vcc, exec, s[40:41]
	s_mov_b32 s22, s34
	s_mov_b32 s70, s2
	s_mov_b64 s[44:45], s[36:37]
	s_mov_b64 s[46:47], s[42:43]
	global_store_dwordx4 v[168:169], v[124:127], off
	global_store_dwordx4 v[108:109], v[104:107], off
	global_store_dwordx4 v[92:93], v[88:91], off
	global_store_dwordx4 v[76:77], v[72:75], off
	global_store_dwordx4 v[76:77], v[68:71], off offset:256
	global_store_dwordx4 v[64:65], v[60:63], off
	global_store_dwordx4 v[44:45], v[40:43], off
	global_store_dwordx4 v[28:29], v[24:27], off
	global_store_dwordx4 v[12:13], v[8:11], off
	global_store_dwordx4 v[12:13], v[4:7], off offset:256
	s_cbranch_vccz .LBB0_179
	s_waitcnt vmcnt(0)
	s_cmpk_gt_u32 s54, 0xff
	s_cbranch_scc1 .LBB0_186
	s_barrier

; #define G_STAGE(bufoff, gbase, voff) do { _Pragma("unroll") for (int _i = 0; _i < 2; ++_i) \
;         __builtin_amdgcn_global_load_lds((const unsigned*)((const char*)(gbase) + (voff)[_i]), (LAS unsigned*)(lds + (bufoff) + ldsw + _i * 8192), 16, 0, 0); } while (0)
; #define G_WAIT_V(n) asm volatile("s_waitcnt vmcnt(" #n ")" ::: "memory")
; #define G_BAR __builtin_amdgcn_s_barrier()
; template <bool PERM, class Dec, class Epi>
; DI void gemm_phase(LAS unsigned char* lds, const int nM, const int nN, const int K, const int lda, const int ldb, const Dec& dec, const Epi& epi, const int vb, const int panel = -1) {
;     ...
;     for (int i = 0; i < 2; ++i) { int R, C; stage_rc(tid * 16 + i * 8192, R, C); const int Rb = PERM ? ((R & ~31) + perm32(R & 31)) : R;
;         voffA[i] = (unsigned)(R * lda + C) * 2u; voffB[i] = (unsigned)(Rb * ldb + C) * 2u; }
;     const size_t kstep = (size_t)(BK * 2);
;     const size_t hstepA = (size_t)HALF * lda * 2, hstepB = (size_t)HALF * ldb * 2;
;     const unsigned ldsw = (unsigned)wid * 1024u;
;     const int aoff = lds_byte(wr * 64 + fr, fq * 8), boff = lds_byte(wc * 32 + fr, fq * 8);
;     ...
;     G_STAGE(G_SB(0, 0), cB, voffB); G_STAGE(G_SA(0, 0), cA, voffA); G_STAGE(G_SB(0, 1), cB + hstepB, voffB); G_STAGE(G_SA(0, 1), cA + hstepA, voffA);
;     if (wr == 1) G_BAR;
;     G_WAIT_V(4); G_BAR;
;     G_STAGE(G_SB(1, 0), cB + kstep, voffB); G_STAGE(G_SA(1, 0), cA + kstep, voffA); G_STAGE(G_SB(1, 1), cB + hstepB + kstep, voffB);
;     G_WAIT_V(6); G_BAR;
.LBB0_311:
	s_lshl_b32 s0, s38, 5
	s_and_b32 s3, s0, 0x60
	s_add_i32 m0, s55, 0x18000
	v_lshl_add_u64 v[6:7], v[6:7], 0, s[56:57]
	s_lshl_b32 s2, s30, 13
	s_lshl_b32 s38, s3, 7
	s_waitcnt vmcnt(4)
	s_barrier
	global_load_lds_dwordx4 v[6:7], off
	v_lshl_add_u64 v[4:5], v[4:5], 0, s[56:57]
	s_add_i32 m0, s55, 0x1a000
	s_add_i32 s82, s55, 0x8000
	s_add_i32 s83, s55, 0xa000
	global_load_lds_dwordx4 v[4:5], off
	v_lshl_add_u64 v[2:3], v[2:3], 0, s[56:57]
	s_mov_b32 m0, s82
	s_add_u32 s0, s58, 0x20080
	global_load_lds_dwordx4 v[2:3], off
	v_lshl_add_u64 v[0:1], v[0:1], 0, s[56:57]
	s_mov_b32 m0, s83
	s_addc_u32 s1, s59, 0
	global_load_lds_dwordx4 v[0:1], off
	s_add_i32 m0, s55, 0x1c000
	v_lshl_add_u64 v[0:1], s[0:1], 0, v[136:137]
	global_load_lds_dwordx4 v[0:1], off
	v_lshl_add_u64 v[0:1], s[0:1], 0, v[140:141]
	s_add_i32 m0, s55, 0x1e000
	v_readlane_b32 s0, v245, 25
	global_load_lds_dwordx4 v[0:1], off
	v_lshrrev_b32_e32 v0, 1, v9
	v_and_b32_e32 v0, 24, v0
	v_and_b32_e32 v1, 15, v9
	v_lshlrev_b32_e32 v2, 1, v0
	v_lshl_or_b32 v142, s30, 6, v1
	v_lshl_or_b32 v1, v1, 6, v2
	v_lshlrev_b32_e32 v2, 2, v9
	v_and_b32_e32 v2, 32, v2
	v_bitop3_b32 v3, v1, s2, v2 bitop3:0xde
	v_bitop3_b32 v164, v1, s38, v2 bitop3:0xde
	v_lshlrev_b32_e32 v1, 15, v8
	v_and_b32_e32 v1, 0xffff0000, v1
	v_lshl_add_u32 v1, v10, 12, v1
	v_and_b32_e32 v2, 1, v8
	v_lshl_or_b32 v1, v2, 6, v1
	v_lshl_add_u32 v158, v11, 1, v1
	v_lshlrev_b32_e32 v1, 15, v12
	v_and_b32_e32 v1, 0xffff0000, v1
	s_waitcnt vmcnt(0)
	v_lshl_add_u32 v1, v13, 12, v1
	v_and_b32_e32 v2, 1, v12
	v_or_b32_e32 v144, 16, v142
	v_or_b32_e32 v146, 32, v142
	v_or_b32_e32 v148, 48, v142
	v_add_u32_e32 v150, 0x80, v142
	v_add_u32_e32 v152, 0x90, v142
	v_add_u32_e32 v154, 0xa0, v142
	v_add_u32_e32 v156, 0xb0, v142
	v_lshl_or_b32 v1, v2, 6, v1
	v_ashrrev_i32_e32 v143, 31, v142
	v_ashrrev_i32_e32 v145, 31, v144
	v_ashrrev_i32_e32 v147, 31, v146
	v_ashrrev_i32_e32 v149, 31, v148
	v_ashrrev_i32_e32 v151, 31, v150
	v_ashrrev_i32_e32 v153, 31, v152
	v_ashrrev_i32_e32 v155, 31, v154
	v_ashrrev_i32_e32 v157, 31, v156
	v_mov_b32_e32 v159, v129
	v_lshl_add_u32 v160, v14, 1, v1
	v_mov_b32_e32 v161, v129
	s_mov_b32 s86, 0
	v_add_u32_e32 v165, 0, v3
	s_lshl_b32 s87, s3, 1
	v_lshlrev_b32_e32 v128, 1, v0
	s_mov_b32 s70, s34
	s_mov_b32 s90, s0
	s_barrier
	v_readlane_b32 s1, v245, 26
	s_branch .LBB0_313

; #define G_STAGE(bufoff, gbase, voff) do { _Pragma("unroll") for (int _i = 0; _i < 2; ++_i) \
;         __builtin_amdgcn_global_load_lds((const unsigned*)((const char*)(gbase) + (voff)[_i]), (LAS unsigned*)(lds + (bufoff) + ldsw + _i * 8192), 16, 0, 0); } while (0)
; #define G_LDA(dst, b, h) do { _Pragma("unroll") for (int m = 0; m < 4; ++m) _Pragma("unroll") for (int k = 0; k < 2; ++k) dst[m][k] = *(const LAS bf16x8*)(lds + G_SA(b, h) + aoff + m * 2048 + k * 1024); } while (0)
; #define G_LDB(dst, b, h) do { _Pragma("unroll") for (int n = 0; n < 2; ++n) _Pragma("unroll") for (int k = 0; k < 2; ++k) dst[n][k] = *(const LAS bf16x8*)(lds + G_SB(b, h) + boff + n * 2048 + k * 1024); } while (0)
; #define G_MMA(ai, bj, At, Bt) do { __builtin_amdgcn_s_setprio(1); _Pragma("unroll") for (int m = 0; m < 4; ++m) _Pragma("unroll") for (int n = 0; n < 2; ++n) _Pragma("unroll") for (int k = 0; k < 2; ++k) \
;         acc[ai][bj][m][n] = __builtin_amdgcn_mfma_f32_16x16x32_bf16(Bt[n][k], At[m][k], acc[ai][bj][m][n], 0, 0, 0); __builtin_amdgcn_s_setprio(0); } while (0)
; #define G_WAIT_V(n) asm volatile("s_waitcnt vmcnt(" #n ")" ::: "memory")
; #define G_WAIT_L(n) asm volatile("s_waitcnt lgkmcnt(" #n ")" ::: "memory")
; #define G_BAR __builtin_amdgcn_s_barrier()
; template <bool PERM, class Dec, class Epi>
; DI void gemm_phase(LAS unsigned char* lds, const int nM, const int nN, const int K, const int lda, const int ldb, const Dec& dec, const Epi& epi, const int vb, const int panel = -1) {
;     ...
;             const bool last = (t == nt - 2);
;             const char* a1 = cA + (size_t)(t + 1) * kstep;
;             const char* a2 = last ? nA : cA + (size_t)(t + 2) * kstep; const char* b2 = last ? nB : cB + (size_t)(t + 2) * kstep;
;             const char* a3 = a2 + kstep; const char* b3 = b2 + kstep;
;             G_LDB(B0, 0, 0); G_SCHED; G_LDA(At, 0, 0); G_STAGE(G_SA(1, 1), a1 + hstepA, voffA);
;             G_WAIT_L(8); G_BAR; G_WAIT_L(0); G_MMA(0, 0, At, B0); G_BAR; G_SCHED;
;             G_LDB(B1, 0, 1); G_STAGE(G_SB(0, 0), b2, voffB);
;             G_BAR; G_WAIT_L(0); G_MMA(0, 1, At, B1); G_BAR;
;             G_LDA(At, 0, 1); G_STAGE(G_SA(0, 0), a2, voffA);
;             G_BAR; G_WAIT_L(0); G_MMA(1, 0, At, B0); G_BAR; G_SCHED;
;             G_STAGE(G_SB(0, 1), b2 + hstepB, voffB);
;             G_WAIT_V(6); G_BAR; G_MMA(1, 1, At, B1); G_BAR;
.LBB0_322:
	s_add_u32 s58, s22, 0xfff80080
	s_addc_u32 s59, s23, -1
	s_add_i32 s64, 0, 0x10000
	v_add_u32_e32 v178, s64, v164
	ds_read_b128 v[166:169], v178
	ds_read_b128 v[170:173], v178 offset:1024
	ds_read_b128 v[174:177], v178 offset:2048
	ds_read_b128 v[178:181], v178 offset:3072
	s_cmp_eq_u32 s61, 4
	s_cselect_b32 s73, s1, s59
	s_cselect_b32 s72, s0, s58
	s_cselect_b32 s59, s67, s30
	s_cselect_b32 s58, s66, s3
	v_lshl_add_u64 v[190:191], s[22:23], 0, v[158:159]
	s_add_i32 m0, s55, 0xc000
	ds_read_b128 v[182:185], v165
	ds_read_b128 v[186:189], v165 offset:1024
	ds_read_b128 v[194:197], v165 offset:2048
	ds_read_b128 v[198:201], v165 offset:3072
	ds_read_b128 v[202:205], v165 offset:4096
	ds_read_b128 v[206:209], v165 offset:5120
	ds_read_b128 v[210:213], v165 offset:6144
	ds_read_b128 v[214:217], v165 offset:7168
	global_load_lds_dwordx4 v[190:191], off
	v_lshl_add_u64 v[190:191], s[22:23], 0, v[160:161]
	s_add_i32 m0, s55, 0xe000
	s_nop 0
	global_load_lds_dwordx4 v[190:191], off
	s_waitcnt lgkmcnt(8)
	s_barrier
	s_waitcnt lgkmcnt(0)
	s_setprio 1
	s_waitcnt lgkmcnt(0)
	v_mfma_f32_16x16x32_bf16 v[124:127], v[166:169], v[182:185], v[124:127]
	v_mfma_f32_16x16x32_bf16 v[120:123], v[174:177], v[182:185], v[120:123]
	v_mfma_f32_16x16x32_bf16 v[116:119], v[166:169], v[194:197], v[116:119]
	v_mfma_f32_16x16x32_bf16 v[112:115], v[174:177], v[194:197], v[112:115]
	v_mfma_f32_16x16x32_bf16 v[100:103], v[166:169], v[202:205], v[100:103]
	v_mfma_f32_16x16x32_bf16 v[96:99], v[174:177], v[202:205], v[96:99]
	v_mfma_f32_16x16x32_bf16 v[84:87], v[166:169], v[210:213], v[84:87]
	v_mfma_f32_16x16x32_bf16 v[80:83], v[174:177], v[210:213], v[80:83]
	v_mfma_f32_16x16x32_bf16 v[124:127], v[170:173], v[186:189], v[124:127]
	v_mfma_f32_16x16x32_bf16 v[120:123], v[178:181], v[186:189], v[120:123]
	v_mfma_f32_16x16x32_bf16 v[116:119], v[170:173], v[198:201], v[116:119]
	v_mfma_f32_16x16x32_bf16 v[112:115], v[178:181], v[198:201], v[112:115]
	v_mfma_f32_16x16x32_bf16 v[100:103], v[170:173], v[206:209], v[100:103]
	v_mfma_f32_16x16x32_bf16 v[96:99], v[178:181], v[206:209], v[96:99]
	v_mfma_f32_16x16x32_bf16 v[84:87], v[170:173], v[214:217], v[84:87]
	v_mfma_f32_16x16x32_bf16 v[80:83], v[178:181], v[214:217], v[80:83]
	s_setprio 0
	s_barrier
	s_add_i32 s68, 0, 0x14000
	v_add_u32_e32 v190, s68, v164
	s_add_i32 s64, s64, s54
	ds_read_b128 v[218:221], v190
	ds_read_b128 v[222:225], v190 offset:1024
	ds_read_b128 v[226:229], v190 offset:2048
	ds_read_b128 v[230:233], v190 offset:3072
	v_lshl_add_u64 v[190:191], s[58:59], 0, v[136:137]
	s_mov_b32 m0, s64
	v_lshl_add_u64 v[234:235], s[58:59], 0, v[140:141]
	global_load_lds_dwordx4 v[190:191], off
	s_add_i32 m0, s64, 0x2000
	s_nop 0
	global_load_lds_dwordx4 v[234:235], off
	s_barrier
	s_waitcnt lgkmcnt(0)
	s_setprio 1
	s_waitcnt lgkmcnt(0)
	v_mfma_f32_16x16x32_bf16 v[108:111], v[218:221], v[182:185], v[108:111]
	v_mfma_f32_16x16x32_bf16 v[104:107], v[226:229], v[182:185], v[104:107]
	v_mfma_f32_16x16x32_bf16 v[92:95], v[218:221], v[194:197], v[92:95]
	v_mfma_f32_16x16x32_bf16 v[88:91], v[226:229], v[194:197], v[88:91]
	v_mfma_f32_16x16x32_bf16 v[76:79], v[218:221], v[202:205], v[76:79]
	v_mfma_f32_16x16x32_bf16 v[72:75], v[226:229], v[202:205], v[72:75]
	v_mfma_f32_16x16x32_bf16 v[68:71], v[218:221], v[210:213], v[68:71]
	v_mfma_f32_16x16x32_bf16 v[64:67], v[226:229], v[210:213], v[64:67]
	v_mfma_f32_16x16x32_bf16 v[108:111], v[222:225], v[186:189], v[108:111]
	v_mfma_f32_16x16x32_bf16 v[104:107], v[230:233], v[186:189], v[104:107]
	v_mfma_f32_16x16x32_bf16 v[92:95], v[222:225], v[198:201], v[92:95]
	v_mfma_f32_16x16x32_bf16 v[88:91], v[230:233], v[198:201], v[88:91]
	v_mfma_f32_16x16x32_bf16 v[76:79], v[222:225], v[206:209], v[76:79]
	v_mfma_f32_16x16x32_bf16 v[72:75], v[230:233], v[206:209], v[72:75]
	v_mfma_f32_16x16x32_bf16 v[68:71], v[222:225], v[214:217], v[68:71]
	v_mfma_f32_16x16x32_bf16 v[64:67], v[230:233], v[214:217], v[64:67]
	s_setprio 0
	s_mov_b32 m0, s55
	v_lshl_add_u64 v[236:237], s[72:73], 0, v[134:135]
	s_barrier
	ds_read_b128 v[182:185], v165 offset:16384
	ds_read_b128 v[186:189], v165 offset:17408
	ds_read_b128 v[194:197], v165 offset:18432
	ds_read_b128 v[198:201], v165 offset:19456
	ds_read_b128 v[202:205], v165 offset:20480
	ds_read_b128 v[206:209], v165 offset:21504
	ds_read_b128 v[210:213], v165 offset:22528
	ds_read_b128 v[214:217], v165 offset:23552
	global_load_lds_dwordx4 v[236:237], off
	v_lshl_add_u64 v[238:239], s[72:73], 0, v[138:139]
	s_mov_b32 m0, s76
	s_nop 0
	global_load_lds_dwordx4 v[238:239], off
	s_barrier
	s_waitcnt lgkmcnt(0)
	s_setprio 1
	s_waitcnt lgkmcnt(0)
	v_mfma_f32_16x16x32_bf16 v[60:63], v[166:169], v[182:185], v[60:63]
	v_mfma_f32_16x16x32_bf16 v[56:59], v[174:177], v[182:185], v[56:59]
	v_mfma_f32_16x16x32_bf16 v[52:55], v[166:169], v[194:197], v[52:55]
	v_mfma_f32_16x16x32_bf16 v[48:51], v[174:177], v[194:197], v[48:51]
	v_mfma_f32_16x16x32_bf16 v[36:39], v[166:169], v[202:205], v[36:39]
	v_mfma_f32_16x16x32_bf16 v[32:35], v[174:177], v[202:205], v[32:35]
	v_mfma_f32_16x16x32_bf16 v[20:23], v[166:169], v[210:213], v[20:23]
	v_mfma_f32_16x16x32_bf16 v[16:19], v[174:177], v[210:213], v[16:19]
	v_mfma_f32_16x16x32_bf16 v[60:63], v[170:173], v[186:189], v[60:63]
	v_mfma_f32_16x16x32_bf16 v[56:59], v[178:181], v[186:189], v[56:59]
	v_mfma_f32_16x16x32_bf16 v[52:55], v[170:173], v[198:201], v[52:55]
	v_mfma_f32_16x16x32_bf16 v[48:51], v[178:181], v[198:201], v[48:51]
	v_mfma_f32_16x16x32_bf16 v[36:39], v[170:173], v[206:209], v[36:39]
	v_mfma_f32_16x16x32_bf16 v[32:35], v[178:181], v[206:209], v[32:35]
	v_mfma_f32_16x16x32_bf16 v[20:23], v[170:173], v[214:217], v[20:23]
	v_mfma_f32_16x16x32_bf16 v[16:19], v[178:181], v[214:217], v[16:19]
	s_setprio 0
	s_barrier
	s_add_u32 s64, s58, 0x20000
	s_addc_u32 s65, s59, 0
	s_add_i32 s68, s68, s54
	v_lshl_add_u64 v[166:167], s[64:65], 0, v[136:137]
	s_mov_b32 m0, s68
	s_nop 0
	global_load_lds_dwordx4 v[166:167], off
	v_lshl_add_u64 v[166:167], s[64:65], 0, v[140:141]
	s_add_i32 m0, s68, 0x2000
	s_nop 0
	global_load_lds_dwordx4 v[166:167], off
	s_cmp_eq_u32 s61, -2
	s_cbranch_scc1 .Lfi4_322
	s_waitcnt vmcnt(6)
; #define G_STAGE(bufoff, gbase, voff) do { _Pragma("unroll") for (int _i = 0; _i < 2; ++_i) \
;         __builtin_amdgcn_global_load_lds((const unsigned*)((const char*)(gbase) + (voff)[_i]), (LAS unsigned*)(lds + (bufoff) + ldsw + _i * 8192), 16, 0, 0); } while (0)
; #define G_LDA(dst, b, h) do { _Pragma("unroll") for (int m = 0; m < 4; ++m) _Pragma("unroll") for (int k = 0; k < 2; ++k) dst[m][k] = *(const LAS bf16x8*)(lds + G_SA(b, h) + aoff + m * 2048 + k * 1024); } while (0)
; #define G_LDB(dst, b, h) do { _Pragma("unroll") for (int n = 0; n < 2; ++n) _Pragma("unroll") for (int k = 0; k < 2; ++k) dst[n][k] = *(const LAS bf16x8*)(lds + G_SB(b, h) + boff + n * 2048 + k * 1024); } while (0)
; #define G_MMA(ai, bj, At, Bt) do { __builtin_amdgcn_s_setprio(1); _Pragma("unroll") for (int m = 0; m < 4; ++m) _Pragma("unroll") for (int n = 0; n < 2; ++n) _Pragma("unroll") for (int k = 0; k < 2; ++k) \
;         acc[ai][bj][m][n] = __builtin_amdgcn_mfma_f32_16x16x32_bf16(Bt[n][k], At[m][k], acc[ai][bj][m][n], 0, 0, 0); __builtin_amdgcn_s_setprio(0); } while (0)
; #define G_WAIT_V(n) asm volatile("s_waitcnt vmcnt(" #n ")" ::: "memory")
; #define G_WAIT_L(n) asm volatile("s_waitcnt lgkmcnt(" #n ")" ::: "memory")
; #define G_BAR __builtin_amdgcn_s_barrier()
; #define G_SCHED __builtin_amdgcn_sched_barrier(0)
; template <bool PERM, class Dec, class Epi>
; DI void gemm_phase(LAS unsigned char* lds, const int nM, const int nN, const int K, const int lda, const int ldb, const Dec& dec, const Epi& epi, const int vb, const int panel = -1) {
;     ...
;             G_WAIT_V(6); G_BAR; G_MMA(1, 1, At, B1); G_BAR;
;             G_LDB(B0, 1, 0); G_SCHED; G_LDA(At, 1, 0); G_STAGE(G_SA(0, 1), a2 + hstepA, voffA);
;             G_WAIT_L(8); G_BAR; G_WAIT_L(0); G_MMA(0, 0, At, B0); G_BAR; G_SCHED;
;             G_LDB(B1, 1, 1); G_STAGE(G_SB(1, 0), b3, voffB);
;             G_BAR; G_WAIT_L(0); G_MMA(0, 1, At, B1); G_BAR;
;             G_LDA(At, 1, 1); G_STAGE(G_SA(1, 0), a3, voffA);
;             G_BAR; G_WAIT_L(0); G_MMA(1, 0, At, B0); G_BAR; G_SCHED;
.Lfi4_322:
	s_barrier
	s_setprio 1
	v_mfma_f32_16x16x32_bf16 v[44:47], v[218:221], v[182:185], v[44:47]
	v_mfma_f32_16x16x32_bf16 v[40:43], v[226:229], v[182:185], v[40:43]
	v_mfma_f32_16x16x32_bf16 v[28:31], v[218:221], v[194:197], v[28:31]
	v_mfma_f32_16x16x32_bf16 v[24:27], v[226:229], v[194:197], v[24:27]
	v_mfma_f32_16x16x32_bf16 v[12:15], v[218:221], v[202:205], v[12:15]
	v_mfma_f32_16x16x32_bf16 v[8:11], v[226:229], v[202:205], v[8:11]
	v_mfma_f32_16x16x32_bf16 v[4:7], v[218:221], v[210:213], v[4:7]
	v_mfma_f32_16x16x32_bf16 v[0:3], v[226:229], v[210:213], v[0:3]
	v_mfma_f32_16x16x32_bf16 v[44:47], v[222:225], v[186:189], v[44:47]
	v_mfma_f32_16x16x32_bf16 v[40:43], v[230:233], v[186:189], v[40:43]
	v_mfma_f32_16x16x32_bf16 v[28:31], v[222:225], v[198:201], v[28:31]
	v_mfma_f32_16x16x32_bf16 v[24:27], v[230:233], v[198:201], v[24:27]
	v_mfma_f32_16x16x32_bf16 v[12:15], v[222:225], v[206:209], v[12:15]
	v_mfma_f32_16x16x32_bf16 v[8:11], v[230:233], v[206:209], v[8:11]
	v_mfma_f32_16x16x32_bf16 v[4:7], v[222:225], v[214:217], v[4:7]
	v_mfma_f32_16x16x32_bf16 v[0:3], v[230:233], v[214:217], v[0:3]
	s_setprio 0
	s_add_i32 s68, 0, 0x18000
	v_add_u32_e32 v178, s68, v164
	s_barrier
	ds_read_b128 v[166:169], v178
	ds_read_b128 v[170:173], v178 offset:1024
	ds_read_b128 v[174:177], v178 offset:2048
	ds_read_b128 v[178:181], v178 offset:3072
	s_add_u32 s64, s72, 0x80000
	s_addc_u32 s65, s73, 0
	s_mov_b32 m0, s77
	v_lshl_add_u64 v[218:219], s[64:65], 0, v[134:135]
	ds_read_b128 v[182:185], v165 offset:32768
	ds_read_b128 v[186:189], v165 offset:33792
	ds_read_b128 v[194:197], v165 offset:34816
	ds_read_b128 v[198:201], v165 offset:35840
	ds_read_b128 v[202:205], v165 offset:36864
	ds_read_b128 v[206:209], v165 offset:37888
	ds_read_b128 v[210:213], v165 offset:38912
	ds_read_b128 v[214:217], v165 offset:39936
	global_load_lds_dwordx4 v[218:219], off
	v_lshl_add_u64 v[218:219], s[64:65], 0, v[138:139]
	s_mov_b32 m0, s79
	s_nop 0
	global_load_lds_dwordx4 v[218:219], off
	s_waitcnt lgkmcnt(8)
	s_barrier
	s_waitcnt lgkmcnt(0)
	s_setprio 1
	s_waitcnt lgkmcnt(0)
	v_mfma_f32_16x16x32_bf16 v[124:127], v[166:169], v[182:185], v[124:127]
	v_mfma_f32_16x16x32_bf16 v[120:123], v[174:177], v[182:185], v[120:123]
	v_mfma_f32_16x16x32_bf16 v[116:119], v[166:169], v[194:197], v[116:119]
	v_mfma_f32_16x16x32_bf16 v[112:115], v[174:177], v[194:197], v[112:115]
	v_mfma_f32_16x16x32_bf16 v[100:103], v[166:169], v[202:205], v[100:103]
	v_mfma_f32_16x16x32_bf16 v[96:99], v[174:177], v[202:205], v[96:99]
	v_mfma_f32_16x16x32_bf16 v[84:87], v[166:169], v[210:213], v[84:87]
	v_mfma_f32_16x16x32_bf16 v[80:83], v[174:177], v[210:213], v[80:83]
	v_mfma_f32_16x16x32_bf16 v[124:127], v[170:173], v[186:189], v[124:127]
	v_mfma_f32_16x16x32_bf16 v[120:123], v[178:181], v[186:189], v[120:123]
	v_mfma_f32_16x16x32_bf16 v[116:119], v[170:173], v[198:201], v[116:119]
	v_mfma_f32_16x16x32_bf16 v[112:115], v[178:181], v[198:201], v[112:115]
	v_mfma_f32_16x16x32_bf16 v[100:103], v[170:173], v[206:209], v[100:103]
	v_mfma_f32_16x16x32_bf16 v[96:99], v[178:181], v[206:209], v[96:99]
	v_mfma_f32_16x16x32_bf16 v[84:87], v[170:173], v[214:217], v[84:87]
	v_mfma_f32_16x16x32_bf16 v[80:83], v[178:181], v[214:217], v[80:83]
	s_setprio 0
	s_barrier
	s_add_i32 s64, 0, 0x1c000
	s_add_i32 s65, s68, s54
	v_add_u32_e32 v193, s64, v164
	v_lshl_add_u64 v[190:191], v[190:191], 0, s[56:57]
	s_mov_b32 m0, s65
	ds_read_b128 v[218:221], v193
	ds_read_b128 v[222:225], v193 offset:1024
	ds_read_b128 v[226:229], v193 offset:2048
	ds_read_b128 v[230:233], v193 offset:3072
	global_load_lds_dwordx4 v[190:191], off
	v_lshl_add_u64 v[190:191], v[234:235], 0, s[56:57]
	s_add_i32 m0, s65, 0x2000
	s_nop 0
	global_load_lds_dwordx4 v[190:191], off
	s_cmp_lg_u32 s61, -2
	s_cbranch_scc1 .Lfi6_322
	s_waitcnt vmcnt(10)
; #define G_STAGE(bufoff, gbase, voff) do { _Pragma("unroll") for (int _i = 0; _i < 2; ++_i) \
;         __builtin_amdgcn_global_load_lds((const unsigned*)((const char*)(gbase) + (voff)[_i]), (LAS unsigned*)(lds + (bufoff) + ldsw + _i * 8192), 16, 0, 0); } while (0)
; #define G_MMA(ai, bj, At, Bt) do { __builtin_amdgcn_s_setprio(1); _Pragma("unroll") for (int m = 0; m < 4; ++m) _Pragma("unroll") for (int n = 0; n < 2; ++n) _Pragma("unroll") for (int k = 0; k < 2; ++k) \
;         acc[ai][bj][m][n] = __builtin_amdgcn_mfma_f32_16x16x32_bf16(Bt[n][k], At[m][k], acc[ai][bj][m][n], 0, 0, 0); __builtin_amdgcn_s_setprio(0); } while (0)
; #define G_WAIT_V(n) asm volatile("s_waitcnt vmcnt(" #n ")" ::: "memory")
; #define G_WAIT_L(n) asm volatile("s_waitcnt lgkmcnt(" #n ")" ::: "memory")
; #define G_BAR __builtin_amdgcn_s_barrier()
; #define G_SCHED __builtin_amdgcn_sched_barrier(0)
; template <bool PERM, class Dec, class Epi>
; DI void gemm_phase(LAS unsigned char* lds, const int nM, const int nN, const int K, const int lda, const int ldb, const Dec& dec, const Epi& epi, const int vb, const int panel = -1) {
;     ...
;             G_BAR; G_WAIT_L(0); G_MMA(1, 0, At, B0); G_BAR; G_SCHED;
;             G_STAGE(G_SB(1, 1), b3 + hstepB, voffB);
;             G_WAIT_V(6); G_BAR; G_MMA(1, 1, At, B1); G_BAR;
;         }
;         epi(acc, cpm, cpn, wr, wc, fr, fq);
; __global__ void __launch_bounds__(512) hybrid_fwd(Params p) {
;     ...
;           [=](const f32x4 (&acc)[2][2][4][2], int pm, int pn, int wr, int wc, int fr, int fq) {
;               if (pn < 8) epi_bf16<0>(acc, OUTB + (size_t)(pn & 1) * T_ * 1024 + (size_t)pm * 256 * 1024 + (pn >> 1) * 256, 1024, wr, wc, fr, fq);
;               else epi_bf16<0>(acc, RC + (size_t)pm * 256 * 2048 + (pn - 8) * 256, 2048, wr, wc, fr, fq); }, vb); }
.Lfi6_322:
	s_barrier
	s_waitcnt lgkmcnt(0)
	s_setprio 1
	s_waitcnt lgkmcnt(0)
	v_mfma_f32_16x16x32_bf16 v[108:111], v[218:221], v[182:185], v[108:111]
	v_mfma_f32_16x16x32_bf16 v[104:107], v[226:229], v[182:185], v[104:107]
	v_mfma_f32_16x16x32_bf16 v[92:95], v[218:221], v[194:197], v[92:95]
	v_mfma_f32_16x16x32_bf16 v[88:91], v[226:229], v[194:197], v[88:91]
	v_mfma_f32_16x16x32_bf16 v[76:79], v[218:221], v[202:205], v[76:79]
	v_mfma_f32_16x16x32_bf16 v[72:75], v[226:229], v[202:205], v[72:75]
	v_mfma_f32_16x16x32_bf16 v[68:71], v[218:221], v[210:213], v[68:71]
	v_mfma_f32_16x16x32_bf16 v[64:67], v[226:229], v[210:213], v[64:67]
	v_mfma_f32_16x16x32_bf16 v[108:111], v[222:225], v[186:189], v[108:111]
	v_mfma_f32_16x16x32_bf16 v[104:107], v[230:233], v[186:189], v[104:107]
	v_mfma_f32_16x16x32_bf16 v[92:95], v[222:225], v[198:201], v[92:95]
	v_mfma_f32_16x16x32_bf16 v[88:91], v[230:233], v[198:201], v[88:91]
	v_mfma_f32_16x16x32_bf16 v[76:79], v[222:225], v[206:209], v[76:79]
	v_mfma_f32_16x16x32_bf16 v[72:75], v[230:233], v[206:209], v[72:75]
	v_mfma_f32_16x16x32_bf16 v[68:71], v[222:225], v[214:217], v[68:71]
	v_mfma_f32_16x16x32_bf16 v[64:67], v[230:233], v[214:217], v[64:67]
	s_setprio 0
	s_mov_b32 m0, s82
	v_lshl_add_u64 v[190:191], v[236:237], 0, s[56:57]
	s_barrier
	ds_read_b128 v[182:185], v165 offset:49152
	ds_read_b128 v[186:189], v165 offset:50176
	ds_read_b128 v[194:197], v165 offset:51200
	ds_read_b128 v[198:201], v165 offset:52224
	ds_read_b128 v[202:205], v165 offset:53248
	ds_read_b128 v[206:209], v165 offset:54272
	ds_read_b128 v[210:213], v165 offset:55296
	ds_read_b128 v[214:217], v165 offset:56320
	global_load_lds_dwordx4 v[190:191], off
	v_lshl_add_u64 v[190:191], v[238:239], 0, s[56:57]
	s_mov_b32 m0, s83
	s_nop 0
	global_load_lds_dwordx4 v[190:191], off
	s_barrier
	s_waitcnt lgkmcnt(0)
	s_setprio 1
	s_waitcnt lgkmcnt(0)
	v_mfma_f32_16x16x32_bf16 v[60:63], v[166:169], v[182:185], v[60:63]
	v_mfma_f32_16x16x32_bf16 v[56:59], v[174:177], v[182:185], v[56:59]
	v_mfma_f32_16x16x32_bf16 v[52:55], v[166:169], v[194:197], v[52:55]
	v_mfma_f32_16x16x32_bf16 v[48:51], v[174:177], v[194:197], v[48:51]
	v_mfma_f32_16x16x32_bf16 v[36:39], v[166:169], v[202:205], v[36:39]
	v_mfma_f32_16x16x32_bf16 v[32:35], v[174:177], v[202:205], v[32:35]
	v_mfma_f32_16x16x32_bf16 v[20:23], v[166:169], v[210:213], v[20:23]
	v_mfma_f32_16x16x32_bf16 v[16:19], v[174:177], v[210:213], v[16:19]
	v_mfma_f32_16x16x32_bf16 v[60:63], v[170:173], v[186:189], v[60:63]
	v_mfma_f32_16x16x32_bf16 v[56:59], v[178:181], v[186:189], v[56:59]
	v_mfma_f32_16x16x32_bf16 v[52:55], v[170:173], v[198:201], v[52:55]
	v_mfma_f32_16x16x32_bf16 v[48:51], v[178:181], v[198:201], v[48:51]
	v_mfma_f32_16x16x32_bf16 v[36:39], v[170:173], v[206:209], v[36:39]
	v_mfma_f32_16x16x32_bf16 v[32:35], v[178:181], v[206:209], v[32:35]
	v_mfma_f32_16x16x32_bf16 v[20:23], v[170:173], v[214:217], v[20:23]
	v_mfma_f32_16x16x32_bf16 v[16:19], v[178:181], v[214:217], v[16:19]
	s_setprio 0
	s_barrier
	s_add_u32 s58, s58, 0x20080
	s_addc_u32 s59, s59, 0
	s_add_i32 s64, s64, s54
	v_lshl_add_u64 v[166:167], s[58:59], 0, v[136:137]
	s_mov_b32 m0, s64
	s_nop 0
	global_load_lds_dwordx4 v[166:167], off
	v_lshl_add_u64 v[166:167], s[58:59], 0, v[140:141]
	s_add_i32 m0, s64, 0x2000
	s_nop 0
	global_load_lds_dwordx4 v[166:167], off
	s_waitcnt vmcnt(6)
	s_barrier
	s_setprio 1
	v_mfma_f32_16x16x32_bf16 v[44:47], v[218:221], v[182:185], v[44:47]
	v_mfma_f32_16x16x32_bf16 v[40:43], v[226:229], v[182:185], v[40:43]
	v_mfma_f32_16x16x32_bf16 v[28:31], v[218:221], v[194:197], v[28:31]
	v_mfma_f32_16x16x32_bf16 v[24:27], v[226:229], v[194:197], v[24:27]
	v_mfma_f32_16x16x32_bf16 v[12:15], v[218:221], v[202:205], v[12:15]
	v_mfma_f32_16x16x32_bf16 v[8:11], v[226:229], v[202:205], v[8:11]
	v_mfma_f32_16x16x32_bf16 v[4:7], v[218:221], v[210:213], v[4:7]
	v_mfma_f32_16x16x32_bf16 v[0:3], v[226:229], v[210:213], v[0:3]
	v_mfma_f32_16x16x32_bf16 v[44:47], v[222:225], v[186:189], v[44:47]
	v_mfma_f32_16x16x32_bf16 v[40:43], v[230:233], v[186:189], v[40:43]
	v_mfma_f32_16x16x32_bf16 v[28:31], v[222:225], v[198:201], v[28:31]
	v_mfma_f32_16x16x32_bf16 v[24:27], v[230:233], v[198:201], v[24:27]
	v_mfma_f32_16x16x32_bf16 v[12:15], v[222:225], v[206:209], v[12:15]
	v_mfma_f32_16x16x32_bf16 v[8:11], v[230:233], v[206:209], v[8:11]
	v_mfma_f32_16x16x32_bf16 v[4:7], v[222:225], v[214:217], v[4:7]
	v_mfma_f32_16x16x32_bf16 v[0:3], v[230:233], v[214:217], v[0:3]
	s_setprio 0
	s_add_i32 s61, s61, 2
	s_add_u32 s22, s22, 0x100
	s_addc_u32 s23, s23, 0
	s_add_u32 s3, s3, 0x100
	s_addc_u32 s30, s30, 0
	s_cmp_gt_u32 s61, 5
	s_barrier
	s_cbranch_scc0 .LBB0_322
	s_waitcnt vmcnt(0)
	s_cmp_gt_i32 s90, 7
	s_mov_b64 s[22:23], -1
	s_cbranch_scc0 .LBB0_325
	s_ashr_i32 s71, s70, 31
	s_lshl_b64 s[22:23], s[70:71], 20
	s_add_u32 s3, s16, s22
	s_addc_u32 s22, s17, s23
	s_lshl_b32 s23, s90, 9
	s_add_u32 s3, s3, s23
	s_addc_u32 s22, s22, 0
	s_add_u32 s58, s3, 0xfffff000
	s_addc_u32 s59, s22, -1
	s_mov_b64 s[22:23], 0

; #define G_STAGE(bufoff, gbase, voff) do { _Pragma("unroll") for (int _i = 0; _i < 2; ++_i) \
;         __builtin_amdgcn_global_load_lds((const unsigned*)((const char*)(gbase) + (voff)[_i]), (LAS unsigned*)(lds + (bufoff) + ldsw + _i * 8192), 16, 0, 0); } while (0)
; #define G_WAIT_V(n) asm volatile("s_waitcnt vmcnt(" #n ")" ::: "memory")
; #define G_BAR __builtin_amdgcn_s_barrier()
; template <bool PERM, class Dec, class Epi>
; DI void gemm_phase(LAS unsigned char* lds, const int nM, const int nN, const int K, const int lda, const int ldb, const Dec& dec, const Epi& epi, const int vb, const int panel = -1) {
;     ...
;     for (int i = 0; i < 2; ++i) { int R, C; stage_rc(tid * 16 + i * 8192, R, C); const int Rb = PERM ? ((R & ~31) + perm32(R & 31)) : R;
;         voffA[i] = (unsigned)(R * lda + C) * 2u; voffB[i] = (unsigned)(Rb * ldb + C) * 2u; }
;     const size_t kstep = (size_t)(BK * 2);
;     const size_t hstepA = (size_t)HALF * lda * 2, hstepB = (size_t)HALF * ldb * 2;
;     const unsigned ldsw = (unsigned)wid * 1024u;
;     const int aoff = lds_byte(wr * 64 + fr, fq * 8), boff = lds_byte(wc * 32 + fr, fq * 8);
;     ...
;     int cpm, cpn, npm, npn, ui = 0;
;     if (panel >= 0) { cpm = panel; cpn = 0; } else if (!unit_next(0, nM, nN, vb, cpm, cpn)) return;
;     f32x4 acc[2][2][4][2];
; #pragma unroll
;     for (int a = 0; a < 2; ++a)
; #pragma unroll
;         for (int b = 0; b < 2; ++b)
; #pragma unroll
;             for (int m = 0; m < 4; ++m)
; #pragma unroll
;                 for (int n = 0; n < 2; ++n) acc[a][b][m][n] = (f32x4){0.f, 0.f, 0.f, 0.f};
;     bf16x8 At[4][2], B0[2][2], B1[2][2];
;     const char* cA; const char* cB; dec(cpm, cpn, cA, cB);
;     G_STAGE(G_SB(0, 0), cB, voffB); G_STAGE(G_SA(0, 0), cA, voffA); G_STAGE(G_SB(0, 1), cB + hstepB, voffB); G_STAGE(G_SA(0, 1), cA + hstepA, voffA);
;     if (wr == 1) G_BAR;
;     G_WAIT_V(4); G_BAR;
;     G_STAGE(G_SB(1, 0), cB + kstep, voffB); G_STAGE(G_SA(1, 0), cA + kstep, voffA); G_STAGE(G_SB(1, 1), cB + hstepB + kstep, voffB);
;     G_WAIT_V(6); G_BAR;
.LBB0_478:
	v_lshrrev_b32_e32 v17, 1, v14
	v_and_b32_e32 v17, 24, v17
	v_and_b32_e32 v15, 15, v14
	v_lshlrev_b32_e32 v18, 1, v17
	v_lshlrev_b32_e32 v14, 2, v14
	v_lshl_or_b32 v16, s4, 6, v15
	v_lshl_or_b32 v15, v15, 6, v18
	s_lshl_b32 s3, s4, 13
	v_and_b32_e32 v14, 32, v14
	v_bitop3_b32 v18, v15, s3, v14 bitop3:0xde
	s_lshl_b32 s3, s5, 5
	s_and_b32 s3, s3, 0x60
	s_add_i32 m0, s35, 0x18000
	v_lshl_add_u64 v[6:7], v[6:7], 0, s[0:1]
	s_lshl_b32 s4, s3, 7
	s_waitcnt vmcnt(4)
	s_barrier
	global_load_lds_dwordx4 v[6:7], off
	v_lshl_add_u64 v[4:5], v[4:5], 0, s[0:1]
	s_add_i32 m0, s35, 0x1a000
	s_add_i32 s50, s35, 0x8000
	s_add_i32 s51, s35, 0xa000
	v_bitop3_b32 v165, v15, s4, v14 bitop3:0xde
	global_load_lds_dwordx4 v[4:5], off
	v_lshl_add_u64 v[2:3], v[2:3], 0, s[0:1]
	s_mov_b32 m0, s50
	s_add_u32 s4, s36, 0x40080
	global_load_lds_dwordx4 v[2:3], off
	v_lshl_add_u64 v[0:1], v[0:1], 0, s[0:1]
	s_mov_b32 m0, s51
	s_addc_u32 s5, s37, 0
	global_load_lds_dwordx4 v[0:1], off
	s_add_i32 m0, s35, 0x1c000
	v_lshl_add_u64 v[0:1], s[4:5], 0, v[128:129]
	global_load_lds_dwordx4 v[0:1], off
	v_lshl_add_u64 v[0:1], s[4:5], 0, v[138:139]
	s_add_i32 m0, s35, 0x1e000
	v_or_b32_e32 v2, s3, v17
	global_load_lds_dwordx4 v[0:1], off
	v_or_b32_e32 v0, 16, v16
	v_ashrrev_i32_e32 v1, 31, v0
	v_lshlrev_b64 v[142:143], 11, v[0:1]
	v_or_b32_e32 v0, 32, v16
	v_ashrrev_i32_e32 v1, 31, v0
	v_lshlrev_b64 v[144:145], 11, v[0:1]
	v_or_b32_e32 v0, 48, v16
	v_ashrrev_i32_e32 v1, 31, v0
	v_lshlrev_b64 v[146:147], 11, v[0:1]
	v_lshlrev_b32_e32 v0, 14, v8
	v_and_b32_e32 v0, 0xffff8000, v0
	v_ashrrev_i32_e32 v17, 31, v16
	v_lshl_add_u32 v0, v9, 11, v0
	v_and_b32_e32 v1, 1, v8
	v_lshlrev_b64 v[140:141], 11, v[16:17]
	v_lshl_or_b32 v0, v1, 6, v0
	v_or_b32_e32 v140, v140, v2
	s_mov_b64 s[4:5], 0x40000
	v_lshl_add_u32 v156, v10, 1, v0
	v_lshlrev_b32_e32 v0, 14, v11
	v_lshl_add_u64 v[148:149], v[140:141], 0, s[4:5]
	s_mov_b64 s[4:5], 0x48000
	v_and_b32_e32 v0, 0xffff8000, v0
	s_waitcnt vmcnt(0)
	v_lshl_add_u64 v[150:151], v[140:141], 0, s[4:5]
	s_mov_b64 s[4:5], 0x50000
	v_lshl_add_u32 v0, v12, 11, v0
	v_and_b32_e32 v1, 1, v11
	v_lshl_add_u64 v[152:153], v[140:141], 0, s[4:5]
	s_mov_b64 s[4:5], 0x58000
	v_lshl_or_b32 v0, v1, 6, v0
	v_or_b32_e32 v142, v142, v2
	v_or_b32_e32 v144, v144, v2
	v_or_b32_e32 v146, v146, v2
	v_lshl_add_u64 v[154:155], v[140:141], 0, s[4:5]
	v_mov_b32_e32 v157, v129
	v_lshl_add_u32 v158, v13, 1, v0
	v_mov_b32_e32 v159, v129
	s_mov_b32 s52, 0
	v_add_u32_e32 v166, 0, v18
	s_barrier
	s_waitcnt vmcnt(0)
	s_branch .LBB0_480

; #define G_STAGE(bufoff, gbase, voff) do { _Pragma("unroll") for (int _i = 0; _i < 2; ++_i) \
;         __builtin_amdgcn_global_load_lds((const unsigned*)((const char*)(gbase) + (voff)[_i]), (LAS unsigned*)(lds + (bufoff) + ldsw + _i * 8192), 16, 0, 0); } while (0)
; #define G_LDA(dst, b, h) do { _Pragma("unroll") for (int m = 0; m < 4; ++m) _Pragma("unroll") for (int k = 0; k < 2; ++k) dst[m][k] = *(const LAS bf16x8*)(lds + G_SA(b, h) + aoff + m * 2048 + k * 1024); } while (0)
; #define G_LDB(dst, b, h) do { _Pragma("unroll") for (int n = 0; n < 2; ++n) _Pragma("unroll") for (int k = 0; k < 2; ++k) dst[n][k] = *(const LAS bf16x8*)(lds + G_SB(b, h) + boff + n * 2048 + k * 1024); } while (0)
; #define G_WAIT_V(n) asm volatile("s_waitcnt vmcnt(" #n ")" ::: "memory")
; #define G_WAIT_L(n) asm volatile("s_waitcnt lgkmcnt(" #n ")" ::: "memory")
; #define G_BAR __builtin_amdgcn_s_barrier()
; #define G_SCHED __builtin_amdgcn_sched_barrier(0)
; template <bool PERM, class Dec, class Epi>
; DI void gemm_phase(LAS unsigned char* lds, const int nM, const int nN, const int K, const int lda, const int ldb, const Dec& dec, const Epi& epi, const int vb, const int panel = -1) {
;     ...
;         if (panel >= 0) { has_next = (ui + 1 < nN); npm = panel; npn = ui + 1; } else has_next = unit_next(ui + 1, nM, nN, vb, npm, npn);
;         const char* nA = cA; const char* nB = cB; if (has_next) dec(npm, npn, nA, nB);
; #pragma nounroll
;         for (int t = 0; t < nt; t += 2) {
;             const bool last = (t == nt - 2);
;             const char* a1 = cA + (size_t)(t + 1) * kstep;
;             const char* a2 = last ? nA : cA + (size_t)(t + 2) * kstep; const char* b2 = last ? nB : cB + (size_t)(t + 2) * kstep;
;             const char* a3 = a2 + kstep; const char* b3 = b2 + kstep;
;             G_LDB(B0, 0, 0); G_SCHED; G_LDA(At, 0, 0); G_STAGE(G_SA(1, 1), a1 + hstepA, voffA);
;             G_WAIT_L(8); G_BAR; G_WAIT_L(0); G_MMA(0, 0, At, B0); G_BAR; G_SCHED;
;             G_LDB(B1, 0, 1); G_STAGE(G_SB(0, 0), b2, voffB);
;             G_BAR; G_WAIT_L(0); G_MMA(0, 1, At, B1); G_BAR;
;             G_LDA(At, 0, 1); G_STAGE(G_SA(0, 0), a2, voffA);
;             G_BAR; G_WAIT_L(0); G_MMA(1, 0, At, B0); G_BAR; G_SCHED;
;             G_STAGE(G_SB(0, 1), b2 + hstepB, voffB);
;             G_WAIT_V(6); G_BAR; G_MMA(1, 1, At, B1); G_BAR;
.LBB0_483:
	s_add_u32 s36, s22, 0xfffc0080
	s_addc_u32 s37, s23, -1
	s_add_i32 s57, 0, 0x10000
	v_add_u32_e32 v167, s57, v165
	ds_read_b128 v[160:163], v167
	ds_read_b128 v[172:175], v167 offset:1024
	ds_read_b128 v[176:179], v167 offset:2048
	ds_read_b128 v[180:183], v167 offset:3072
	s_cmp_eq_u32 s56, 12
	s_cselect_b32 s45, s3, s37
	s_cselect_b32 s44, s5, s36
	s_cselect_b32 s37, s7, s55
	s_cselect_b32 s36, s53, s54
	v_lshl_add_u64 v[168:169], s[22:23], 0, v[156:157]
	s_add_i32 m0, s35, 0xc000
	ds_read_b128 v[184:187], v166
	ds_read_b128 v[188:191], v166 offset:1024
	ds_read_b128 v[194:197], v166 offset:2048
	ds_read_b128 v[198:201], v166 offset:3072
	ds_read_b128 v[202:205], v166 offset:4096
	ds_read_b128 v[206:209], v166 offset:5120
	ds_read_b128 v[210:213], v166 offset:6144
	ds_read_b128 v[214:217], v166 offset:7168
	global_load_lds_dwordx4 v[168:169], off
	v_lshl_add_u64 v[168:169], s[22:23], 0, v[158:159]
	s_add_i32 m0, s35, 0xe000
	s_nop 0
	global_load_lds_dwordx4 v[168:169], off
	s_waitcnt lgkmcnt(8)
	s_barrier
	s_waitcnt lgkmcnt(0)
	s_setprio 1
	s_waitcnt lgkmcnt(0)
	v_mfma_f32_16x16x32_bf16 v[124:127], v[160:163], v[184:187], v[124:127]
	v_mfma_f32_16x16x32_bf16 v[120:123], v[176:179], v[184:187], v[120:123]
	v_mfma_f32_16x16x32_bf16 v[108:111], v[160:163], v[194:197], v[108:111]
	v_mfma_f32_16x16x32_bf16 v[104:107], v[176:179], v[194:197], v[104:107]
	v_mfma_f32_16x16x32_bf16 v[92:95], v[160:163], v[202:205], v[92:95]
	v_mfma_f32_16x16x32_bf16 v[88:91], v[176:179], v[202:205], v[88:91]
	v_mfma_f32_16x16x32_bf16 v[76:79], v[160:163], v[210:213], v[76:79]
	v_mfma_f32_16x16x32_bf16 v[72:75], v[176:179], v[210:213], v[72:75]
	v_mfma_f32_16x16x32_bf16 v[124:127], v[172:175], v[188:191], v[124:127]
	v_mfma_f32_16x16x32_bf16 v[120:123], v[180:183], v[188:191], v[120:123]
	v_mfma_f32_16x16x32_bf16 v[108:111], v[172:175], v[198:201], v[108:111]
	v_mfma_f32_16x16x32_bf16 v[104:107], v[180:183], v[198:201], v[104:107]
	v_mfma_f32_16x16x32_bf16 v[92:95], v[172:175], v[206:209], v[92:95]
	v_mfma_f32_16x16x32_bf16 v[88:91], v[180:183], v[206:209], v[88:91]
	v_mfma_f32_16x16x32_bf16 v[76:79], v[172:175], v[214:217], v[76:79]
	v_mfma_f32_16x16x32_bf16 v[72:75], v[180:183], v[214:217], v[72:75]
	s_setprio 0
	s_barrier
	s_add_i32 s60, 0, 0x14000
	s_add_i32 s57, s57, s46
	v_add_u32_e32 v167, s60, v165
	v_lshl_add_u64 v[168:169], s[36:37], 0, v[128:129]
	s_mov_b32 m0, s57
	ds_read_b128 v[218:221], v167
	ds_read_b128 v[222:225], v167 offset:1024
	ds_read_b128 v[226:229], v167 offset:2048
	ds_read_b128 v[230:233], v167 offset:3072
	global_load_lds_dwordx4 v[168:169], off
	v_lshl_add_u64 v[234:235], s[36:37], 0, v[138:139]
	s_add_i32 m0, s57, 0x2000
	s_nop 0
	global_load_lds_dwordx4 v[234:235], off
	s_barrier
	s_waitcnt lgkmcnt(0)
	s_setprio 1
	s_waitcnt lgkmcnt(0)
	v_mfma_f32_16x16x32_bf16 v[116:119], v[218:221], v[184:187], v[116:119]
	v_mfma_f32_16x16x32_bf16 v[112:115], v[226:229], v[184:187], v[112:115]
	v_mfma_f32_16x16x32_bf16 v[100:103], v[218:221], v[194:197], v[100:103]
	v_mfma_f32_16x16x32_bf16 v[96:99], v[226:229], v[194:197], v[96:99]
	v_mfma_f32_16x16x32_bf16 v[84:87], v[218:221], v[202:205], v[84:87]
	v_mfma_f32_16x16x32_bf16 v[80:83], v[226:229], v[202:205], v[80:83]
	v_mfma_f32_16x16x32_bf16 v[68:71], v[218:221], v[210:213], v[68:71]
	v_mfma_f32_16x16x32_bf16 v[64:67], v[226:229], v[210:213], v[64:67]
	v_mfma_f32_16x16x32_bf16 v[116:119], v[222:225], v[188:191], v[116:119]
	v_mfma_f32_16x16x32_bf16 v[112:115], v[230:233], v[188:191], v[112:115]
	v_mfma_f32_16x16x32_bf16 v[100:103], v[222:225], v[198:201], v[100:103]
	v_mfma_f32_16x16x32_bf16 v[96:99], v[230:233], v[198:201], v[96:99]
	v_mfma_f32_16x16x32_bf16 v[84:87], v[222:225], v[206:209], v[84:87]
	v_mfma_f32_16x16x32_bf16 v[80:83], v[230:233], v[206:209], v[80:83]
	v_mfma_f32_16x16x32_bf16 v[68:71], v[222:225], v[214:217], v[68:71]
	v_mfma_f32_16x16x32_bf16 v[64:67], v[230:233], v[214:217], v[64:67]
	s_setprio 0
	s_mov_b32 m0, s35
	v_lshl_add_u64 v[236:237], s[44:45], 0, v[134:135]
	s_barrier
	ds_read_b128 v[184:187], v166 offset:16384
	ds_read_b128 v[188:191], v166 offset:17408
	ds_read_b128 v[194:197], v166 offset:18432
	ds_read_b128 v[198:201], v166 offset:19456
	ds_read_b128 v[202:205], v166 offset:20480
	ds_read_b128 v[206:209], v166 offset:21504
	ds_read_b128 v[210:213], v166 offset:22528
	ds_read_b128 v[214:217], v166 offset:23552
	global_load_lds_dwordx4 v[236:237], off
	v_lshl_add_u64 v[238:239], s[44:45], 0, v[136:137]
	s_mov_b32 m0, s47
	s_nop 0
	global_load_lds_dwordx4 v[238:239], off
	s_barrier
	s_waitcnt lgkmcnt(0)
	s_setprio 1
	s_waitcnt lgkmcnt(0)
	v_mfma_f32_16x16x32_bf16 v[60:63], v[160:163], v[184:187], v[60:63]
	v_mfma_f32_16x16x32_bf16 v[56:59], v[176:179], v[184:187], v[56:59]
	v_mfma_f32_16x16x32_bf16 v[44:47], v[160:163], v[194:197], v[44:47]
	v_mfma_f32_16x16x32_bf16 v[40:43], v[176:179], v[194:197], v[40:43]
	v_mfma_f32_16x16x32_bf16 v[28:31], v[160:163], v[202:205], v[28:31]
	v_mfma_f32_16x16x32_bf16 v[24:27], v[176:179], v[202:205], v[24:27]
	v_mfma_f32_16x16x32_bf16 v[12:15], v[160:163], v[210:213], v[12:15]
	v_mfma_f32_16x16x32_bf16 v[8:11], v[176:179], v[210:213], v[8:11]
	v_mfma_f32_16x16x32_bf16 v[60:63], v[172:175], v[188:191], v[60:63]
	v_mfma_f32_16x16x32_bf16 v[56:59], v[180:183], v[188:191], v[56:59]
	v_mfma_f32_16x16x32_bf16 v[44:47], v[172:175], v[198:201], v[44:47]
	v_mfma_f32_16x16x32_bf16 v[40:43], v[180:183], v[198:201], v[40:43]
	v_mfma_f32_16x16x32_bf16 v[28:31], v[172:175], v[206:209], v[28:31]
	v_mfma_f32_16x16x32_bf16 v[24:27], v[180:183], v[206:209], v[24:27]
	v_mfma_f32_16x16x32_bf16 v[12:15], v[172:175], v[214:217], v[12:15]
	v_mfma_f32_16x16x32_bf16 v[8:11], v[180:183], v[214:217], v[8:11]
	s_setprio 0
	s_barrier
	s_add_u32 s58, s36, 0x40000
	s_addc_u32 s59, s37, 0
	s_add_i32 s57, s60, s46
	v_lshl_add_u64 v[160:161], s[58:59], 0, v[128:129]
	s_mov_b32 m0, s57
	s_nop 0
	global_load_lds_dwordx4 v[160:161], off
	v_lshl_add_u64 v[160:161], s[58:59], 0, v[138:139]
	s_add_i32 m0, s57, 0x2000
	s_nop 0
	global_load_lds_dwordx4 v[160:161], off
	s_cmp_eq_u32 s56, -2
	s_cbranch_scc1 .Lfi4_483
	s_waitcnt vmcnt(6)
; #define G_STAGE(bufoff, gbase, voff) do { _Pragma("unroll") for (int _i = 0; _i < 2; ++_i) \
;         __builtin_amdgcn_global_load_lds((const unsigned*)((const char*)(gbase) + (voff)[_i]), (LAS unsigned*)(lds + (bufoff) + ldsw + _i * 8192), 16, 0, 0); } while (0)
; #define G_LDA(dst, b, h) do { _Pragma("unroll") for (int m = 0; m < 4; ++m) _Pragma("unroll") for (int k = 0; k < 2; ++k) dst[m][k] = *(const LAS bf16x8*)(lds + G_SA(b, h) + aoff + m * 2048 + k * 1024); } while (0)
; #define G_LDB(dst, b, h) do { _Pragma("unroll") for (int n = 0; n < 2; ++n) _Pragma("unroll") for (int k = 0; k < 2; ++k) dst[n][k] = *(const LAS bf16x8*)(lds + G_SB(b, h) + boff + n * 2048 + k * 1024); } while (0)
; #define G_MMA(ai, bj, At, Bt) do { __builtin_amdgcn_s_setprio(1); _Pragma("unroll") for (int m = 0; m < 4; ++m) _Pragma("unroll") for (int n = 0; n < 2; ++n) _Pragma("unroll") for (int k = 0; k < 2; ++k) \
;         acc[ai][bj][m][n] = __builtin_amdgcn_mfma_f32_16x16x32_bf16(Bt[n][k], At[m][k], acc[ai][bj][m][n], 0, 0, 0); __builtin_amdgcn_s_setprio(0); } while (0)
; #define G_WAIT_V(n) asm volatile("s_waitcnt vmcnt(" #n ")" ::: "memory")
; #define G_WAIT_L(n) asm volatile("s_waitcnt lgkmcnt(" #n ")" ::: "memory")
; #define G_BAR __builtin_amdgcn_s_barrier()
; #define G_SCHED __builtin_amdgcn_sched_barrier(0)
; template <bool PERM, class Dec, class Epi>
; DI void gemm_phase(LAS unsigned char* lds, const int nM, const int nN, const int K, const int lda, const int ldb, const Dec& dec, const Epi& epi, const int vb, const int panel = -1) {
;     ...
;             G_WAIT_V(6); G_BAR; G_MMA(1, 1, At, B1); G_BAR;
;             G_LDB(B0, 1, 0); G_SCHED; G_LDA(At, 1, 0); G_STAGE(G_SA(0, 1), a2 + hstepA, voffA);
;             G_WAIT_L(8); G_BAR; G_WAIT_L(0); G_MMA(0, 0, At, B0); G_BAR; G_SCHED;
;             G_LDB(B1, 1, 1); G_STAGE(G_SB(1, 0), b3, voffB);
;             G_BAR; G_WAIT_L(0); G_MMA(0, 1, At, B1); G_BAR;
.Lfi4_483:
	s_barrier
	s_setprio 1
	v_mfma_f32_16x16x32_bf16 v[52:55], v[218:221], v[184:187], v[52:55]
	v_mfma_f32_16x16x32_bf16 v[48:51], v[226:229], v[184:187], v[48:51]
	v_mfma_f32_16x16x32_bf16 v[36:39], v[218:221], v[194:197], v[36:39]
	v_mfma_f32_16x16x32_bf16 v[32:35], v[226:229], v[194:197], v[32:35]
	v_mfma_f32_16x16x32_bf16 v[20:23], v[218:221], v[202:205], v[20:23]
	v_mfma_f32_16x16x32_bf16 v[16:19], v[226:229], v[202:205], v[16:19]
	v_mfma_f32_16x16x32_bf16 v[4:7], v[218:221], v[210:213], v[4:7]
	v_mfma_f32_16x16x32_bf16 v[0:3], v[226:229], v[210:213], v[0:3]
	v_mfma_f32_16x16x32_bf16 v[52:55], v[222:225], v[188:191], v[52:55]
	v_mfma_f32_16x16x32_bf16 v[48:51], v[230:233], v[188:191], v[48:51]
	v_mfma_f32_16x16x32_bf16 v[36:39], v[222:225], v[198:201], v[36:39]
	v_mfma_f32_16x16x32_bf16 v[32:35], v[230:233], v[198:201], v[32:35]
	v_mfma_f32_16x16x32_bf16 v[20:23], v[222:225], v[206:209], v[20:23]
	v_mfma_f32_16x16x32_bf16 v[16:19], v[230:233], v[206:209], v[16:19]
	v_mfma_f32_16x16x32_bf16 v[4:7], v[222:225], v[214:217], v[4:7]
	v_mfma_f32_16x16x32_bf16 v[0:3], v[230:233], v[214:217], v[0:3]
	s_setprio 0
	s_add_i32 s57, 0, 0x18000
	v_add_u32_e32 v167, s57, v165
	s_barrier
	ds_read_b128 v[160:163], v167
	ds_read_b128 v[172:175], v167 offset:1024
	ds_read_b128 v[176:179], v167 offset:2048
	ds_read_b128 v[180:183], v167 offset:3072
	s_add_u32 s44, s44, 0x40000
	s_addc_u32 s45, s45, 0
	s_mov_b32 m0, s48
	v_lshl_add_u64 v[218:219], s[44:45], 0, v[134:135]
	ds_read_b128 v[184:187], v166 offset:32768
	ds_read_b128 v[188:191], v166 offset:33792
	ds_read_b128 v[194:197], v166 offset:34816
	ds_read_b128 v[198:201], v166 offset:35840
	ds_read_b128 v[202:205], v166 offset:36864
	ds_read_b128 v[206:209], v166 offset:37888
	ds_read_b128 v[210:213], v166 offset:38912
	ds_read_b128 v[214:217], v166 offset:39936
	global_load_lds_dwordx4 v[218:219], off
	v_lshl_add_u64 v[218:219], s[44:45], 0, v[136:137]
	s_mov_b32 m0, s49
	s_nop 0
	global_load_lds_dwordx4 v[218:219], off
	s_waitcnt lgkmcnt(8)
	s_barrier
	s_waitcnt lgkmcnt(0)
	s_setprio 1
	s_waitcnt lgkmcnt(0)
	v_mfma_f32_16x16x32_bf16 v[124:127], v[160:163], v[184:187], v[124:127]
	v_mfma_f32_16x16x32_bf16 v[120:123], v[176:179], v[184:187], v[120:123]
	v_mfma_f32_16x16x32_bf16 v[108:111], v[160:163], v[194:197], v[108:111]
	v_mfma_f32_16x16x32_bf16 v[104:107], v[176:179], v[194:197], v[104:107]
	v_mfma_f32_16x16x32_bf16 v[92:95], v[160:163], v[202:205], v[92:95]
	v_mfma_f32_16x16x32_bf16 v[88:91], v[176:179], v[202:205], v[88:91]
	v_mfma_f32_16x16x32_bf16 v[76:79], v[160:163], v[210:213], v[76:79]
	v_mfma_f32_16x16x32_bf16 v[72:75], v[176:179], v[210:213], v[72:75]
	v_mfma_f32_16x16x32_bf16 v[124:127], v[172:175], v[188:191], v[124:127]
	v_mfma_f32_16x16x32_bf16 v[120:123], v[180:183], v[188:191], v[120:123]
	v_mfma_f32_16x16x32_bf16 v[108:111], v[172:175], v[198:201], v[108:111]
	v_mfma_f32_16x16x32_bf16 v[104:107], v[180:183], v[198:201], v[104:107]
	v_mfma_f32_16x16x32_bf16 v[92:95], v[172:175], v[206:209], v[92:95]
	v_mfma_f32_16x16x32_bf16 v[88:91], v[180:183], v[206:209], v[88:91]
	v_mfma_f32_16x16x32_bf16 v[76:79], v[172:175], v[214:217], v[76:79]
	v_mfma_f32_16x16x32_bf16 v[72:75], v[180:183], v[214:217], v[72:75]
	s_setprio 0
	s_barrier
	s_add_i32 s44, 0, 0x1c000
	s_add_i32 s45, s57, s46
	v_add_u32_e32 v167, s44, v165
	v_lshl_add_u64 v[168:169], v[168:169], 0, s[0:1]
	s_mov_b32 m0, s45
	ds_read_b128 v[218:221], v167
	ds_read_b128 v[222:225], v167 offset:1024
	ds_read_b128 v[226:229], v167 offset:2048
	ds_read_b128 v[230:233], v167 offset:3072
	global_load_lds_dwordx4 v[168:169], off
	v_lshl_add_u64 v[168:169], v[234:235], 0, s[0:1]
	s_add_i32 m0, s45, 0x2000
	s_nop 0
	global_load_lds_dwordx4 v[168:169], off
	s_cmp_lg_u32 s56, -2
	s_cbranch_scc1 .Lfi6_483
	s_waitcnt vmcnt(10)
; DI unsigned pk2(float a, float b) { f32x2 v = {a, b}; bf2_t r = __builtin_convertvector(v, bf2_t); return __builtin_bit_cast(unsigned, r); }
; DI unsigned pk_fp8x4(float a, float b, float c, float d) { int w = __builtin_amdgcn_cvt_pk_fp8_f32(a, b, 0, false); w = __builtin_amdgcn_cvt_pk_fp8_f32(c, d, w, true); return (unsigned)w; }
; #define G_STAGE(bufoff, gbase, voff) do { _Pragma("unroll") for (int _i = 0; _i < 2; ++_i) \
;         __builtin_amdgcn_global_load_lds((const unsigned*)((const char*)(gbase) + (voff)[_i]), (LAS unsigned*)(lds + (bufoff) + ldsw + _i * 8192), 16, 0, 0); } while (0)
; #define G_LDA(dst, b, h) do { _Pragma("unroll") for (int m = 0; m < 4; ++m) _Pragma("unroll") for (int k = 0; k < 2; ++k) dst[m][k] = *(const LAS bf16x8*)(lds + G_SA(b, h) + aoff + m * 2048 + k * 1024); } while (0)
; #define G_WAIT_V(n) asm volatile("s_waitcnt vmcnt(" #n ")" ::: "memory")
; template <bool PERM, class Dec, class Epi>
; DI void gemm_phase(LAS unsigned char* lds, const int nM, const int nN, const int K, const int lda, const int ldb, const Dec& dec, const Epi& epi, const int vb, const int panel = -1) {
;     ...
;             G_BAR; G_WAIT_L(0); G_MMA(0, 1, At, B1); G_BAR;
;             G_LDA(At, 1, 1); G_STAGE(G_SA(1, 0), a3, voffA);
;             G_BAR; G_WAIT_L(0); G_MMA(1, 0, At, B0); G_BAR; G_SCHED;
;             G_STAGE(G_SB(1, 1), b3 + hstepB, voffB);
;             G_WAIT_V(6); G_BAR; G_MMA(1, 1, At, B1); G_BAR;
;         }
;         epi(acc, cpm, cpn, wr, wc, fr, fq);
;         if (!has_next) break;
; DI void epi_zo(const f32x4 (&acc)[2][2][4][2], unsigned char* O, const int esz, int wr, int wc, int fr, int fq) {
; #pragma unroll
;     for (int ai = 0; ai < 2; ++ai)
; #pragma unroll
;         for (int m = 0; m < 4; ++m) {
;             unsigned char* rowp = O + ((size_t)(ai * HALF + wr * 64 + m * 16 + fr) * 2048 + wc * 32 + 8 * fq) * esz;
; #pragma unroll
;             for (int bj = 0; bj < 2; ++bj) {
;                 const f32x4 v0 = acc[ai][bj][m][0], v1 = acc[ai][bj][m][1];
;                 if (esz == 2) { u32x4 w; w[0] = pk2(v0[0], v0[1]); w[1] = pk2(v0[2], v0[3]); w[2] = pk2(v1[0], v1[1]); w[3] = pk2(v1[2], v1[3]); *(u32x4*)(rowp + bj * HALF * 2) = w; }
;                 else { u32x2 w; w[0] = pk_fp8x4(v0[0], v0[1], v0[2], v0[3]); w[1] = pk_fp8x4(v1[0], v1[1], v1[2], v1[3]); *(u32x2*)(rowp + bj * HALF) = w; }
.Lfi6_483:
	s_barrier
	s_waitcnt lgkmcnt(0)
	s_setprio 1
	s_waitcnt lgkmcnt(0)
	v_mfma_f32_16x16x32_bf16 v[116:119], v[218:221], v[184:187], v[116:119]
	v_mfma_f32_16x16x32_bf16 v[112:115], v[226:229], v[184:187], v[112:115]
	v_mfma_f32_16x16x32_bf16 v[100:103], v[218:221], v[194:197], v[100:103]
	v_mfma_f32_16x16x32_bf16 v[96:99], v[226:229], v[194:197], v[96:99]
	v_mfma_f32_16x16x32_bf16 v[84:87], v[218:221], v[202:205], v[84:87]
	v_mfma_f32_16x16x32_bf16 v[80:83], v[226:229], v[202:205], v[80:83]
	v_mfma_f32_16x16x32_bf16 v[68:71], v[218:221], v[210:213], v[68:71]
	v_mfma_f32_16x16x32_bf16 v[64:67], v[226:229], v[210:213], v[64:67]
	v_mfma_f32_16x16x32_bf16 v[116:119], v[222:225], v[188:191], v[116:119]
	v_mfma_f32_16x16x32_bf16 v[112:115], v[230:233], v[188:191], v[112:115]
	v_mfma_f32_16x16x32_bf16 v[100:103], v[222:225], v[198:201], v[100:103]
	v_mfma_f32_16x16x32_bf16 v[96:99], v[230:233], v[198:201], v[96:99]
	v_mfma_f32_16x16x32_bf16 v[84:87], v[222:225], v[206:209], v[84:87]
	v_mfma_f32_16x16x32_bf16 v[80:83], v[230:233], v[206:209], v[80:83]
	v_mfma_f32_16x16x32_bf16 v[68:71], v[222:225], v[214:217], v[68:71]
	v_mfma_f32_16x16x32_bf16 v[64:67], v[230:233], v[214:217], v[64:67]
	s_setprio 0
	s_mov_b32 m0, s50
	v_lshl_add_u64 v[168:169], v[236:237], 0, s[0:1]
	s_barrier
	ds_read_b128 v[184:187], v166 offset:49152
	ds_read_b128 v[188:191], v166 offset:50176
	ds_read_b128 v[194:197], v166 offset:51200
	ds_read_b128 v[198:201], v166 offset:52224
	ds_read_b128 v[202:205], v166 offset:53248
	ds_read_b128 v[206:209], v166 offset:54272
	ds_read_b128 v[210:213], v166 offset:55296
	ds_read_b128 v[214:217], v166 offset:56320
	global_load_lds_dwordx4 v[168:169], off
	v_lshl_add_u64 v[168:169], v[238:239], 0, s[0:1]
	s_mov_b32 m0, s51
	s_nop 0
	global_load_lds_dwordx4 v[168:169], off
	s_barrier
	s_waitcnt lgkmcnt(0)
	s_setprio 1
	s_waitcnt lgkmcnt(0)
	v_mfma_f32_16x16x32_bf16 v[60:63], v[160:163], v[184:187], v[60:63]
	v_mfma_f32_16x16x32_bf16 v[56:59], v[176:179], v[184:187], v[56:59]
	v_mfma_f32_16x16x32_bf16 v[44:47], v[160:163], v[194:197], v[44:47]
	v_mfma_f32_16x16x32_bf16 v[40:43], v[176:179], v[194:197], v[40:43]
	v_mfma_f32_16x16x32_bf16 v[28:31], v[160:163], v[202:205], v[28:31]
	v_mfma_f32_16x16x32_bf16 v[24:27], v[176:179], v[202:205], v[24:27]
	v_mfma_f32_16x16x32_bf16 v[12:15], v[160:163], v[210:213], v[12:15]
	v_mfma_f32_16x16x32_bf16 v[8:11], v[176:179], v[210:213], v[8:11]
	v_mfma_f32_16x16x32_bf16 v[60:63], v[172:175], v[188:191], v[60:63]
	v_mfma_f32_16x16x32_bf16 v[56:59], v[180:183], v[188:191], v[56:59]
	v_mfma_f32_16x16x32_bf16 v[44:47], v[172:175], v[198:201], v[44:47]
	v_mfma_f32_16x16x32_bf16 v[40:43], v[180:183], v[198:201], v[40:43]
	v_mfma_f32_16x16x32_bf16 v[28:31], v[172:175], v[206:209], v[28:31]
	v_mfma_f32_16x16x32_bf16 v[24:27], v[180:183], v[206:209], v[24:27]
	v_mfma_f32_16x16x32_bf16 v[12:15], v[172:175], v[214:217], v[12:15]
	v_mfma_f32_16x16x32_bf16 v[8:11], v[180:183], v[214:217], v[8:11]
	s_setprio 0
	s_barrier
	s_add_u32 s36, s36, 0x40080
	s_addc_u32 s37, s37, 0
	s_add_i32 s44, s44, s46
	v_lshl_add_u64 v[160:161], s[36:37], 0, v[128:129]
	s_mov_b32 m0, s44
	s_nop 0
	global_load_lds_dwordx4 v[160:161], off
	v_lshl_add_u64 v[160:161], s[36:37], 0, v[138:139]
	s_add_i32 m0, s44, 0x2000
	s_nop 0
	global_load_lds_dwordx4 v[160:161], off
	s_waitcnt vmcnt(6)
	s_barrier
	s_setprio 1
	v_mfma_f32_16x16x32_bf16 v[52:55], v[218:221], v[184:187], v[52:55]
	v_mfma_f32_16x16x32_bf16 v[48:51], v[226:229], v[184:187], v[48:51]
	v_mfma_f32_16x16x32_bf16 v[36:39], v[218:221], v[194:197], v[36:39]
	v_mfma_f32_16x16x32_bf16 v[32:35], v[226:229], v[194:197], v[32:35]
	v_mfma_f32_16x16x32_bf16 v[20:23], v[218:221], v[202:205], v[20:23]
	v_mfma_f32_16x16x32_bf16 v[16:19], v[226:229], v[202:205], v[16:19]
	v_mfma_f32_16x16x32_bf16 v[4:7], v[218:221], v[210:213], v[4:7]
	v_mfma_f32_16x16x32_bf16 v[0:3], v[226:229], v[210:213], v[0:3]
	v_mfma_f32_16x16x32_bf16 v[52:55], v[222:225], v[188:191], v[52:55]
	v_mfma_f32_16x16x32_bf16 v[48:51], v[230:233], v[188:191], v[48:51]
	v_mfma_f32_16x16x32_bf16 v[36:39], v[222:225], v[198:201], v[36:39]
	v_mfma_f32_16x16x32_bf16 v[32:35], v[230:233], v[198:201], v[32:35]
	v_mfma_f32_16x16x32_bf16 v[20:23], v[222:225], v[206:209], v[20:23]
	v_mfma_f32_16x16x32_bf16 v[16:19], v[230:233], v[206:209], v[16:19]
	v_mfma_f32_16x16x32_bf16 v[4:7], v[222:225], v[214:217], v[4:7]
	v_mfma_f32_16x16x32_bf16 v[0:3], v[230:233], v[214:217], v[0:3]
	s_setprio 0
	s_add_i32 s56, s56, 2
	s_add_u32 s22, s22, 0x100
	s_addc_u32 s23, s23, 0
	s_add_u32 s54, s54, 0x100
	s_addc_u32 s55, s55, 0
	s_cmp_gt_u32 s56, 13
	s_barrier
	s_cbranch_scc0 .LBB0_483
	s_waitcnt vmcnt(0)
	s_cmp_gt_i32 s34, 7
	s_cselect_b64 s[22:23], -1, 0
	s_cmp_lt_i32 s34, 8
	s_cselect_b64 s[36:37], -1, 0
	v_cndmask_b32_e64 v167, 0, 1, s[36:37]
	s_and_b64 s[36:37], s[36:37], exec
	s_cselect_b32 s37, s17, s95
	s_cselect_b32 s36, s16, s94
	s_ashr_i32 s3, s2, 31
	s_lshl_b32 s5, s34, 8
	s_lshl_b64 s[2:3], s[2:3], 19
	s_and_b32 s5, s5, 0x700
	s_or_b32 s2, s2, s5
	v_lshlrev_b64 v[160:161], v167, s[2:3]
	v_lshl_add_u64 v[160:161], s[36:37], 0, v[160:161]
	v_lshlrev_b64 v[162:163], v167, v[140:141]
	v_lshl_add_u64 v[162:163], v[160:161], 0, v[162:163]
	s_mov_b64 s[2:3], -1
	s_and_b64 vcc, exec, s[22:23]
	s_cbranch_vccz .LBB0_486
	v_mov_b32_e32 v168, 0
	v_mov_b32_e32 v169, 0
	v_cvt_pk_fp8_f32 v168, v124, v125
	v_cvt_pk_fp8_f32 v169, v120, v121
	s_mov_b64 s[2:3], 0
	v_cvt_pk_fp8_f32 v168, v126, v127 op_sel:[0,0,1]
	v_cvt_pk_fp8_f32 v169, v122, v123 op_sel:[0,0,1]
	global_store_dwordx2 v[162:163], v[168:169], off

; #define G_STAGE(bufoff, gbase, voff) do { _Pragma("unroll") for (int _i = 0; _i < 2; ++_i) \
;         __builtin_amdgcn_global_load_lds((const unsigned*)((const char*)(gbase) + (voff)[_i]), (LAS unsigned*)(lds + (bufoff) + ldsw + _i * 8192), 16, 0, 0); } while (0)
; #define G_WAIT_V(n) asm volatile("s_waitcnt vmcnt(" #n ")" ::: "memory")
; #define G_BAR __builtin_amdgcn_s_barrier()
; template <bool PERM, class Dec, class Epi>
; DI void gemm_phase(LAS unsigned char* lds, const int nM, const int nN, const int K, const int lda, const int ldb, const Dec& dec, const Epi& epi, const int vb, const int panel = -1) {
;     ...
;     for (int i = 0; i < 2; ++i) { int R, C; stage_rc(tid * 16 + i * 8192, R, C); const int Rb = PERM ? ((R & ~31) + perm32(R & 31)) : R;
;         voffA[i] = (unsigned)(R * lda + C) * 2u; voffB[i] = (unsigned)(Rb * ldb + C) * 2u; }
;     const size_t kstep = (size_t)(BK * 2);
;     const size_t hstepA = (size_t)HALF * lda * 2, hstepB = (size_t)HALF * ldb * 2;
;     const unsigned ldsw = (unsigned)wid * 1024u;
;     const int aoff = lds_byte(wr * 64 + fr, fq * 8), boff = lds_byte(wc * 32 + fr, fq * 8);
;     ...
;     int cpm, cpn, npm, npn, ui = 0;
;     if (panel >= 0) { cpm = panel; cpn = 0; } else if (!unit_next(0, nM, nN, vb, cpm, cpn)) return;
;     f32x4 acc[2][2][4][2];
; #pragma unroll
;     for (int a = 0; a < 2; ++a)
; #pragma unroll
;         for (int b = 0; b < 2; ++b)
; #pragma unroll
;             for (int m = 0; m < 4; ++m)
; #pragma unroll
;                 for (int n = 0; n < 2; ++n) acc[a][b][m][n] = (f32x4){0.f, 0.f, 0.f, 0.f};
;     bf16x8 At[4][2], B0[2][2], B1[2][2];
;     const char* cA; const char* cB; dec(cpm, cpn, cA, cB);
;     G_STAGE(G_SB(0, 0), cB, voffB); G_STAGE(G_SA(0, 0), cA, voffA); G_STAGE(G_SB(0, 1), cB + hstepB, voffB); G_STAGE(G_SA(0, 1), cA + hstepA, voffA);
;     if (wr == 1) G_BAR;
;     G_WAIT_V(4); G_BAR;
;     G_STAGE(G_SB(1, 0), cB + kstep, voffB); G_STAGE(G_SA(1, 0), cA + kstep, voffA); G_STAGE(G_SB(1, 1), cB + hstepB + kstep, voffB);
;     G_WAIT_V(6); G_BAR;
.LBB0_665:
	v_bfe_u32 v16, v6, 4, 2
	v_and_b32_e32 v7, 15, v6
	v_lshlrev_b32_e32 v17, 4, v16
	v_lshlrev_b32_e32 v6, 2, v6
	s_lshl_b32 s2, s2, 5
	v_lshl_or_b32 v146, s3, 6, v7
	v_lshl_or_b32 v7, v7, 6, v17
	s_lshl_b32 s3, s3, 13
	v_and_b32_e32 v6, 32, v6
	s_and_b32 s2, s2, 0x60
	v_lshl_add_u64 v[8:9], s[76:77], 0, v[128:129]
	v_mov_b32_e32 v135, v129
	v_bitop3_b32 v17, v7, s3, v6 bitop3:0xde
	s_lshl_b32 s3, s2, 7
	v_lshl_add_u64 v[10:11], s[76:77], 0, v[134:135]
	v_bitop3_b32 v147, v7, s3, v6 bitop3:0xde
	s_add_i32 m0, s54, 0x18000
	v_lshl_add_u64 v[6:7], v[8:9], 0, s[30:31]
	v_lshl_add_u64 v[12:13], s[82:83], 0, v[128:129]
	s_waitcnt vmcnt(4)
	s_barrier
	global_load_lds_dwordx4 v[6:7], off
	v_lshl_add_u64 v[6:7], v[10:11], 0, s[30:31]
	s_add_i32 m0, s54, 0x1a000
	s_add_i32 s62, s54, 0x8000
	v_lshl_add_u64 v[14:15], s[82:83], 0, v[134:135]
	global_load_lds_dwordx4 v[6:7], off
	v_lshl_add_u64 v[6:7], v[12:13], 0, s[30:31]
	s_mov_b32 m0, s62
	s_add_i32 s63, s54, 0xa000
	global_load_lds_dwordx4 v[6:7], off
	v_lshl_add_u64 v[6:7], v[14:15], 0, s[30:31]
	s_mov_b32 m0, s63
	v_lshl_or_b32 v136, v16, 2, s2
	global_load_lds_dwordx4 v[6:7], off
	s_add_i32 m0, s54, 0x1c000
	v_lshl_add_u64 v[6:7], s[28:29], 0, v[128:129]
	global_load_lds_dwordx4 v[6:7], off
	v_lshl_add_u64 v[6:7], s[28:29], 0, v[134:135]
	s_add_i32 m0, s54, 0x1e000
	s_mov_b32 s66, 0
	global_load_lds_dwordx4 v[6:7], off
	v_lshlrev_b32_e32 v6, 15, v3
	v_and_b32_e32 v6, 0xffff0000, v6
	v_lshl_add_u32 v4, v4, 12, v6
	v_and_b32_e32 v3, 1, v3
	v_lshl_or_b32 v3, v3, 6, v4
	v_lshl_add_u32 v138, v5, 1, v3
	v_lshlrev_b32_e32 v3, 15, v0
	v_and_b32_e32 v3, 0xffff0000, v3
	s_waitcnt vmcnt(0)
	v_lshl_add_u32 v1, v1, 12, v3
	v_and_b32_e32 v0, 1, v0
	v_lshl_or_b32 v0, v0, 6, v1
	v_cmp_eq_u32_e64 s[42:43], 0, v16
	v_mov_b32_e32 v139, v129
	v_lshl_add_u32 v140, v2, 1, v0
	v_mov_b32_e32 v141, v129
	v_add_u32_e32 v148, 0, v17
	s_mov_b32 s67, s90
	s_mov_b32 s70, s56
	s_mov_b64 s[2:3], s[82:83]
	s_mov_b64 s[50:51], s[76:77]
	s_barrier
	s_branch .LBB0_667

; #define G_STAGE(bufoff, gbase, voff) do { _Pragma("unroll") for (int _i = 0; _i < 2; ++_i) \
;         __builtin_amdgcn_global_load_lds((const unsigned*)((const char*)(gbase) + (voff)[_i]), (LAS unsigned*)(lds + (bufoff) + ldsw + _i * 8192), 16, 0, 0); } while (0)
; #define G_LDA(dst, b, h) do { _Pragma("unroll") for (int m = 0; m < 4; ++m) _Pragma("unroll") for (int k = 0; k < 2; ++k) dst[m][k] = *(const LAS bf16x8*)(lds + G_SA(b, h) + aoff + m * 2048 + k * 1024); } while (0)
; #define G_LDB(dst, b, h) do { _Pragma("unroll") for (int n = 0; n < 2; ++n) _Pragma("unroll") for (int k = 0; k < 2; ++k) dst[n][k] = *(const LAS bf16x8*)(lds + G_SB(b, h) + boff + n * 2048 + k * 1024); } while (0)
; #define G_WAIT_V(n) asm volatile("s_waitcnt vmcnt(" #n ")" ::: "memory")
; #define G_WAIT_L(n) asm volatile("s_waitcnt lgkmcnt(" #n ")" ::: "memory")
; #define G_BAR __builtin_amdgcn_s_barrier()
; #define G_SCHED __builtin_amdgcn_sched_barrier(0)
; template <bool PERM, class Dec, class Epi>
; DI void gemm_phase(LAS unsigned char* lds, const int nM, const int nN, const int K, const int lda, const int ldb, const Dec& dec, const Epi& epi, const int vb, const int panel = -1) {
;     ...
;         if (panel >= 0) { has_next = (ui + 1 < nN); npm = panel; npn = ui + 1; } else has_next = unit_next(ui + 1, nM, nN, vb, npm, npn);
;         const char* nA = cA; const char* nB = cB; if (has_next) dec(npm, npn, nA, nB);
; #pragma nounroll
;         for (int t = 0; t < nt; t += 2) {
;             const bool last = (t == nt - 2);
;             const char* a1 = cA + (size_t)(t + 1) * kstep;
;             const char* a2 = last ? nA : cA + (size_t)(t + 2) * kstep; const char* b2 = last ? nB : cB + (size_t)(t + 2) * kstep;
;             const char* a3 = a2 + kstep; const char* b3 = b2 + kstep;
;             G_LDB(B0, 0, 0); G_SCHED; G_LDA(At, 0, 0); G_STAGE(G_SA(1, 1), a1 + hstepA, voffA);
;             G_WAIT_L(8); G_BAR; G_WAIT_L(0); G_MMA(0, 0, At, B0); G_BAR; G_SCHED;
;             G_LDB(B1, 0, 1); G_STAGE(G_SB(0, 0), b2, voffB);
;             G_BAR; G_WAIT_L(0); G_MMA(0, 1, At, B1); G_BAR;
;             G_LDA(At, 0, 1); G_STAGE(G_SA(0, 0), a2, voffA);
;             G_BAR; G_WAIT_L(0); G_MMA(1, 0, At, B0); G_BAR; G_SCHED;
;             G_STAGE(G_SB(0, 1), b2 + hstepB, voffB);
;             G_WAIT_V(6); G_BAR; G_MMA(1, 1, At, B1); G_BAR;
.LBB0_670:
	s_add_u32 s50, s2, 0xfff80080
	s_addc_u32 s51, s3, -1
	s_add_i32 s64, 0, 0x10000
	v_add_u32_e32 v149, s64, v147
	ds_read_b128 v[142:145], v149
	ds_read_b128 v[150:153], v149 offset:1024
	ds_read_b128 v[154:157], v149 offset:2048
	ds_read_b128 v[158:161], v149 offset:3072
	s_cmp_eq_u32 s75, 28
	s_cselect_b32 s53, s35, s51
	s_cselect_b32 s52, s37, s50
	s_cselect_b32 s51, s71, s74
	s_cselect_b32 s50, s72, s73
	v_lshl_add_u64 v[198:199], s[2:3], 0, v[138:139]
	s_add_i32 m0, s54, 0xc000
	ds_read_b128 v[162:165], v148
	ds_read_b128 v[166:169], v148 offset:1024
	ds_read_b128 v[170:173], v148 offset:2048
	ds_read_b128 v[176:179], v148 offset:3072
	ds_read_b128 v[180:183], v148 offset:4096
	ds_read_b128 v[184:187], v148 offset:5120
	ds_read_b128 v[188:191], v148 offset:6144
	ds_read_b128 v[194:197], v148 offset:7168
	global_load_lds_dwordx4 v[198:199], off
	v_lshl_add_u64 v[198:199], s[2:3], 0, v[140:141]
	s_add_i32 m0, s54, 0xe000
	s_nop 0
	global_load_lds_dwordx4 v[198:199], off
	s_waitcnt lgkmcnt(8)
	s_barrier
	s_waitcnt lgkmcnt(0)
	s_setprio 1
	s_waitcnt lgkmcnt(0)
	v_mfma_f32_16x16x32_bf16 v[124:127], v[142:145], v[162:165], v[124:127]
	v_mfma_f32_16x16x32_bf16 v[120:123], v[154:157], v[162:165], v[120:123]
	v_mfma_f32_16x16x32_bf16 v[108:111], v[142:145], v[170:173], v[108:111]
	v_mfma_f32_16x16x32_bf16 v[104:107], v[154:157], v[170:173], v[104:107]
	v_mfma_f32_16x16x32_bf16 v[92:95], v[142:145], v[180:183], v[92:95]
	v_mfma_f32_16x16x32_bf16 v[88:91], v[154:157], v[180:183], v[88:91]
	v_mfma_f32_16x16x32_bf16 v[76:79], v[142:145], v[188:191], v[76:79]
	v_mfma_f32_16x16x32_bf16 v[72:75], v[154:157], v[188:191], v[72:75]
	v_mfma_f32_16x16x32_bf16 v[124:127], v[150:153], v[166:169], v[124:127]
	v_mfma_f32_16x16x32_bf16 v[120:123], v[158:161], v[166:169], v[120:123]
	v_mfma_f32_16x16x32_bf16 v[108:111], v[150:153], v[176:179], v[108:111]
	v_mfma_f32_16x16x32_bf16 v[104:107], v[158:161], v[176:179], v[104:107]
	v_mfma_f32_16x16x32_bf16 v[92:95], v[150:153], v[184:187], v[92:95]
	v_mfma_f32_16x16x32_bf16 v[88:91], v[158:161], v[184:187], v[88:91]
	v_mfma_f32_16x16x32_bf16 v[76:79], v[150:153], v[194:197], v[76:79]
	v_mfma_f32_16x16x32_bf16 v[72:75], v[158:161], v[194:197], v[72:75]
	s_setprio 0
	s_barrier
	s_add_i32 s68, 0, 0x14000
	s_add_i32 s64, s64, s39
	v_add_u32_e32 v149, s68, v147
	v_lshl_add_u64 v[214:215], s[50:51], 0, v[128:129]
	s_mov_b32 m0, s64
	ds_read_b128 v[198:201], v149
	ds_read_b128 v[202:205], v149 offset:1024
	ds_read_b128 v[206:209], v149 offset:2048
	ds_read_b128 v[210:213], v149 offset:3072
	global_load_lds_dwordx4 v[214:215], off
	v_lshl_add_u64 v[216:217], s[50:51], 0, v[134:135]
	s_add_i32 m0, s64, 0x2000
	s_nop 0
	global_load_lds_dwordx4 v[216:217], off
	s_barrier
	s_waitcnt lgkmcnt(0)
	s_setprio 1
	s_waitcnt lgkmcnt(0)
	v_mfma_f32_16x16x32_bf16 v[116:119], v[198:201], v[162:165], v[116:119]
	v_mfma_f32_16x16x32_bf16 v[112:115], v[206:209], v[162:165], v[112:115]
	v_mfma_f32_16x16x32_bf16 v[100:103], v[198:201], v[170:173], v[100:103]
	v_mfma_f32_16x16x32_bf16 v[96:99], v[206:209], v[170:173], v[96:99]
	v_mfma_f32_16x16x32_bf16 v[84:87], v[198:201], v[180:183], v[84:87]
	v_mfma_f32_16x16x32_bf16 v[80:83], v[206:209], v[180:183], v[80:83]
	v_mfma_f32_16x16x32_bf16 v[68:71], v[198:201], v[188:191], v[68:71]
	v_mfma_f32_16x16x32_bf16 v[64:67], v[206:209], v[188:191], v[64:67]
	v_mfma_f32_16x16x32_bf16 v[116:119], v[202:205], v[166:169], v[116:119]
	v_mfma_f32_16x16x32_bf16 v[112:115], v[210:213], v[166:169], v[112:115]
	v_mfma_f32_16x16x32_bf16 v[100:103], v[202:205], v[176:179], v[100:103]
	v_mfma_f32_16x16x32_bf16 v[96:99], v[210:213], v[176:179], v[96:99]
	v_mfma_f32_16x16x32_bf16 v[84:87], v[202:205], v[184:187], v[84:87]
	v_mfma_f32_16x16x32_bf16 v[80:83], v[210:213], v[184:187], v[80:83]
	v_mfma_f32_16x16x32_bf16 v[68:71], v[202:205], v[194:197], v[68:71]
	v_mfma_f32_16x16x32_bf16 v[64:67], v[210:213], v[194:197], v[64:67]
	s_setprio 0
	s_mov_b32 m0, s54
	v_lshl_add_u64 v[218:219], s[52:53], 0, v[128:129]
	s_barrier
	ds_read_b128 v[162:165], v148 offset:16384
	ds_read_b128 v[166:169], v148 offset:17408
	ds_read_b128 v[170:173], v148 offset:18432
	ds_read_b128 v[176:179], v148 offset:19456
	ds_read_b128 v[180:183], v148 offset:20480
	ds_read_b128 v[184:187], v148 offset:21504
	ds_read_b128 v[188:191], v148 offset:22528
	ds_read_b128 v[194:197], v148 offset:23552
	global_load_lds_dwordx4 v[218:219], off
	v_lshl_add_u64 v[220:221], s[52:53], 0, v[134:135]
	s_mov_b32 m0, s55
	s_nop 0
	global_load_lds_dwordx4 v[220:221], off
	s_barrier
	s_waitcnt lgkmcnt(0)
	s_setprio 1
	s_waitcnt lgkmcnt(0)
	v_mfma_f32_16x16x32_bf16 v[60:63], v[142:145], v[162:165], v[60:63]
	v_mfma_f32_16x16x32_bf16 v[56:59], v[154:157], v[162:165], v[56:59]
	v_mfma_f32_16x16x32_bf16 v[44:47], v[142:145], v[170:173], v[44:47]
	v_mfma_f32_16x16x32_bf16 v[40:43], v[154:157], v[170:173], v[40:43]
	v_mfma_f32_16x16x32_bf16 v[28:31], v[142:145], v[180:183], v[28:31]
	v_mfma_f32_16x16x32_bf16 v[24:27], v[154:157], v[180:183], v[24:27]
	v_mfma_f32_16x16x32_bf16 v[12:15], v[142:145], v[188:191], v[12:15]
	v_mfma_f32_16x16x32_bf16 v[8:11], v[154:157], v[188:191], v[8:11]
	v_mfma_f32_16x16x32_bf16 v[60:63], v[150:153], v[166:169], v[60:63]
	v_mfma_f32_16x16x32_bf16 v[56:59], v[158:161], v[166:169], v[56:59]
	v_mfma_f32_16x16x32_bf16 v[44:47], v[150:153], v[176:179], v[44:47]
	v_mfma_f32_16x16x32_bf16 v[40:43], v[158:161], v[176:179], v[40:43]
	v_mfma_f32_16x16x32_bf16 v[28:31], v[150:153], v[184:187], v[28:31]
	v_mfma_f32_16x16x32_bf16 v[24:27], v[158:161], v[184:187], v[24:27]
	v_mfma_f32_16x16x32_bf16 v[12:15], v[150:153], v[194:197], v[12:15]
	v_mfma_f32_16x16x32_bf16 v[8:11], v[158:161], v[194:197], v[8:11]
	s_setprio 0
	s_barrier
	s_add_u32 s64, s50, 0x80000
	s_addc_u32 s65, s51, 0
	s_add_i32 s68, s68, s39
	v_lshl_add_u64 v[142:143], s[64:65], 0, v[128:129]
	s_mov_b32 m0, s68
	s_nop 0
	global_load_lds_dwordx4 v[142:143], off
	v_lshl_add_u64 v[142:143], s[64:65], 0, v[134:135]
	s_add_i32 m0, s68, 0x2000
	s_nop 0
	global_load_lds_dwordx4 v[142:143], off
	s_cmp_eq_u32 s75, -2
	s_cbranch_scc1 .Lfi4_670
	s_waitcnt vmcnt(6)
; #define G_STAGE(bufoff, gbase, voff) do { _Pragma("unroll") for (int _i = 0; _i < 2; ++_i) \
;         __builtin_amdgcn_global_load_lds((const unsigned*)((const char*)(gbase) + (voff)[_i]), (LAS unsigned*)(lds + (bufoff) + ldsw + _i * 8192), 16, 0, 0); } while (0)
; #define G_LDA(dst, b, h) do { _Pragma("unroll") for (int m = 0; m < 4; ++m) _Pragma("unroll") for (int k = 0; k < 2; ++k) dst[m][k] = *(const LAS bf16x8*)(lds + G_SA(b, h) + aoff + m * 2048 + k * 1024); } while (0)
; #define G_LDB(dst, b, h) do { _Pragma("unroll") for (int n = 0; n < 2; ++n) _Pragma("unroll") for (int k = 0; k < 2; ++k) dst[n][k] = *(const LAS bf16x8*)(lds + G_SB(b, h) + boff + n * 2048 + k * 1024); } while (0)
; #define G_MMA(ai, bj, At, Bt) do { __builtin_amdgcn_s_setprio(1); _Pragma("unroll") for (int m = 0; m < 4; ++m) _Pragma("unroll") for (int n = 0; n < 2; ++n) _Pragma("unroll") for (int k = 0; k < 2; ++k) \
;         acc[ai][bj][m][n] = __builtin_amdgcn_mfma_f32_16x16x32_bf16(Bt[n][k], At[m][k], acc[ai][bj][m][n], 0, 0, 0); __builtin_amdgcn_s_setprio(0); } while (0)
; #define G_WAIT_V(n) asm volatile("s_waitcnt vmcnt(" #n ")" ::: "memory")
; #define G_WAIT_L(n) asm volatile("s_waitcnt lgkmcnt(" #n ")" ::: "memory")
; #define G_BAR __builtin_amdgcn_s_barrier()
; #define G_SCHED __builtin_amdgcn_sched_barrier(0)
; template <bool PERM, class Dec, class Epi>
; DI void gemm_phase(LAS unsigned char* lds, const int nM, const int nN, const int K, const int lda, const int ldb, const Dec& dec, const Epi& epi, const int vb, const int panel = -1) {
;     ...
;             G_WAIT_V(6); G_BAR; G_MMA(1, 1, At, B1); G_BAR;
;             G_LDB(B0, 1, 0); G_SCHED; G_LDA(At, 1, 0); G_STAGE(G_SA(0, 1), a2 + hstepA, voffA);
;             G_WAIT_L(8); G_BAR; G_WAIT_L(0); G_MMA(0, 0, At, B0); G_BAR; G_SCHED;
;             G_LDB(B1, 1, 1); G_STAGE(G_SB(1, 0), b3, voffB);
;             G_BAR; G_WAIT_L(0); G_MMA(0, 1, At, B1); G_BAR;
;             G_LDA(At, 1, 1); G_STAGE(G_SA(1, 0), a3, voffA);
;             G_BAR; G_WAIT_L(0); G_MMA(1, 0, At, B0); G_BAR; G_SCHED;
.Lfi4_670:
	s_barrier
	s_setprio 1
	v_mfma_f32_16x16x32_bf16 v[52:55], v[198:201], v[162:165], v[52:55]
	v_mfma_f32_16x16x32_bf16 v[48:51], v[206:209], v[162:165], v[48:51]
	v_mfma_f32_16x16x32_bf16 v[36:39], v[198:201], v[170:173], v[36:39]
	v_mfma_f32_16x16x32_bf16 v[32:35], v[206:209], v[170:173], v[32:35]
	v_mfma_f32_16x16x32_bf16 v[20:23], v[198:201], v[180:183], v[20:23]
	v_mfma_f32_16x16x32_bf16 v[16:19], v[206:209], v[180:183], v[16:19]
	v_mfma_f32_16x16x32_bf16 v[4:7], v[198:201], v[188:191], v[4:7]
	v_mfma_f32_16x16x32_bf16 v[0:3], v[206:209], v[188:191], v[0:3]
	v_mfma_f32_16x16x32_bf16 v[52:55], v[202:205], v[166:169], v[52:55]
	v_mfma_f32_16x16x32_bf16 v[48:51], v[210:213], v[166:169], v[48:51]
	v_mfma_f32_16x16x32_bf16 v[36:39], v[202:205], v[176:179], v[36:39]
	v_mfma_f32_16x16x32_bf16 v[32:35], v[210:213], v[176:179], v[32:35]
	v_mfma_f32_16x16x32_bf16 v[20:23], v[202:205], v[184:187], v[20:23]
	v_mfma_f32_16x16x32_bf16 v[16:19], v[210:213], v[184:187], v[16:19]
	v_mfma_f32_16x16x32_bf16 v[4:7], v[202:205], v[194:197], v[4:7]
	v_mfma_f32_16x16x32_bf16 v[0:3], v[210:213], v[194:197], v[0:3]
	s_setprio 0
	s_add_i32 s64, 0, 0x18000
	v_add_u32_e32 v149, s64, v147
	s_barrier
	ds_read_b128 v[142:145], v149
	ds_read_b128 v[150:153], v149 offset:1024
	ds_read_b128 v[154:157], v149 offset:2048
	ds_read_b128 v[158:161], v149 offset:3072
	s_add_u32 s52, s52, 0x80000
	s_addc_u32 s53, s53, 0
	s_mov_b32 m0, s58
	v_lshl_add_u64 v[198:199], s[52:53], 0, v[128:129]
	ds_read_b128 v[162:165], v148 offset:32768
	ds_read_b128 v[166:169], v148 offset:33792
	ds_read_b128 v[170:173], v148 offset:34816
	ds_read_b128 v[176:179], v148 offset:35840
	ds_read_b128 v[180:183], v148 offset:36864
	ds_read_b128 v[184:187], v148 offset:37888
	ds_read_b128 v[188:191], v148 offset:38912
	ds_read_b128 v[194:197], v148 offset:39936
	global_load_lds_dwordx4 v[198:199], off
	v_lshl_add_u64 v[198:199], s[52:53], 0, v[134:135]
	s_mov_b32 m0, s59
	s_nop 0
	global_load_lds_dwordx4 v[198:199], off
	s_waitcnt lgkmcnt(8)
	s_barrier
	s_waitcnt lgkmcnt(0)
	s_setprio 1
	s_waitcnt lgkmcnt(0)
	v_mfma_f32_16x16x32_bf16 v[124:127], v[142:145], v[162:165], v[124:127]
	v_mfma_f32_16x16x32_bf16 v[120:123], v[154:157], v[162:165], v[120:123]
	v_mfma_f32_16x16x32_bf16 v[108:111], v[142:145], v[170:173], v[108:111]
	v_mfma_f32_16x16x32_bf16 v[104:107], v[154:157], v[170:173], v[104:107]
	v_mfma_f32_16x16x32_bf16 v[92:95], v[142:145], v[180:183], v[92:95]
	v_mfma_f32_16x16x32_bf16 v[88:91], v[154:157], v[180:183], v[88:91]
	v_mfma_f32_16x16x32_bf16 v[76:79], v[142:145], v[188:191], v[76:79]
	v_mfma_f32_16x16x32_bf16 v[72:75], v[154:157], v[188:191], v[72:75]
	v_mfma_f32_16x16x32_bf16 v[124:127], v[150:153], v[166:169], v[124:127]
	v_mfma_f32_16x16x32_bf16 v[120:123], v[158:161], v[166:169], v[120:123]
	v_mfma_f32_16x16x32_bf16 v[108:111], v[150:153], v[176:179], v[108:111]
	v_mfma_f32_16x16x32_bf16 v[104:107], v[158:161], v[176:179], v[104:107]
	v_mfma_f32_16x16x32_bf16 v[92:95], v[150:153], v[184:187], v[92:95]
	v_mfma_f32_16x16x32_bf16 v[88:91], v[158:161], v[184:187], v[88:91]
	v_mfma_f32_16x16x32_bf16 v[76:79], v[150:153], v[194:197], v[76:79]
	v_mfma_f32_16x16x32_bf16 v[72:75], v[158:161], v[194:197], v[72:75]
	s_setprio 0
	s_barrier
	s_add_i32 s52, 0, 0x1c000
	s_add_i32 s53, s64, s39
	v_add_u32_e32 v149, s52, v147
	v_lshl_add_u64 v[214:215], v[214:215], 0, s[30:31]
	s_mov_b32 m0, s53
	ds_read_b128 v[198:201], v149
	ds_read_b128 v[202:205], v149 offset:1024
	ds_read_b128 v[206:209], v149 offset:2048
	ds_read_b128 v[210:213], v149 offset:3072
	global_load_lds_dwordx4 v[214:215], off
	v_lshl_add_u64 v[214:215], v[216:217], 0, s[30:31]
	s_add_i32 m0, s53, 0x2000
	s_nop 0
	global_load_lds_dwordx4 v[214:215], off
	s_cmp_lg_u32 s75, -2
	s_cbranch_scc1 .Lfi6_670
	s_waitcnt vmcnt(10)
.Lfi6_670:
	s_barrier
	s_waitcnt lgkmcnt(0)
	s_setprio 1
	s_waitcnt lgkmcnt(0)
	v_mfma_f32_16x16x32_bf16 v[116:119], v[198:201], v[162:165], v[116:119]
	v_mfma_f32_16x16x32_bf16 v[112:115], v[206:209], v[162:165], v[112:115]
	v_mfma_f32_16x16x32_bf16 v[100:103], v[198:201], v[170:173], v[100:103]
	v_mfma_f32_16x16x32_bf16 v[96:99], v[206:209], v[170:173], v[96:99]
	v_mfma_f32_16x16x32_bf16 v[84:87], v[198:201], v[180:183], v[84:87]
	v_mfma_f32_16x16x32_bf16 v[80:83], v[206:209], v[180:183], v[80:83]
	v_mfma_f32_16x16x32_bf16 v[68:71], v[198:201], v[188:191], v[68:71]
	v_mfma_f32_16x16x32_bf16 v[64:67], v[206:209], v[188:191], v[64:67]
	v_mfma_f32_16x16x32_bf16 v[116:119], v[202:205], v[166:169], v[116:119]
	v_mfma_f32_16x16x32_bf16 v[112:115], v[210:213], v[166:169], v[112:115]
	v_mfma_f32_16x16x32_bf16 v[100:103], v[202:205], v[176:179], v[100:103]
	v_mfma_f32_16x16x32_bf16 v[96:99], v[210:213], v[176:179], v[96:99]
	v_mfma_f32_16x16x32_bf16 v[84:87], v[202:205], v[184:187], v[84:87]
	v_mfma_f32_16x16x32_bf16 v[80:83], v[210:213], v[184:187], v[80:83]
	v_mfma_f32_16x16x32_bf16 v[68:71], v[202:205], v[194:197], v[68:71]
	v_mfma_f32_16x16x32_bf16 v[64:67], v[210:213], v[194:197], v[64:67]
	s_setprio 0
	s_mov_b32 m0, s62
	v_lshl_add_u64 v[214:215], v[218:219], 0, s[30:31]
	s_barrier
	ds_read_b128 v[162:165], v148 offset:49152
	ds_read_b128 v[166:169], v148 offset:50176
	ds_read_b128 v[170:173], v148 offset:51200
	ds_read_b128 v[176:179], v148 offset:52224
	ds_read_b128 v[180:183], v148 offset:53248
	ds_read_b128 v[184:187], v148 offset:54272
	ds_read_b128 v[188:191], v148 offset:55296
	ds_read_b128 v[194:197], v148 offset:56320
	global_load_lds_dwordx4 v[214:215], off
	v_lshl_add_u64 v[214:215], v[220:221], 0, s[30:31]
	s_mov_b32 m0, s63
	s_nop 0
	global_load_lds_dwordx4 v[214:215], off
	s_barrier
; #define G_STAGE(bufoff, gbase, voff) do { _Pragma("unroll") for (int _i = 0; _i < 2; ++_i) \
;         __builtin_amdgcn_global_load_lds((const unsigned*)((const char*)(gbase) + (voff)[_i]), (LAS unsigned*)(lds + (bufoff) + ldsw + _i * 8192), 16, 0, 0); } while (0)
; #define G_LDA(dst, b, h) do { _Pragma("unroll") for (int m = 0; m < 4; ++m) _Pragma("unroll") for (int k = 0; k < 2; ++k) dst[m][k] = *(const LAS bf16x8*)(lds + G_SA(b, h) + aoff + m * 2048 + k * 1024); } while (0)
; #define G_MMA(ai, bj, At, Bt) do { __builtin_amdgcn_s_setprio(1); _Pragma("unroll") for (int m = 0; m < 4; ++m) _Pragma("unroll") for (int n = 0; n < 2; ++n) _Pragma("unroll") for (int k = 0; k < 2; ++k) \
;         acc[ai][bj][m][n] = __builtin_amdgcn_mfma_f32_16x16x32_bf16(Bt[n][k], At[m][k], acc[ai][bj][m][n], 0, 0, 0); __builtin_amdgcn_s_setprio(0); } while (0)
; #define G_WAIT_V(n) asm volatile("s_waitcnt vmcnt(" #n ")" ::: "memory")
; #define G_WAIT_L(n) asm volatile("s_waitcnt lgkmcnt(" #n ")" ::: "memory")
; #define G_BAR __builtin_amdgcn_s_barrier()
; #define G_SCHED __builtin_amdgcn_sched_barrier(0)
; template <bool PERM, class Dec, class Epi>
; DI void gemm_phase(LAS unsigned char* lds, const int nM, const int nN, const int K, const int lda, const int ldb, const Dec& dec, const Epi& epi, const int vb, const int panel = -1) {
;     ...
;             G_LDA(At, 1, 1); G_STAGE(G_SA(1, 0), a3, voffA);
;             G_BAR; G_WAIT_L(0); G_MMA(1, 0, At, B0); G_BAR; G_SCHED;
;             G_STAGE(G_SB(1, 1), b3 + hstepB, voffB);
;             G_WAIT_V(6); G_BAR; G_MMA(1, 1, At, B1); G_BAR;
;         }
; __global__ void __launch_bounds__(512) hybrid_fwd(Params p) {
;     ...
;                   for (int m = 0; m < 4; ++m) { const int row = pm * 256 + ai * 128 + wr * 64 + m * 16 + fr; const size_t ro = (size_t)row * 1024 + pn * 256 + wc * 32 + 4 * fq;
;                       float ssq = 0.f;
; #pragma unroll
;                       for (int bj = 0; bj < 2; ++bj)
; #pragma unroll
;                           for (int n = 0; n < 2; ++n) { const size_t o = ro + bj * 128 + n * 16; const f32x4 v = *(const f32x4*)(X + o) + acc[ai][bj][m][n];
	s_waitcnt lgkmcnt(0)
	s_setprio 1
	s_waitcnt lgkmcnt(0)
	v_mfma_f32_16x16x32_bf16 v[60:63], v[142:145], v[162:165], v[60:63]
	v_mfma_f32_16x16x32_bf16 v[56:59], v[154:157], v[162:165], v[56:59]
	v_mfma_f32_16x16x32_bf16 v[44:47], v[142:145], v[170:173], v[44:47]
	v_mfma_f32_16x16x32_bf16 v[40:43], v[154:157], v[170:173], v[40:43]
	v_mfma_f32_16x16x32_bf16 v[28:31], v[142:145], v[180:183], v[28:31]
	v_mfma_f32_16x16x32_bf16 v[24:27], v[154:157], v[180:183], v[24:27]
	v_mfma_f32_16x16x32_bf16 v[12:15], v[142:145], v[188:191], v[12:15]
	v_mfma_f32_16x16x32_bf16 v[8:11], v[154:157], v[188:191], v[8:11]
	v_mfma_f32_16x16x32_bf16 v[60:63], v[150:153], v[166:169], v[60:63]
	v_mfma_f32_16x16x32_bf16 v[56:59], v[158:161], v[166:169], v[56:59]
	v_mfma_f32_16x16x32_bf16 v[44:47], v[150:153], v[176:179], v[44:47]
	v_mfma_f32_16x16x32_bf16 v[40:43], v[158:161], v[176:179], v[40:43]
	v_mfma_f32_16x16x32_bf16 v[28:31], v[150:153], v[184:187], v[28:31]
	v_mfma_f32_16x16x32_bf16 v[24:27], v[158:161], v[184:187], v[24:27]
	v_mfma_f32_16x16x32_bf16 v[12:15], v[150:153], v[194:197], v[12:15]
	v_mfma_f32_16x16x32_bf16 v[8:11], v[158:161], v[194:197], v[8:11]
	s_setprio 0
	s_barrier
	s_add_u32 s50, s50, 0x80080
	s_addc_u32 s51, s51, 0
	s_add_i32 s52, s52, s39
	v_lshl_add_u64 v[142:143], s[50:51], 0, v[128:129]
	s_mov_b32 m0, s52
	s_nop 0
	global_load_lds_dwordx4 v[142:143], off
	v_lshl_add_u64 v[142:143], s[50:51], 0, v[134:135]
	s_add_i32 m0, s52, 0x2000
	s_nop 0
	global_load_lds_dwordx4 v[142:143], off
	s_waitcnt vmcnt(6)
	s_barrier
	s_setprio 1
	v_mfma_f32_16x16x32_bf16 v[52:55], v[198:201], v[162:165], v[52:55]
	v_mfma_f32_16x16x32_bf16 v[48:51], v[206:209], v[162:165], v[48:51]
	v_mfma_f32_16x16x32_bf16 v[36:39], v[198:201], v[170:173], v[36:39]
	v_mfma_f32_16x16x32_bf16 v[32:35], v[206:209], v[170:173], v[32:35]
	v_mfma_f32_16x16x32_bf16 v[20:23], v[198:201], v[180:183], v[20:23]
	v_mfma_f32_16x16x32_bf16 v[16:19], v[206:209], v[180:183], v[16:19]
	v_mfma_f32_16x16x32_bf16 v[4:7], v[198:201], v[188:191], v[4:7]
	v_mfma_f32_16x16x32_bf16 v[0:3], v[206:209], v[188:191], v[0:3]
	v_mfma_f32_16x16x32_bf16 v[52:55], v[202:205], v[166:169], v[52:55]
	v_mfma_f32_16x16x32_bf16 v[48:51], v[210:213], v[166:169], v[48:51]
	v_mfma_f32_16x16x32_bf16 v[36:39], v[202:205], v[176:179], v[36:39]
	v_mfma_f32_16x16x32_bf16 v[32:35], v[210:213], v[176:179], v[32:35]
	v_mfma_f32_16x16x32_bf16 v[20:23], v[202:205], v[184:187], v[20:23]
	v_mfma_f32_16x16x32_bf16 v[16:19], v[210:213], v[184:187], v[16:19]
	v_mfma_f32_16x16x32_bf16 v[4:7], v[202:205], v[194:197], v[4:7]
	v_mfma_f32_16x16x32_bf16 v[0:3], v[210:213], v[194:197], v[0:3]
	s_setprio 0
	s_add_i32 s75, s75, 2
	s_add_u32 s2, s2, 0x100
	s_addc_u32 s3, s3, 0
	s_add_u32 s73, s73, 0x100
	s_addc_u32 s74, s74, 0
	s_cmp_gt_u32 s75, 29
	s_barrier
	s_cbranch_scc0 .LBB0_670
	v_and_b32_e32 v149, 64, v174
	v_xor_b32_e32 v145, 16, v174
	v_add_u32_e32 v149, 64, v149
	v_cmp_lt_i32_e32 vcc, v145, v149
	v_lshl_add_u32 v144, s67, 8, v146
	s_lshl_b32 s2, s70, 8
	v_cndmask_b32_e32 v145, v174, v145, vcc
	v_lshlrev_b32_e32 v150, 2, v145
	v_xor_b32_e32 v145, 32, v174
	v_cmp_lt_i32_e32 vcc, v145, v149
	s_ashr_i32 s3, s2, 31
	v_mov_b32_e32 v143, s3
	v_cndmask_b32_e32 v145, v174, v145, vcc
	v_lshlrev_b32_e32 v149, 2, v145
	v_ashrrev_i32_e32 v145, 31, v144
	v_or_b32_e32 v142, s2, v136
	v_lshlrev_b64 v[152:153], 10, v[144:145]
	v_readlane_b32 s0, v246, 53
	v_lshl_add_u64 v[156:157], v[152:153], 0, v[142:143]
	v_readlane_b32 s1, v246, 54
	v_readlane_b32 s2, v246, 55
	v_readlane_b32 s3, v246, 56
	v_lshl_add_u64 v[158:159], v[156:157], 2, s[0:1]
	global_load_dwordx4 v[160:163], v[158:159], off
	global_load_dwordx4 v[164:167], v[158:159], off offset:64
	global_load_dwordx4 v[168:171], v[158:159], off offset:512
	global_load_dwordx4 v[176:179], v[158:159], off offset:576
	v_add_co_u32_e32 v214, vcc, 0x10000, v158
	s_nop 1
	v_addc_co_u32_e32 v215, vcc, 0, v159, vcc
	global_load_dwordx4 v[180:183], v[214:215], off
	global_load_dwordx4 v[184:187], v[214:215], off offset:64
	global_load_dwordx4 v[188:191], v[214:215], off offset:512
	global_load_dwordx4 v[194:197], v[214:215], off offset:576
	v_add_co_u32_e32 v214, vcc, 0x20000, v158
	s_nop 1
	v_addc_co_u32_e32 v215, vcc, 0, v159, vcc
	global_load_dwordx4 v[198:201], v[214:215], off
	global_load_dwordx4 v[202:205], v[214:215], off offset:64
	global_load_dwordx4 v[206:209], v[214:215], off offset:512
	global_load_dwordx4 v[210:213], v[214:215], off offset:576
	s_waitcnt vmcnt(8)
	v_pk_add_f32 v[124:125], v[124:125], v[160:161]
	v_pk_add_f32 v[126:127], v[126:127], v[162:163]
	v_pk_add_f32 v[120:121], v[120:121], v[164:165]
	v_pk_add_f32 v[122:123], v[122:123], v[166:167]
	v_pk_add_f32 v[116:117], v[116:117], v[168:169]
	v_pk_add_f32 v[118:119], v[118:119], v[170:171]
	v_pk_add_f32 v[112:113], v[112:113], v[176:177]
	v_pk_add_f32 v[114:115], v[114:115], v[178:179]
	v_add_co_u32_e32 v214, vcc, 0x30000, v158
	s_nop 1
	v_addc_co_u32_e32 v215, vcc, 0, v159, vcc
	global_load_dwordx4 v[160:163], v[214:215], off
	global_load_dwordx4 v[164:167], v[214:215], off offset:64
	global_load_dwordx4 v[168:171], v[214:215], off offset:512
	global_load_dwordx4 v[176:179], v[214:215], off offset:576
	s_waitcnt vmcnt(8)
	v_pk_add_f32 v[108:109], v[108:109], v[180:181]
	v_pk_add_f32 v[110:111], v[110:111], v[182:183]
	v_pk_add_f32 v[104:105], v[104:105], v[184:185]
	v_pk_add_f32 v[106:107], v[106:107], v[186:187]
	v_pk_add_f32 v[100:101], v[100:101], v[188:189]
	v_pk_add_f32 v[102:103], v[102:103], v[190:191]
	v_pk_add_f32 v[96:97], v[96:97], v[194:195]
	v_pk_add_f32 v[98:99], v[98:99], v[196:197]
	v_add_co_u32_e32 v214, vcc, 0x80000, v158
	s_nop 1
	v_addc_co_u32_e32 v215, vcc, 0, v159, vcc
	global_load_dwordx4 v[180:183], v[214:215], off
	global_load_dwordx4 v[184:187], v[214:215], off offset:64
	global_load_dwordx4 v[188:191], v[214:215], off offset:512
	global_load_dwordx4 v[194:197], v[214:215], off offset:576
	s_waitcnt vmcnt(8)
; DI unsigned pk2(float a, float b) { f32x2 v = {a, b}; bf2_t r = __builtin_convertvector(v, bf2_t); return __builtin_bit_cast(unsigned, r); }
; __global__ void __launch_bounds__(512) hybrid_fwd(Params p) {
;     ...
;                           for (int n = 0; n < 2; ++n) { const size_t o = ro + bj * 128 + n * 16; const f32x4 v = *(const f32x4*)(X + o) + acc[ai][bj][m][n];
;                               u32x2 wv; wv[0] = pk2(v[0], v[1]); wv[1] = pk2(v[2], v[3]); *(u32x2*)(U + o) = wv;
;                               ssq += v[0] * v[0] + v[1] * v[1] + v[2] * v[2] + v[3] * v[3]; }
;                       ssq += __shfl_xor(ssq, 16); ssq += __shfl_xor(ssq, 32);
;                       if (fq == 0) unsafeAtomicAdd(SS1 + row, ssq); } }, vb); }
	v_pk_add_f32 v[92:93], v[92:93], v[198:199]
	v_pk_add_f32 v[94:95], v[94:95], v[200:201]
	v_pk_add_f32 v[88:89], v[88:89], v[202:203]
	v_pk_add_f32 v[90:91], v[90:91], v[204:205]
	v_pk_add_f32 v[84:85], v[84:85], v[206:207]
	v_pk_add_f32 v[86:87], v[86:87], v[208:209]
	v_pk_add_f32 v[80:81], v[80:81], v[210:211]
	v_pk_add_f32 v[82:83], v[82:83], v[212:213]
	v_add_co_u32_e32 v214, vcc, 0x90000, v158
	s_nop 1
	v_addc_co_u32_e32 v215, vcc, 0, v159, vcc
	global_load_dwordx4 v[198:201], v[214:215], off
	global_load_dwordx4 v[202:205], v[214:215], off offset:64
	global_load_dwordx4 v[206:209], v[214:215], off offset:512
	global_load_dwordx4 v[210:213], v[214:215], off offset:576
	s_waitcnt vmcnt(8)
	v_pk_add_f32 v[76:77], v[76:77], v[160:161]
	v_pk_add_f32 v[78:79], v[78:79], v[162:163]
	v_pk_add_f32 v[72:73], v[72:73], v[164:165]
	v_pk_add_f32 v[74:75], v[74:75], v[166:167]
	v_pk_add_f32 v[68:69], v[68:69], v[168:169]
	v_pk_add_f32 v[70:71], v[70:71], v[170:171]
	v_pk_add_f32 v[64:65], v[64:65], v[176:177]
	v_pk_add_f32 v[66:67], v[66:67], v[178:179]
	v_add_co_u32_e32 v214, vcc, 0xa0000, v158
	s_nop 1
	v_addc_co_u32_e32 v215, vcc, 0, v159, vcc
	global_load_dwordx4 v[160:163], v[214:215], off
	global_load_dwordx4 v[164:167], v[214:215], off offset:64
	global_load_dwordx4 v[168:171], v[214:215], off offset:512
	global_load_dwordx4 v[176:179], v[214:215], off offset:576
	s_waitcnt vmcnt(8)
	v_pk_add_f32 v[60:61], v[60:61], v[180:181]
	v_pk_add_f32 v[62:63], v[62:63], v[182:183]
	v_pk_add_f32 v[56:57], v[56:57], v[184:185]
	v_pk_add_f32 v[58:59], v[58:59], v[186:187]
	v_pk_add_f32 v[52:53], v[52:53], v[188:189]
	v_pk_add_f32 v[54:55], v[54:55], v[190:191]
	v_pk_add_f32 v[48:49], v[48:49], v[194:195]
	v_pk_add_f32 v[50:51], v[50:51], v[196:197]
	v_add_co_u32_e32 v214, vcc, 0xb0000, v158
	s_nop 1
	v_addc_co_u32_e32 v215, vcc, 0, v159, vcc
	global_load_dwordx4 v[180:183], v[214:215], off
	global_load_dwordx4 v[184:187], v[214:215], off offset:64
	global_load_dwordx4 v[188:191], v[214:215], off offset:512
	global_load_dwordx4 v[194:197], v[214:215], off offset:576
	s_waitcnt vmcnt(8)
	v_pk_add_f32 v[44:45], v[44:45], v[198:199]
	v_pk_add_f32 v[46:47], v[46:47], v[200:201]
	v_pk_add_f32 v[40:41], v[40:41], v[202:203]
	v_pk_add_f32 v[42:43], v[42:43], v[204:205]
	v_pk_add_f32 v[36:37], v[36:37], v[206:207]
	v_pk_add_f32 v[38:39], v[38:39], v[208:209]
	v_pk_add_f32 v[32:33], v[32:33], v[210:211]
	v_pk_add_f32 v[34:35], v[34:35], v[212:213]
	s_waitcnt vmcnt(4)
	v_pk_add_f32 v[28:29], v[28:29], v[160:161]
	v_pk_add_f32 v[30:31], v[30:31], v[162:163]
	v_pk_add_f32 v[24:25], v[24:25], v[164:165]
	v_pk_add_f32 v[26:27], v[26:27], v[166:167]
	v_pk_add_f32 v[20:21], v[20:21], v[168:169]
	v_pk_add_f32 v[22:23], v[22:23], v[170:171]
	v_pk_add_f32 v[16:17], v[16:17], v[176:177]
	v_pk_add_f32 v[18:19], v[18:19], v[178:179]
	s_waitcnt vmcnt(0)
	v_pk_add_f32 v[12:13], v[12:13], v[180:181]
	v_pk_add_f32 v[14:15], v[14:15], v[182:183]
	v_pk_add_f32 v[8:9], v[8:9], v[184:185]
	v_pk_add_f32 v[10:11], v[10:11], v[186:187]
	v_pk_add_f32 v[4:5], v[4:5], v[188:189]
	v_pk_add_f32 v[6:7], v[6:7], v[190:191]
	v_pk_add_f32 v[0:1], v[0:1], v[194:195]
	v_pk_add_f32 v[2:3], v[2:3], v[196:197]
	v_readlane_b32 s4, v246, 57
	v_readlane_b32 s5, v246, 58
	v_readlane_b32 s6, v246, 59
	v_readlane_b32 s7, v246, 60
	v_readlane_b32 s8, v246, 61
	v_readlane_b32 s9, v246, 62
	v_readlane_b32 s10, v246, 63
	v_readlane_b32 s11, v245, 0
	v_readlane_b32 s12, v245, 1
	v_readlane_b32 s13, v245, 2
	v_readlane_b32 s14, v245, 3
	v_readlane_b32 s15, v245, 4
	v_lshlrev_b64 v[154:155], 1, v[156:157]
	v_mul_f32_e32 v151, v125, v125
	v_cvt_pk_bf16_f32 v152, v124, v125
	v_cvt_pk_bf16_f32 v153, v126, v127
	v_lshl_add_u64 v[156:157], s[20:21], 0, v[154:155]
	v_fmac_f32_e32 v151, v124, v124
	global_store_dwordx2 v[156:157], v[152:153], off
	v_fmac_f32_e32 v151, v126, v126
	v_fmac_f32_e32 v151, v127, v127
	s_nop 0
	v_cvt_pk_bf16_f32 v124, v120, v121
	v_mul_f32_e32 v121, v121, v121
	v_or_b32_e32 v126, 32, v154
	v_mov_b32_e32 v127, v155
	v_fmac_f32_e32 v121, v120, v120
	v_cvt_pk_bf16_f32 v125, v122, v123
	v_lshl_add_u64 v[126:127], s[20:21], 0, v[126:127]
	v_fmac_f32_e32 v121, v122, v122
	global_store_dwordx2 v[126:127], v[124:125], off
	v_fmac_f32_e32 v121, v123, v123
	v_add_f32_e32 v124, v151, v121
	s_nop 0
	v_cvt_pk_bf16_f32 v120, v116, v117
	v_mul_f32_e32 v117, v117, v117
	v_or_b32_e32 v122, 0x100, v154
	v_mov_b32_e32 v123, v155
	v_fmac_f32_e32 v117, v116, v116
	v_cvt_pk_bf16_f32 v121, v118, v119
	v_lshl_add_u64 v[122:123], s[20:21], 0, v[122:123]
	v_fmac_f32_e32 v117, v118, v118
	global_store_dwordx2 v[122:123], v[120:121], off
	v_fmac_f32_e32 v117, v119, v119
	v_add_f32_e32 v120, v124, v117
	v_or_b32_e32 v154, 0x120, v154
	s_nop 0
	v_cvt_pk_bf16_f32 v116, v112, v113
	v_mul_f32_e32 v113, v113, v113
	v_fmac_f32_e32 v113, v112, v112
	v_fmac_f32_e32 v113, v114, v114
	v_fmac_f32_e32 v113, v115, v115
	v_add_f32_e32 v112, v120, v113
	ds_bpermute_b32 v113, v150, v112
	v_cvt_pk_bf16_f32 v117, v114, v115
	v_lshl_add_u64 v[118:119], s[20:21], 0, v[154:155]
	global_store_dwordx2 v[118:119], v[116:117], off
	s_waitcnt lgkmcnt(0)
	v_add_f32_e32 v112, v112, v113
	ds_bpermute_b32 v113, v149, v112
	s_and_saveexec_b64 s[2:3], s[42:43]
	s_cbranch_execz .LBB0_673
	v_lshl_add_u64 v[114:115], v[144:145], 2, s[86:87]
	s_waitcnt lgkmcnt(0)
	v_add_f32_e32 v112, v112, v113
	global_atomic_add_f32 v[114:115], v112, off

; #define G_WAIT_V(n) asm volatile("s_waitcnt vmcnt(" #n ")" ::: "memory")
; #define G_BAR __builtin_amdgcn_s_barrier()
; template <bool PERM, class Dec, class Epi>
; DI void gemm_phase(LAS unsigned char* lds, const int nM, const int nN, const int K, const int lda, const int ldb, const Dec& dec, const Epi& epi, const int vb, const int panel = -1) {
;     ...
;     for (int i = 0; i < 2; ++i) { int R, C; stage_rc(tid * 16 + i * 8192, R, C); const int Rb = PERM ? ((R & ~31) + perm32(R & 31)) : R;
;         voffA[i] = (unsigned)(R * lda + C) * 2u; voffB[i] = (unsigned)(Rb * ldb + C) * 2u; }
;     const size_t kstep = (size_t)(BK * 2);
;     const size_t hstepA = (size_t)HALF * lda * 2, hstepB = (size_t)HALF * ldb * 2;
;     const unsigned ldsw = (unsigned)wid * 1024u;
;     const int aoff = lds_byte(wr * 64 + fr, fq * 8), boff = lds_byte(wc * 32 + fr, fq * 8);
;     ...
;     int cpm, cpn, npm, npn, ui = 0;
;     if (panel >= 0) { cpm = panel; cpn = 0; } else if (!unit_next(0, nM, nN, vb, cpm, cpn)) return;
;     f32x4 acc[2][2][4][2];
; #pragma unroll
;     for (int a = 0; a < 2; ++a)
; #pragma unroll
;         for (int b = 0; b < 2; ++b)
; #pragma unroll
;             for (int m = 0; m < 4; ++m)
; #pragma unroll
;                 for (int n = 0; n < 2; ++n) acc[a][b][m][n] = (f32x4){0.f, 0.f, 0.f, 0.f};
;     bf16x8 At[4][2], B0[2][2], B1[2][2];
;     const char* cA; const char* cB; dec(cpm, cpn, cA, cB);
;     G_STAGE(G_SB(0, 0), cB, voffB); G_STAGE(G_SA(0, 0), cA, voffA); G_STAGE(G_SB(0, 1), cB + hstepB, voffB); G_STAGE(G_SA(0, 1), cA + hstepA, voffA);
;     if (wr == 1) G_BAR;
;     G_WAIT_V(4); G_BAR;
;     G_STAGE(G_SB(1, 0), cB + kstep, voffB); G_STAGE(G_SA(1, 0), cA + kstep, voffA); G_STAGE(G_SB(1, 1), cB + hstepB + kstep, voffB);
;     G_WAIT_V(6); G_BAR;
; template <int ACT>
; DI void epi_bf16(const f32x4 (&acc)[2][2][4][2], bf16_t* O, const int ldc, int wr, int wc, int fr, int fq, const float* ssrow = nullptr) {
; #pragma unroll
;     for (int ai = 0; ai < 2; ++ai)
; #pragma unroll
;         for (int m = 0; m < 4; ++m) {
;             bf16_t* rowp = O + (size_t)(ai * HALF + wr * 64 + m * 16 + fr) * ldc + wc * 32 + 8 * fq;
;             const float rsc = ssrow ? __builtin_amdgcn_rsqf(ssrow[ai * HALF + wr * 64 + m * 16 + fr] * (1.f / 1024.f) + EPS_) : 1.f;
.LBB0_747:
	v_mov_b32_e32 v143, v133
	v_lshl_add_u64 v[8:9], s[10:11], 0, v[142:143]
	v_mov_b32_e32 v139, v133
	v_lshl_add_u64 v[10:11], s[10:11], 0, v[138:139]
	v_mov_b32_e32 v145, v133
	s_add_i32 m0, s36, 0x18000
	v_lshl_add_u64 v[8:9], v[8:9], 0, s[48:49]
	v_lshl_add_u64 v[12:13], s[12:13], 0, v[144:145]
	v_mov_b32_e32 v141, v133
	s_waitcnt vmcnt(4)
	s_barrier
	global_load_lds_dwordx4 v[8:9], off
	v_lshl_add_u64 v[8:9], v[10:11], 0, s[48:49]
	s_add_i32 m0, s36, 0x1a000
	s_add_i32 s72, s36, 0x8000
	v_lshl_add_u64 v[14:15], s[12:13], 0, v[140:141]
	global_load_lds_dwordx4 v[8:9], off
	v_lshl_add_u64 v[8:9], v[12:13], 0, s[48:49]
	s_mov_b32 m0, s72
	s_add_i32 s73, s36, 0xa000
	global_load_lds_dwordx4 v[8:9], off
	v_lshl_add_u64 v[8:9], v[14:15], 0, s[48:49]
	s_mov_b32 m0, s73
	s_lshl_b32 s2, s2, 5
	global_load_lds_dwordx4 v[8:9], off
	s_add_i32 m0, s36, 0x1c000
	v_lshl_add_u64 v[8:9], s[46:47], 0, v[142:143]
	global_load_lds_dwordx4 v[8:9], off
	v_lshl_add_u64 v[8:9], s[46:47], 0, v[138:139]
	s_add_i32 m0, s36, 0x1e000
	v_and_b32_e32 v7, 15, v3
	global_load_lds_dwordx4 v[8:9], off
	v_lshrrev_b32_e32 v8, 1, v3
	v_and_b32_e32 v8, 24, v8
	v_lshlrev_b32_e32 v9, 1, v8
	v_lshlrev_b32_e32 v3, 2, v3
	s_and_b32 s74, s2, 0x60
	v_lshl_or_b32 v146, s3, 6, v7
	v_lshl_or_b32 v7, v7, 6, v9
	s_lshl_b32 s3, s3, 13
	v_and_b32_e32 v3, 32, v3
	s_lshl_b32 s2, s74, 7
	v_bitop3_b32 v9, v7, s3, v3 bitop3:0xde
	v_bitop3_b32 v177, v7, s2, v3 bitop3:0xde
	v_or_b32_e32 v3, 16, v146
	v_mad_i64_i32 v[150:151], s[2:3], v3, s63, 0
	v_or_b32_e32 v3, 32, v146
	v_mad_i64_i32 v[152:153], s[2:3], v3, s63, 0
	v_or_b32_e32 v3, 48, v146
	v_mad_i64_i32 v[154:155], s[2:3], v3, s63, 0
	v_add_u32_e32 v3, 0x80, v146
	v_mad_i64_i32 v[156:157], s[2:3], v3, s63, 0
	v_add_u32_e32 v3, 0x90, v146
	v_mad_i64_i32 v[158:159], s[2:3], v3, s63, 0
	v_add_u32_e32 v3, 0xa0, v146
	v_mad_i64_i32 v[160:161], s[2:3], v3, s63, 0
	v_add_u32_e32 v3, 0xb0, v146
	v_mad_i64_i32 v[162:163], s[2:3], v3, s63, 0
	v_lshlrev_b32_e32 v3, 14, v5
	v_and_b32_e32 v3, 0xffff8000, v3
	v_lshl_add_u32 v3, v4, 11, v3
	v_and_b32_e32 v4, 1, v5
	v_lshl_or_b32 v3, v4, 6, v3
	v_lshl_add_u32 v164, v6, 1, v3
	v_lshlrev_b32_e32 v3, 14, v0
	v_and_b32_e32 v3, 0xffff8000, v3
	s_waitcnt vmcnt(0)
	v_lshl_add_u32 v1, v1, 11, v3
	v_and_b32_e32 v0, 1, v0
	v_mad_i64_i32 v[148:149], s[2:3], v146, s63, 0
	v_lshl_or_b32 v0, v0, 6, v1
	v_ashrrev_i32_e32 v147, 31, v146
	v_mov_b32_e32 v165, v133
	v_lshl_add_u32 v166, v2, 1, v0
	v_mov_b32_e32 v167, v133
	s_mov_b32 s75, 0
	v_add_u32_e32 v178, 0, v9
	v_lshlrev_b32_e32 v132, 1, v8
	s_mov_b32 s4, s6
	s_mov_b32 s15, s64
	s_mov_b64 s[2:3], s[12:13]
	s_mov_b64 s[28:29], s[10:11]
	s_barrier
	s_branch .LBB0_749

; #define G_STAGE(bufoff, gbase, voff) do { _Pragma("unroll") for (int _i = 0; _i < 2; ++_i) \
;         __builtin_amdgcn_global_load_lds((const unsigned*)((const char*)(gbase) + (voff)[_i]), (LAS unsigned*)(lds + (bufoff) + ldsw + _i * 8192), 16, 0, 0); } while (0)
; #define G_LDA(dst, b, h) do { _Pragma("unroll") for (int m = 0; m < 4; ++m) _Pragma("unroll") for (int k = 0; k < 2; ++k) dst[m][k] = *(const LAS bf16x8*)(lds + G_SA(b, h) + aoff + m * 2048 + k * 1024); } while (0)
; #define G_LDB(dst, b, h) do { _Pragma("unroll") for (int n = 0; n < 2; ++n) _Pragma("unroll") for (int k = 0; k < 2; ++k) dst[n][k] = *(const LAS bf16x8*)(lds + G_SB(b, h) + boff + n * 2048 + k * 1024); } while (0)
; #define G_WAIT_V(n) asm volatile("s_waitcnt vmcnt(" #n ")" ::: "memory")
; #define G_WAIT_L(n) asm volatile("s_waitcnt lgkmcnt(" #n ")" ::: "memory")
; #define G_BAR __builtin_amdgcn_s_barrier()
; #define G_SCHED __builtin_amdgcn_sched_barrier(0)
; template <bool PERM, class Dec, class Epi>
; DI void gemm_phase(LAS unsigned char* lds, const int nM, const int nN, const int K, const int lda, const int ldb, const Dec& dec, const Epi& epi, const int vb, const int panel = -1) {
;     ...
;         if (panel >= 0) { has_next = (ui + 1 < nN); npm = panel; npn = ui + 1; } else has_next = unit_next(ui + 1, nM, nN, vb, npm, npn);
;         const char* nA = cA; const char* nB = cB; if (has_next) dec(npm, npn, nA, nB);
; #pragma nounroll
;         for (int t = 0; t < nt; t += 2) {
;             const bool last = (t == nt - 2);
;             const char* a1 = cA + (size_t)(t + 1) * kstep;
;             const char* a2 = last ? nA : cA + (size_t)(t + 2) * kstep; const char* b2 = last ? nB : cB + (size_t)(t + 2) * kstep;
;             const char* a3 = a2 + kstep; const char* b3 = b2 + kstep;
;             G_LDB(B0, 0, 0); G_SCHED; G_LDA(At, 0, 0); G_STAGE(G_SA(1, 1), a1 + hstepA, voffA);
;             G_WAIT_L(8); G_BAR; G_WAIT_L(0); G_MMA(0, 0, At, B0); G_BAR; G_SCHED;
;             G_LDB(B1, 0, 1); G_STAGE(G_SB(0, 0), b2, voffB);
;             G_BAR; G_WAIT_L(0); G_MMA(0, 1, At, B1); G_BAR;
;             G_LDA(At, 0, 1); G_STAGE(G_SA(0, 0), a2, voffA);
;             G_BAR; G_WAIT_L(0); G_MMA(1, 0, At, B0); G_BAR; G_SCHED;
;             G_STAGE(G_SB(0, 1), b2 + hstepB, voffB);
;             G_WAIT_V(6); G_BAR; G_MMA(1, 1, At, B1); G_BAR;
.LBB0_752:
	s_add_u32 s28, s2, 0xfffc0080
	s_addc_u32 s29, s3, -1
	s_add_i32 s68, 0, 0x10000
	v_add_u32_e32 v172, s68, v177
	ds_read_b128 v[128:131], v172
	ds_read_b128 v[168:171], v172 offset:1024
	ds_read_b128 v[180:183], v172 offset:2048
	ds_read_b128 v[184:187], v172 offset:3072
	s_cmp_eq_u32 s76, 12
	s_cselect_b32 s31, s27, s29
	s_cselect_b32 s30, s33, s28
	s_cselect_b32 s29, s38, s53
	s_cselect_b32 s28, s39, s51
	v_lshl_add_u64 v[172:173], s[2:3], 0, v[164:165]
	s_add_i32 m0, s36, 0xc000
	ds_read_b128 v[188:191], v178
	ds_read_b128 v[194:197], v178 offset:1024
	ds_read_b128 v[198:201], v178 offset:2048
	ds_read_b128 v[202:205], v178 offset:3072
	ds_read_b128 v[206:209], v178 offset:4096
	ds_read_b128 v[210:213], v178 offset:5120
	ds_read_b128 v[214:217], v178 offset:6144
	ds_read_b128 v[218:221], v178 offset:7168
	global_load_lds_dwordx4 v[172:173], off
	v_lshl_add_u64 v[172:173], s[2:3], 0, v[166:167]
	s_add_i32 m0, s36, 0xe000
	s_nop 0
	global_load_lds_dwordx4 v[172:173], off
	s_waitcnt lgkmcnt(8)
	s_barrier
	s_waitcnt lgkmcnt(0)
	s_setprio 1
	s_waitcnt lgkmcnt(0)
	v_mfma_f32_16x16x32_bf16 v[124:127], v[128:131], v[188:191], v[124:127]
	v_mfma_f32_16x16x32_bf16 v[120:123], v[180:183], v[188:191], v[120:123]
	v_mfma_f32_16x16x32_bf16 v[112:115], v[128:131], v[198:201], v[112:115]
	v_mfma_f32_16x16x32_bf16 v[104:107], v[180:183], v[198:201], v[104:107]
	v_mfma_f32_16x16x32_bf16 v[96:99], v[128:131], v[206:209], v[96:99]
	v_mfma_f32_16x16x32_bf16 v[88:91], v[180:183], v[206:209], v[88:91]
	v_mfma_f32_16x16x32_bf16 v[80:83], v[128:131], v[214:217], v[80:83]
	v_mfma_f32_16x16x32_bf16 v[72:75], v[180:183], v[214:217], v[72:75]
	v_mfma_f32_16x16x32_bf16 v[124:127], v[168:171], v[194:197], v[124:127]
	v_mfma_f32_16x16x32_bf16 v[120:123], v[184:187], v[194:197], v[120:123]
	v_mfma_f32_16x16x32_bf16 v[112:115], v[168:171], v[202:205], v[112:115]
	v_mfma_f32_16x16x32_bf16 v[104:107], v[184:187], v[202:205], v[104:107]
	v_mfma_f32_16x16x32_bf16 v[96:99], v[168:171], v[210:213], v[96:99]
	v_mfma_f32_16x16x32_bf16 v[88:91], v[184:187], v[210:213], v[88:91]
	v_mfma_f32_16x16x32_bf16 v[80:83], v[168:171], v[218:221], v[80:83]
	v_mfma_f32_16x16x32_bf16 v[72:75], v[184:187], v[218:221], v[72:75]
	s_setprio 0
	s_barrier
	s_add_i32 s77, 0, 0x14000
	v_add_u32_e32 v172, s77, v177
	s_add_i32 s68, s68, s35
	ds_read_b128 v[222:225], v172
	ds_read_b128 v[226:229], v172 offset:1024
	ds_read_b128 v[230:233], v172 offset:2048
	ds_read_b128 v[234:237], v172 offset:3072
	v_lshl_add_u64 v[172:173], s[28:29], 0, v[142:143]
	s_mov_b32 m0, s68
	v_lshl_add_u64 v[238:239], s[28:29], 0, v[138:139]
	global_load_lds_dwordx4 v[172:173], off
	s_add_i32 m0, s68, 0x2000
	s_nop 0
	global_load_lds_dwordx4 v[238:239], off
	s_barrier
	s_waitcnt lgkmcnt(0)
	s_setprio 1
	s_waitcnt lgkmcnt(0)
	v_mfma_f32_16x16x32_bf16 v[116:119], v[222:225], v[188:191], v[116:119]
	v_mfma_f32_16x16x32_bf16 v[108:111], v[230:233], v[188:191], v[108:111]
	v_mfma_f32_16x16x32_bf16 v[100:103], v[222:225], v[198:201], v[100:103]
	v_mfma_f32_16x16x32_bf16 v[92:95], v[230:233], v[198:201], v[92:95]
	v_mfma_f32_16x16x32_bf16 v[84:87], v[222:225], v[206:209], v[84:87]
	v_mfma_f32_16x16x32_bf16 v[76:79], v[230:233], v[206:209], v[76:79]
	v_mfma_f32_16x16x32_bf16 v[68:71], v[222:225], v[214:217], v[68:71]
	v_mfma_f32_16x16x32_bf16 v[64:67], v[230:233], v[214:217], v[64:67]
	v_mfma_f32_16x16x32_bf16 v[116:119], v[226:229], v[194:197], v[116:119]
	v_mfma_f32_16x16x32_bf16 v[108:111], v[234:237], v[194:197], v[108:111]
	v_mfma_f32_16x16x32_bf16 v[100:103], v[226:229], v[202:205], v[100:103]
	v_mfma_f32_16x16x32_bf16 v[92:95], v[234:237], v[202:205], v[92:95]
	v_mfma_f32_16x16x32_bf16 v[84:87], v[226:229], v[210:213], v[84:87]
	v_mfma_f32_16x16x32_bf16 v[76:79], v[234:237], v[210:213], v[76:79]
	v_mfma_f32_16x16x32_bf16 v[68:71], v[226:229], v[218:221], v[68:71]
	v_mfma_f32_16x16x32_bf16 v[64:67], v[234:237], v[218:221], v[64:67]
	s_setprio 0
	s_mov_b32 m0, s36
	v_lshl_add_u64 v[240:241], s[30:31], 0, v[144:145]
	s_barrier
	ds_read_b128 v[188:191], v178 offset:16384
	ds_read_b128 v[194:197], v178 offset:17408
	ds_read_b128 v[198:201], v178 offset:18432
	ds_read_b128 v[202:205], v178 offset:19456
	ds_read_b128 v[206:209], v178 offset:20480
	ds_read_b128 v[210:213], v178 offset:21504
	ds_read_b128 v[214:217], v178 offset:22528
	ds_read_b128 v[218:221], v178 offset:23552
	global_load_lds_dwordx4 v[240:241], off
	v_lshl_add_u64 v[242:243], s[30:31], 0, v[140:141]
	s_mov_b32 m0, s37
	s_nop 0
	global_load_lds_dwordx4 v[242:243], off
	s_barrier
	s_waitcnt lgkmcnt(0)
	s_setprio 1
	s_waitcnt lgkmcnt(0)
	v_mfma_f32_16x16x32_bf16 v[60:63], v[128:131], v[188:191], v[60:63]
	v_mfma_f32_16x16x32_bf16 v[56:59], v[180:183], v[188:191], v[56:59]
	v_mfma_f32_16x16x32_bf16 v[48:51], v[128:131], v[198:201], v[48:51]
	v_mfma_f32_16x16x32_bf16 v[40:43], v[180:183], v[198:201], v[40:43]
	v_mfma_f32_16x16x32_bf16 v[32:35], v[128:131], v[206:209], v[32:35]
	v_mfma_f32_16x16x32_bf16 v[24:27], v[180:183], v[206:209], v[24:27]
	v_mfma_f32_16x16x32_bf16 v[16:19], v[128:131], v[214:217], v[16:19]
	v_mfma_f32_16x16x32_bf16 v[8:11], v[180:183], v[214:217], v[8:11]
	v_mfma_f32_16x16x32_bf16 v[60:63], v[168:171], v[194:197], v[60:63]
	v_mfma_f32_16x16x32_bf16 v[56:59], v[184:187], v[194:197], v[56:59]
	v_mfma_f32_16x16x32_bf16 v[48:51], v[168:171], v[202:205], v[48:51]
	v_mfma_f32_16x16x32_bf16 v[40:43], v[184:187], v[202:205], v[40:43]
	v_mfma_f32_16x16x32_bf16 v[32:35], v[168:171], v[210:213], v[32:35]
	v_mfma_f32_16x16x32_bf16 v[24:27], v[184:187], v[210:213], v[24:27]
	v_mfma_f32_16x16x32_bf16 v[16:19], v[168:171], v[218:221], v[16:19]
	v_mfma_f32_16x16x32_bf16 v[8:11], v[184:187], v[218:221], v[8:11]
	s_setprio 0
	s_barrier
	s_add_u32 s68, s28, 0x40000
	s_addc_u32 s69, s29, 0
	s_add_i32 s77, s77, s35
	v_lshl_add_u64 v[128:129], s[68:69], 0, v[142:143]
	s_mov_b32 m0, s77
	s_nop 0
	global_load_lds_dwordx4 v[128:129], off
	v_lshl_add_u64 v[128:129], s[68:69], 0, v[138:139]
	s_add_i32 m0, s77, 0x2000
	s_nop 0
	global_load_lds_dwordx4 v[128:129], off
	s_cmp_eq_u32 s76, -2
	s_cbranch_scc1 .Lfi4_752
	s_waitcnt vmcnt(6)
; #define G_STAGE(bufoff, gbase, voff) do { _Pragma("unroll") for (int _i = 0; _i < 2; ++_i) \
;         __builtin_amdgcn_global_load_lds((const unsigned*)((const char*)(gbase) + (voff)[_i]), (LAS unsigned*)(lds + (bufoff) + ldsw + _i * 8192), 16, 0, 0); } while (0)
; #define G_LDA(dst, b, h) do { _Pragma("unroll") for (int m = 0; m < 4; ++m) _Pragma("unroll") for (int k = 0; k < 2; ++k) dst[m][k] = *(const LAS bf16x8*)(lds + G_SA(b, h) + aoff + m * 2048 + k * 1024); } while (0)
; #define G_LDB(dst, b, h) do { _Pragma("unroll") for (int n = 0; n < 2; ++n) _Pragma("unroll") for (int k = 0; k < 2; ++k) dst[n][k] = *(const LAS bf16x8*)(lds + G_SB(b, h) + boff + n * 2048 + k * 1024); } while (0)
; #define G_MMA(ai, bj, At, Bt) do { __builtin_amdgcn_s_setprio(1); _Pragma("unroll") for (int m = 0; m < 4; ++m) _Pragma("unroll") for (int n = 0; n < 2; ++n) _Pragma("unroll") for (int k = 0; k < 2; ++k) \
;         acc[ai][bj][m][n] = __builtin_amdgcn_mfma_f32_16x16x32_bf16(Bt[n][k], At[m][k], acc[ai][bj][m][n], 0, 0, 0); __builtin_amdgcn_s_setprio(0); } while (0)
; #define G_WAIT_V(n) asm volatile("s_waitcnt vmcnt(" #n ")" ::: "memory")
; #define G_WAIT_L(n) asm volatile("s_waitcnt lgkmcnt(" #n ")" ::: "memory")
; #define G_BAR __builtin_amdgcn_s_barrier()
; #define G_SCHED __builtin_amdgcn_sched_barrier(0)
; template <bool PERM, class Dec, class Epi>
; DI void gemm_phase(LAS unsigned char* lds, const int nM, const int nN, const int K, const int lda, const int ldb, const Dec& dec, const Epi& epi, const int vb, const int panel = -1) {
;     ...
;             G_WAIT_V(6); G_BAR; G_MMA(1, 1, At, B1); G_BAR;
;             G_LDB(B0, 1, 0); G_SCHED; G_LDA(At, 1, 0); G_STAGE(G_SA(0, 1), a2 + hstepA, voffA);
;             G_WAIT_L(8); G_BAR; G_WAIT_L(0); G_MMA(0, 0, At, B0); G_BAR; G_SCHED;
;             G_LDB(B1, 1, 1); G_STAGE(G_SB(1, 0), b3, voffB);
;             G_BAR; G_WAIT_L(0); G_MMA(0, 1, At, B1); G_BAR;
;             G_LDA(At, 1, 1); G_STAGE(G_SA(1, 0), a3, voffA);
;             G_BAR; G_WAIT_L(0); G_MMA(1, 0, At, B0); G_BAR; G_SCHED;
.Lfi4_752:
	s_barrier
	s_setprio 1
	v_mfma_f32_16x16x32_bf16 v[52:55], v[222:225], v[188:191], v[52:55]
	v_mfma_f32_16x16x32_bf16 v[44:47], v[230:233], v[188:191], v[44:47]
	v_mfma_f32_16x16x32_bf16 v[36:39], v[222:225], v[198:201], v[36:39]
	v_mfma_f32_16x16x32_bf16 v[28:31], v[230:233], v[198:201], v[28:31]
	v_mfma_f32_16x16x32_bf16 v[20:23], v[222:225], v[206:209], v[20:23]
	v_mfma_f32_16x16x32_bf16 v[12:15], v[230:233], v[206:209], v[12:15]
	v_mfma_f32_16x16x32_bf16 v[4:7], v[222:225], v[214:217], v[4:7]
	v_mfma_f32_16x16x32_bf16 v[0:3], v[230:233], v[214:217], v[0:3]
	v_mfma_f32_16x16x32_bf16 v[52:55], v[226:229], v[194:197], v[52:55]
	v_mfma_f32_16x16x32_bf16 v[44:47], v[234:237], v[194:197], v[44:47]
	v_mfma_f32_16x16x32_bf16 v[36:39], v[226:229], v[202:205], v[36:39]
	v_mfma_f32_16x16x32_bf16 v[28:31], v[234:237], v[202:205], v[28:31]
	v_mfma_f32_16x16x32_bf16 v[20:23], v[226:229], v[210:213], v[20:23]
	v_mfma_f32_16x16x32_bf16 v[12:15], v[234:237], v[210:213], v[12:15]
	v_mfma_f32_16x16x32_bf16 v[4:7], v[226:229], v[218:221], v[4:7]
	v_mfma_f32_16x16x32_bf16 v[0:3], v[234:237], v[218:221], v[0:3]
	s_setprio 0
	s_add_i32 s68, 0, 0x18000
	v_add_u32_e32 v179, s68, v177
	s_barrier
	ds_read_b128 v[128:131], v179
	ds_read_b128 v[168:171], v179 offset:1024
	ds_read_b128 v[180:183], v179 offset:2048
	ds_read_b128 v[184:187], v179 offset:3072
	s_add_u32 s30, s30, 0x40000
	s_addc_u32 s31, s31, 0
	s_mov_b32 m0, s70
	v_lshl_add_u64 v[222:223], s[30:31], 0, v[144:145]
	ds_read_b128 v[188:191], v178 offset:32768
	ds_read_b128 v[194:197], v178 offset:33792
	ds_read_b128 v[198:201], v178 offset:34816
	ds_read_b128 v[202:205], v178 offset:35840
	ds_read_b128 v[206:209], v178 offset:36864
	ds_read_b128 v[210:213], v178 offset:37888
	ds_read_b128 v[214:217], v178 offset:38912
	ds_read_b128 v[218:221], v178 offset:39936
	global_load_lds_dwordx4 v[222:223], off
	v_lshl_add_u64 v[222:223], s[30:31], 0, v[140:141]
	s_mov_b32 m0, s71
	s_nop 0
	global_load_lds_dwordx4 v[222:223], off
	s_waitcnt lgkmcnt(8)
	s_barrier
	s_waitcnt lgkmcnt(0)
	s_setprio 1
	s_waitcnt lgkmcnt(0)
	v_mfma_f32_16x16x32_bf16 v[124:127], v[128:131], v[188:191], v[124:127]
	v_mfma_f32_16x16x32_bf16 v[120:123], v[180:183], v[188:191], v[120:123]
	v_mfma_f32_16x16x32_bf16 v[112:115], v[128:131], v[198:201], v[112:115]
	v_mfma_f32_16x16x32_bf16 v[104:107], v[180:183], v[198:201], v[104:107]
	v_mfma_f32_16x16x32_bf16 v[96:99], v[128:131], v[206:209], v[96:99]
	v_mfma_f32_16x16x32_bf16 v[88:91], v[180:183], v[206:209], v[88:91]
	v_mfma_f32_16x16x32_bf16 v[80:83], v[128:131], v[214:217], v[80:83]
	v_mfma_f32_16x16x32_bf16 v[72:75], v[180:183], v[214:217], v[72:75]
	v_mfma_f32_16x16x32_bf16 v[124:127], v[168:171], v[194:197], v[124:127]
	v_mfma_f32_16x16x32_bf16 v[120:123], v[184:187], v[194:197], v[120:123]
	v_mfma_f32_16x16x32_bf16 v[112:115], v[168:171], v[202:205], v[112:115]
	v_mfma_f32_16x16x32_bf16 v[104:107], v[184:187], v[202:205], v[104:107]
	v_mfma_f32_16x16x32_bf16 v[96:99], v[168:171], v[210:213], v[96:99]
	v_mfma_f32_16x16x32_bf16 v[88:91], v[184:187], v[210:213], v[88:91]
	v_mfma_f32_16x16x32_bf16 v[80:83], v[168:171], v[218:221], v[80:83]
	v_mfma_f32_16x16x32_bf16 v[72:75], v[184:187], v[218:221], v[72:75]
	s_setprio 0
	s_barrier
	s_add_i32 s30, 0, 0x1c000
	s_add_i32 s31, s68, s35
	v_add_u32_e32 v179, s30, v177
	v_lshl_add_u64 v[172:173], v[172:173], 0, s[48:49]
	s_mov_b32 m0, s31
	ds_read_b128 v[222:225], v179
	ds_read_b128 v[226:229], v179 offset:1024
	ds_read_b128 v[230:233], v179 offset:2048
	ds_read_b128 v[234:237], v179 offset:3072
	global_load_lds_dwordx4 v[172:173], off
	v_lshl_add_u64 v[172:173], v[238:239], 0, s[48:49]
	s_add_i32 m0, s31, 0x2000
	s_nop 0
	global_load_lds_dwordx4 v[172:173], off
	s_cmp_lg_u32 s76, -2
	s_cbranch_scc1 .Lfi6_752
	s_waitcnt vmcnt(10)
.Lfi6_752:
	s_barrier
	s_waitcnt lgkmcnt(0)
	s_setprio 1
	s_waitcnt lgkmcnt(0)
	v_mfma_f32_16x16x32_bf16 v[116:119], v[222:225], v[188:191], v[116:119]
	v_mfma_f32_16x16x32_bf16 v[108:111], v[230:233], v[188:191], v[108:111]
	v_mfma_f32_16x16x32_bf16 v[100:103], v[222:225], v[198:201], v[100:103]
	v_mfma_f32_16x16x32_bf16 v[92:95], v[230:233], v[198:201], v[92:95]
	v_mfma_f32_16x16x32_bf16 v[84:87], v[222:225], v[206:209], v[84:87]
	v_mfma_f32_16x16x32_bf16 v[76:79], v[230:233], v[206:209], v[76:79]
	v_mfma_f32_16x16x32_bf16 v[68:71], v[222:225], v[214:217], v[68:71]
	v_mfma_f32_16x16x32_bf16 v[64:67], v[230:233], v[214:217], v[64:67]
	v_mfma_f32_16x16x32_bf16 v[116:119], v[226:229], v[194:197], v[116:119]
	v_mfma_f32_16x16x32_bf16 v[108:111], v[234:237], v[194:197], v[108:111]
	v_mfma_f32_16x16x32_bf16 v[100:103], v[226:229], v[202:205], v[100:103]
	v_mfma_f32_16x16x32_bf16 v[92:95], v[234:237], v[202:205], v[92:95]
	v_mfma_f32_16x16x32_bf16 v[84:87], v[226:229], v[210:213], v[84:87]
	v_mfma_f32_16x16x32_bf16 v[76:79], v[234:237], v[210:213], v[76:79]
	v_mfma_f32_16x16x32_bf16 v[68:71], v[226:229], v[218:221], v[68:71]
	v_mfma_f32_16x16x32_bf16 v[64:67], v[234:237], v[218:221], v[64:67]
	s_setprio 0
	s_mov_b32 m0, s72
	v_lshl_add_u64 v[172:173], v[240:241], 0, s[48:49]
	s_barrier
	ds_read_b128 v[188:191], v178 offset:49152
	ds_read_b128 v[194:197], v178 offset:50176
	ds_read_b128 v[198:201], v178 offset:51200
	ds_read_b128 v[202:205], v178 offset:52224
	ds_read_b128 v[206:209], v178 offset:53248
	ds_read_b128 v[210:213], v178 offset:54272
	ds_read_b128 v[214:217], v178 offset:55296
	ds_read_b128 v[218:221], v178 offset:56320
	global_load_lds_dwordx4 v[172:173], off
	v_lshl_add_u64 v[172:173], v[242:243], 0, s[48:49]
	s_mov_b32 m0, s73
	s_nop 0
	global_load_lds_dwordx4 v[172:173], off
	s_barrier
; DI unsigned pk2(float a, float b) { f32x2 v = {a, b}; bf2_t r = __builtin_convertvector(v, bf2_t); return __builtin_bit_cast(unsigned, r); }
; DI float sigm(float x) { return __builtin_amdgcn_rcpf(1.f + __expf(-x)); }
; DI float silu_(float x) { return x * __builtin_amdgcn_rcpf(1.f + __expf(-x)); }
; #define G_STAGE(bufoff, gbase, voff) do { _Pragma("unroll") for (int _i = 0; _i < 2; ++_i) \
;         __builtin_amdgcn_global_load_lds((const unsigned*)((const char*)(gbase) + (voff)[_i]), (LAS unsigned*)(lds + (bufoff) + ldsw + _i * 8192), 16, 0, 0); } while (0)
; #define G_WAIT_V(n) asm volatile("s_waitcnt vmcnt(" #n ")" ::: "memory")
; #define G_WAIT_L(n) asm volatile("s_waitcnt lgkmcnt(" #n ")" ::: "memory")
; template <bool PERM, class Dec, class Epi>
; DI void gemm_phase(LAS unsigned char* lds, const int nM, const int nN, const int K, const int lda, const int ldb, const Dec& dec, const Epi& epi, const int vb, const int panel = -1) {
;     ...
;             G_LDA(At, 1, 1); G_STAGE(G_SA(1, 0), a3, voffA);
;             G_BAR; G_WAIT_L(0); G_MMA(1, 0, At, B0); G_BAR; G_SCHED;
;             G_STAGE(G_SB(1, 1), b3 + hstepB, voffB);
;             G_WAIT_V(6); G_BAR; G_MMA(1, 1, At, B1); G_BAR;
;         }
; template <int ACT>
; DI void epi_bf16(const f32x4 (&acc)[2][2][4][2], bf16_t* O, const int ldc, int wr, int wc, int fr, int fq, const float* ssrow = nullptr) {
; #pragma unroll
;     for (int ai = 0; ai < 2; ++ai)
; #pragma unroll
;         for (int m = 0; m < 4; ++m) {
;             bf16_t* rowp = O + (size_t)(ai * HALF + wr * 64 + m * 16 + fr) * ldc + wc * 32 + 8 * fq;
;             const float rsc = ssrow ? __builtin_amdgcn_rsqf(ssrow[ai * HALF + wr * 64 + m * 16 + fr] * (1.f / 1024.f) + EPS_) : 1.f;
; #pragma unroll
;             for (int bj = 0; bj < 2; ++bj) {
;                 f32x4 v0 = acc[ai][bj][m][0] * rsc, v1 = acc[ai][bj][m][1] * rsc;
;                 if (ACT == 1) {
; #pragma unroll
;                     for (int j = 0; j < 4; ++j) { v0[j] = silu_(v0[j]); v1[j] = silu_(v1[j]); } }
;                 if (ACT == 2) {
; #pragma unroll
;                     for (int j = 0; j < 4; ++j) { v0[j] = sigm(v0[j]); v1[j] = sigm(v1[j]); } }
;                 u32x4 w; w[0] = pk2(v0[0], v0[1]); w[1] = pk2(v0[2], v0[3]); w[2] = pk2(v1[0], v1[1]); w[3] = pk2(v1[2], v1[3]);
;                 *(u32x4*)(rowp + bj * HALF) = w;
	s_waitcnt lgkmcnt(0)
	s_setprio 1
	s_waitcnt lgkmcnt(0)
	v_mfma_f32_16x16x32_bf16 v[60:63], v[128:131], v[188:191], v[60:63]
	v_mfma_f32_16x16x32_bf16 v[56:59], v[180:183], v[188:191], v[56:59]
	v_mfma_f32_16x16x32_bf16 v[48:51], v[128:131], v[198:201], v[48:51]
	v_mfma_f32_16x16x32_bf16 v[40:43], v[180:183], v[198:201], v[40:43]
	v_mfma_f32_16x16x32_bf16 v[32:35], v[128:131], v[206:209], v[32:35]
	v_mfma_f32_16x16x32_bf16 v[24:27], v[180:183], v[206:209], v[24:27]
	v_mfma_f32_16x16x32_bf16 v[16:19], v[128:131], v[214:217], v[16:19]
	v_mfma_f32_16x16x32_bf16 v[8:11], v[180:183], v[214:217], v[8:11]
	v_mfma_f32_16x16x32_bf16 v[60:63], v[168:171], v[194:197], v[60:63]
	v_mfma_f32_16x16x32_bf16 v[56:59], v[184:187], v[194:197], v[56:59]
	v_mfma_f32_16x16x32_bf16 v[48:51], v[168:171], v[202:205], v[48:51]
	v_mfma_f32_16x16x32_bf16 v[40:43], v[184:187], v[202:205], v[40:43]
	v_mfma_f32_16x16x32_bf16 v[32:35], v[168:171], v[210:213], v[32:35]
	v_mfma_f32_16x16x32_bf16 v[24:27], v[184:187], v[210:213], v[24:27]
	v_mfma_f32_16x16x32_bf16 v[16:19], v[168:171], v[218:221], v[16:19]
	v_mfma_f32_16x16x32_bf16 v[8:11], v[184:187], v[218:221], v[8:11]
	s_setprio 0
	s_barrier
	s_add_u32 s28, s28, 0x40080
	s_addc_u32 s29, s29, 0
	s_add_i32 s30, s30, s35
	v_lshl_add_u64 v[128:129], s[28:29], 0, v[142:143]
	s_mov_b32 m0, s30
	s_nop 0
	global_load_lds_dwordx4 v[128:129], off
	v_lshl_add_u64 v[128:129], s[28:29], 0, v[138:139]
	s_add_i32 m0, s30, 0x2000
	s_nop 0
	global_load_lds_dwordx4 v[128:129], off
	s_waitcnt vmcnt(6)
	s_barrier
	s_setprio 1
	v_mfma_f32_16x16x32_bf16 v[52:55], v[222:225], v[188:191], v[52:55]
	v_mfma_f32_16x16x32_bf16 v[44:47], v[230:233], v[188:191], v[44:47]
	v_mfma_f32_16x16x32_bf16 v[36:39], v[222:225], v[198:201], v[36:39]
	v_mfma_f32_16x16x32_bf16 v[28:31], v[230:233], v[198:201], v[28:31]
	v_mfma_f32_16x16x32_bf16 v[20:23], v[222:225], v[206:209], v[20:23]
	v_mfma_f32_16x16x32_bf16 v[12:15], v[230:233], v[206:209], v[12:15]
	v_mfma_f32_16x16x32_bf16 v[4:7], v[222:225], v[214:217], v[4:7]
	v_mfma_f32_16x16x32_bf16 v[0:3], v[230:233], v[214:217], v[0:3]
	v_mfma_f32_16x16x32_bf16 v[52:55], v[226:229], v[194:197], v[52:55]
	v_mfma_f32_16x16x32_bf16 v[44:47], v[234:237], v[194:197], v[44:47]
	v_mfma_f32_16x16x32_bf16 v[36:39], v[226:229], v[202:205], v[36:39]
	v_mfma_f32_16x16x32_bf16 v[28:31], v[234:237], v[202:205], v[28:31]
	v_mfma_f32_16x16x32_bf16 v[20:23], v[226:229], v[210:213], v[20:23]
	v_mfma_f32_16x16x32_bf16 v[12:15], v[234:237], v[210:213], v[12:15]
	v_mfma_f32_16x16x32_bf16 v[4:7], v[226:229], v[218:221], v[4:7]
	v_mfma_f32_16x16x32_bf16 v[0:3], v[234:237], v[218:221], v[0:3]
	s_setprio 0
	s_add_i32 s76, s76, 2
	s_add_u32 s2, s2, 0x100
	s_addc_u32 s3, s3, 0
	s_add_u32 s51, s51, 0x100
	s_addc_u32 s53, s53, 0
	s_cmp_gt_u32 s76, 13
	s_barrier
	s_cbranch_scc0 .LBB0_752
	s_lshl_b32 s2, s4, 8
	s_ashr_i32 s3, s2, 31
	s_lshl_b64 s[2:3], s[2:3], 2
	s_add_u32 s28, s86, s2
	s_addc_u32 s29, s87, s3
	s_lshl_b32 s30, s15, 8
	s_cmp_gt_i32 s15, 5
	s_mul_hi_i32 s15, s4, 0xc0000
	s_mul_i32 s27, s4, 0xc0000
	s_mov_b64 s[2:3], -1
	v_lshl_add_u64 v[168:169], v[146:147], 2, s[28:29]
	s_cbranch_scc0 .LBB0_755
	global_load_dword v236, v[168:169], off
	global_load_dword v237, v[168:169], off offset:64
	global_load_dword v238, v[168:169], off offset:128
	global_load_dword v239, v[168:169], off offset:192
	global_load_dword v240, v[168:169], off offset:512
	global_load_dword v241, v[168:169], off offset:576
	global_load_dword v242, v[168:169], off offset:640
	global_load_dword v243, v[168:169], off offset:704
	s_add_u32 s28, s16, s27
	s_addc_u32 s29, s17, s15
	s_add_i32 s4, s30, 0xfffffa00
	s_lshl_b64 s[2:3], s[4:5], 1
	s_add_u32 s28, s28, s2
	s_addc_u32 s29, s29, s3
	s_lshl_b32 s2, s74, 1
	s_add_u32 s2, s28, s2
	s_addc_u32 s3, s29, 0
	v_lshl_add_u64 v[128:129], s[2:3], 0, v[132:133]
	v_lshl_add_u64 v[130:131], v[128:129], 0, v[148:149]
	s_mov_b64 s[2:3], 0
	s_waitcnt vmcnt(0)
	v_mov_b32_e32 v170, v236
	v_fmamk_f32 v170, v170, 0x3a800000, v175
	v_rsq_f32_e32 v180, v170
	s_nop 0
	v_pk_mul_f32 v[172:173], v[124:125], v[180:181] op_sel_hi:[1,0]
	s_nop 0
	v_mul_f32_e32 v179, 0xbfb8aa3b, v172
	v_exp_f32_e32 v179, v179
	v_pk_mul_f32 v[184:185], v[120:121], v[180:181] op_sel_hi:[1,0]
	v_pk_mul_f32 v[170:171], v[126:127], v[180:181] op_sel_hi:[1,0]
	v_pk_mul_f32 v[182:183], v[122:123], v[180:181] op_sel_hi:[1,0]
	v_add_f32_e32 v179, 1.0, v179
	v_rcp_f32_e32 v186, v179
	v_mul_f32_e32 v179, 0xbfb8aa3b, v184
	v_exp_f32_e32 v179, v179
	s_nop 0
	v_add_f32_e32 v179, 1.0, v179
	v_rcp_f32_e32 v188, v179
	v_mul_f32_e32 v179, 0xbfb8aa3b, v173
	v_exp_f32_e32 v179, v179
	s_nop 0
	v_add_f32_e32 v179, 1.0, v179
	v_rcp_f32_e32 v187, v179
	v_mul_f32_e32 v179, 0xbfb8aa3b, v185
	v_exp_f32_e32 v179, v179
	v_pk_mul_f32 v[172:173], v[172:173], v[186:187]
	v_add_f32_e32 v179, 1.0, v179
	v_rcp_f32_e32 v189, v179
	v_mul_f32_e32 v179, 0xbfb8aa3b, v170
	v_exp_f32_e32 v179, v179
	v_pk_mul_f32 v[184:185], v[184:185], v[188:189]
	v_add_f32_e32 v179, 1.0, v179
	v_rcp_f32_e32 v186, v179
	v_mul_f32_e32 v179, 0xbfb8aa3b, v182
	v_exp_f32_e32 v179, v179
	s_nop 0
	v_add_f32_e32 v179, 1.0, v179
	v_rcp_f32_e32 v188, v179
	v_mul_f32_e32 v179, 0xbfb8aa3b, v171
	v_exp_f32_e32 v179, v179
	s_nop 0
	v_add_f32_e32 v179, 1.0, v179
	v_rcp_f32_e32 v187, v179
	s_nop 0
	v_pk_mul_f32 v[186:187], v[170:171], v[186:187]
	v_mul_f32_e32 v170, 0xbfb8aa3b, v183
	v_exp_f32_e32 v170, v170
	v_cvt_pk_bf16_f32 v171, v186, v187
	v_add_f32_e32 v170, 1.0, v170
	v_rcp_f32_e32 v189, v170
	v_cvt_pk_bf16_f32 v170, v172, v173
	v_cvt_pk_bf16_f32 v172, v184, v185
	v_pk_mul_f32 v[182:183], v[182:183], v[188:189]
	s_nop 0
; DI unsigned pk2(float a, float b) { f32x2 v = {a, b}; bf2_t r = __builtin_convertvector(v, bf2_t); return __builtin_bit_cast(unsigned, r); }
; DI float sigm(float x) { return __builtin_amdgcn_rcpf(1.f + __expf(-x)); }
; DI float silu_(float x) { return x * __builtin_amdgcn_rcpf(1.f + __expf(-x)); }
; template <int ACT>
; DI void epi_bf16(const f32x4 (&acc)[2][2][4][2], bf16_t* O, const int ldc, int wr, int wc, int fr, int fq, const float* ssrow = nullptr) {
;     ...
;             bf16_t* rowp = O + (size_t)(ai * HALF + wr * 64 + m * 16 + fr) * ldc + wc * 32 + 8 * fq;
;             const float rsc = ssrow ? __builtin_amdgcn_rsqf(ssrow[ai * HALF + wr * 64 + m * 16 + fr] * (1.f / 1024.f) + EPS_) : 1.f;
; #pragma unroll
;             for (int bj = 0; bj < 2; ++bj) {
;                 f32x4 v0 = acc[ai][bj][m][0] * rsc, v1 = acc[ai][bj][m][1] * rsc;
;                 if (ACT == 1) {
; #pragma unroll
;                     for (int j = 0; j < 4; ++j) { v0[j] = silu_(v0[j]); v1[j] = silu_(v1[j]); } }
;                 if (ACT == 2) {
; #pragma unroll
;                     for (int j = 0; j < 4; ++j) { v0[j] = sigm(v0[j]); v1[j] = sigm(v1[j]); } }
;                 u32x4 w; w[0] = pk2(v0[0], v0[1]); w[1] = pk2(v0[2], v0[3]); w[2] = pk2(v1[0], v1[1]); w[3] = pk2(v1[2], v1[3]);
;                 *(u32x4*)(rowp + bj * HALF) = w;
	v_cvt_pk_bf16_f32 v173, v182, v183
	global_store_dwordx4 v[130:131], v[170:173], off
	v_pk_mul_f32 v[182:183], v[118:119], v[180:181] op_sel_hi:[1,0]
	s_nop 0
	v_pk_mul_f32 v[172:173], v[116:117], v[180:181] op_sel_hi:[1,0]
	v_pk_mul_f32 v[170:171], v[110:111], v[180:181] op_sel_hi:[1,0]
	v_mul_f32_e32 v179, 0xbfb8aa3b, v172
	v_exp_f32_e32 v179, v179
	v_pk_mul_f32 v[180:181], v[108:109], v[180:181] op_sel_hi:[1,0]
	v_add_f32_e32 v179, 1.0, v179
	v_rcp_f32_e32 v184, v179
	v_mul_f32_e32 v179, 0xbfb8aa3b, v180
	v_exp_f32_e32 v179, v179
	s_nop 0
	v_add_f32_e32 v179, 1.0, v179
	v_rcp_f32_e32 v186, v179
	v_mul_f32_e32 v179, 0xbfb8aa3b, v173
	v_exp_f32_e32 v179, v179
	s_nop 0
	v_add_f32_e32 v179, 1.0, v179
	v_rcp_f32_e32 v185, v179
	v_mul_f32_e32 v179, 0xbfb8aa3b, v181
	v_exp_f32_e32 v179, v179
	v_pk_mul_f32 v[172:173], v[172:173], v[184:185]
	v_add_f32_e32 v179, 1.0, v179
	v_rcp_f32_e32 v187, v179
	v_mul_f32_e32 v179, 0xbfb8aa3b, v182
	v_exp_f32_e32 v179, v179
	v_pk_mul_f32 v[180:181], v[180:181], v[186:187]
	v_add_f32_e32 v179, 1.0, v179
	v_rcp_f32_e32 v184, v179
	v_mul_f32_e32 v179, 0xbfb8aa3b, v170
	v_exp_f32_e32 v179, v179
	s_nop 0
	v_add_f32_e32 v179, 1.0, v179
	v_rcp_f32_e32 v186, v179
	v_mul_f32_e32 v179, 0xbfb8aa3b, v183
	v_exp_f32_e32 v179, v179
	s_nop 0
	v_add_f32_e32 v179, 1.0, v179
	v_rcp_f32_e32 v185, v179
	v_mul_f32_e32 v179, 0xbfb8aa3b, v171
	v_exp_f32_e32 v179, v179
	v_pk_mul_f32 v[182:183], v[182:183], v[184:185]
	v_add_f32_e32 v179, 1.0, v179
	v_rcp_f32_e32 v187, v179
	s_nop 0
	v_pk_mul_f32 v[184:185], v[170:171], v[186:187]
	v_cvt_pk_bf16_f32 v170, v172, v173
	v_cvt_pk_bf16_f32 v171, v182, v183
	v_cvt_pk_bf16_f32 v172, v180, v181
	v_cvt_pk_bf16_f32 v173, v184, v185
	global_store_dwordx4 v[130:131], v[170:173], off offset:256
	v_lshl_add_u64 v[130:131], v[128:129], 0, v[150:151]
	s_nop 1
	v_mov_b32_e32 v170, v237
	v_fmamk_f32 v170, v170, 0x3a800000, v175
	v_rsq_f32_e32 v180, v170
	s_nop 0
	v_pk_mul_f32 v[172:173], v[112:113], v[180:181] op_sel_hi:[1,0]
	s_nop 0
	v_mul_f32_e32 v179, 0xbfb8aa3b, v172
	v_exp_f32_e32 v179, v179
	v_pk_mul_f32 v[184:185], v[104:105], v[180:181] op_sel_hi:[1,0]
	v_pk_mul_f32 v[170:171], v[114:115], v[180:181] op_sel_hi:[1,0]
	v_pk_mul_f32 v[182:183], v[106:107], v[180:181] op_sel_hi:[1,0]
	v_add_f32_e32 v179, 1.0, v179
	v_rcp_f32_e32 v186, v179
	v_mul_f32_e32 v179, 0xbfb8aa3b, v184
	v_exp_f32_e32 v179, v179
	s_nop 0
	v_add_f32_e32 v179, 1.0, v179
	v_rcp_f32_e32 v188, v179
	v_mul_f32_e32 v179, 0xbfb8aa3b, v173
	v_exp_f32_e32 v179, v179
	s_nop 0
	v_add_f32_e32 v179, 1.0, v179
	v_rcp_f32_e32 v187, v179
	v_mul_f32_e32 v179, 0xbfb8aa3b, v185
	v_exp_f32_e32 v179, v179
	v_pk_mul_f32 v[172:173], v[172:173], v[186:187]
	v_add_f32_e32 v179, 1.0, v179
	v_rcp_f32_e32 v189, v179
	v_mul_f32_e32 v179, 0xbfb8aa3b, v170
	v_exp_f32_e32 v179, v179
	v_pk_mul_f32 v[184:185], v[184:185], v[188:189]
	v_add_f32_e32 v179, 1.0, v179
	v_rcp_f32_e32 v186, v179
	v_mul_f32_e32 v179, 0xbfb8aa3b, v182
	v_exp_f32_e32 v179, v179
	s_nop 0
	v_add_f32_e32 v179, 1.0, v179
	v_rcp_f32_e32 v188, v179
	v_mul_f32_e32 v179, 0xbfb8aa3b, v171
	v_exp_f32_e32 v179, v179
	s_nop 0
	v_add_f32_e32 v179, 1.0, v179
	v_rcp_f32_e32 v187, v179
	s_nop 0
	v_pk_mul_f32 v[186:187], v[170:171], v[186:187]
	v_mul_f32_e32 v170, 0xbfb8aa3b, v183
	v_exp_f32_e32 v170, v170
	v_cvt_pk_bf16_f32 v171, v186, v187
	v_add_f32_e32 v170, 1.0, v170
	v_rcp_f32_e32 v189, v170
	v_cvt_pk_bf16_f32 v170, v172, v173
	v_cvt_pk_bf16_f32 v172, v184, v185
	v_pk_mul_f32 v[182:183], v[182:183], v[188:189]
	s_nop 0
	v_cvt_pk_bf16_f32 v173, v182, v183
	global_store_dwordx4 v[130:131], v[170:173], off
	v_pk_mul_f32 v[182:183], v[102:103], v[180:181] op_sel_hi:[1,0]
	s_nop 0
	v_pk_mul_f32 v[172:173], v[100:101], v[180:181] op_sel_hi:[1,0]
	v_pk_mul_f32 v[170:171], v[94:95], v[180:181] op_sel_hi:[1,0]
	v_mul_f32_e32 v179, 0xbfb8aa3b, v172
	v_exp_f32_e32 v179, v179
	v_pk_mul_f32 v[180:181], v[92:93], v[180:181] op_sel_hi:[1,0]
	v_add_f32_e32 v179, 1.0, v179
	v_rcp_f32_e32 v184, v179
	v_mul_f32_e32 v179, 0xbfb8aa3b, v180
	v_exp_f32_e32 v179, v179
	s_nop 0
	v_add_f32_e32 v179, 1.0, v179
	v_rcp_f32_e32 v186, v179
	v_mul_f32_e32 v179, 0xbfb8aa3b, v173
	v_exp_f32_e32 v179, v179
	s_nop 0
	v_add_f32_e32 v179, 1.0, v179
	v_rcp_f32_e32 v185, v179
	v_mul_f32_e32 v179, 0xbfb8aa3b, v181
	v_exp_f32_e32 v179, v179
	v_pk_mul_f32 v[172:173], v[172:173], v[184:185]
	v_add_f32_e32 v179, 1.0, v179
	v_rcp_f32_e32 v187, v179
	v_mul_f32_e32 v179, 0xbfb8aa3b, v182
	v_exp_f32_e32 v179, v179
	v_pk_mul_f32 v[180:181], v[180:181], v[186:187]
	v_add_f32_e32 v179, 1.0, v179
	v_rcp_f32_e32 v184, v179
	v_mul_f32_e32 v179, 0xbfb8aa3b, v170
	v_exp_f32_e32 v179, v179
	s_nop 0
	v_add_f32_e32 v179, 1.0, v179
	v_rcp_f32_e32 v186, v179
	v_mul_f32_e32 v179, 0xbfb8aa3b, v183
	v_exp_f32_e32 v179, v179
	s_nop 0
	v_add_f32_e32 v179, 1.0, v179
	v_rcp_f32_e32 v185, v179
	v_mul_f32_e32 v179, 0xbfb8aa3b, v171
	v_exp_f32_e32 v179, v179
	v_pk_mul_f32 v[182:183], v[182:183], v[184:185]
	v_add_f32_e32 v179, 1.0, v179
	v_rcp_f32_e32 v187, v179
	s_nop 0
	v_pk_mul_f32 v[184:185], v[170:171], v[186:187]
	v_cvt_pk_bf16_f32 v170, v172, v173
	v_cvt_pk_bf16_f32 v171, v182, v183
	v_cvt_pk_bf16_f32 v172, v180, v181
	v_cvt_pk_bf16_f32 v173, v184, v185
	global_store_dwordx4 v[130:131], v[170:173], off offset:256
	v_lshl_add_u64 v[130:131], v[128:129], 0, v[152:153]
	s_nop 1
	v_mov_b32_e32 v170, v238
	v_fmamk_f32 v170, v170, 0x3a800000, v175
	v_rsq_f32_e32 v180, v170
	s_nop 0
	v_pk_mul_f32 v[172:173], v[96:97], v[180:181] op_sel_hi:[1,0]
	s_nop 0
	v_mul_f32_e32 v179, 0xbfb8aa3b, v172
	v_exp_f32_e32 v179, v179
	v_pk_mul_f32 v[184:185], v[88:89], v[180:181] op_sel_hi:[1,0]
; DI unsigned pk2(float a, float b) { f32x2 v = {a, b}; bf2_t r = __builtin_convertvector(v, bf2_t); return __builtin_bit_cast(unsigned, r); }
; DI float sigm(float x) { return __builtin_amdgcn_rcpf(1.f + __expf(-x)); }
; DI float silu_(float x) { return x * __builtin_amdgcn_rcpf(1.f + __expf(-x)); }
; template <int ACT>
; DI void epi_bf16(const f32x4 (&acc)[2][2][4][2], bf16_t* O, const int ldc, int wr, int wc, int fr, int fq, const float* ssrow = nullptr) {
;     ...
;             bf16_t* rowp = O + (size_t)(ai * HALF + wr * 64 + m * 16 + fr) * ldc + wc * 32 + 8 * fq;
;             const float rsc = ssrow ? __builtin_amdgcn_rsqf(ssrow[ai * HALF + wr * 64 + m * 16 + fr] * (1.f / 1024.f) + EPS_) : 1.f;
; #pragma unroll
;             for (int bj = 0; bj < 2; ++bj) {
;                 f32x4 v0 = acc[ai][bj][m][0] * rsc, v1 = acc[ai][bj][m][1] * rsc;
;                 if (ACT == 1) {
; #pragma unroll
;                     for (int j = 0; j < 4; ++j) { v0[j] = silu_(v0[j]); v1[j] = silu_(v1[j]); } }
;                 if (ACT == 2) {
; #pragma unroll
;                     for (int j = 0; j < 4; ++j) { v0[j] = sigm(v0[j]); v1[j] = sigm(v1[j]); } }
;                 u32x4 w; w[0] = pk2(v0[0], v0[1]); w[1] = pk2(v0[2], v0[3]); w[2] = pk2(v1[0], v1[1]); w[3] = pk2(v1[2], v1[3]);
;                 *(u32x4*)(rowp + bj * HALF) = w;
	v_pk_mul_f32 v[170:171], v[98:99], v[180:181] op_sel_hi:[1,0]
	v_pk_mul_f32 v[182:183], v[90:91], v[180:181] op_sel_hi:[1,0]
	v_add_f32_e32 v179, 1.0, v179
	v_rcp_f32_e32 v186, v179
	v_mul_f32_e32 v179, 0xbfb8aa3b, v184
	v_exp_f32_e32 v179, v179
	s_nop 0
	v_add_f32_e32 v179, 1.0, v179
	v_rcp_f32_e32 v188, v179
	v_mul_f32_e32 v179, 0xbfb8aa3b, v173
	v_exp_f32_e32 v179, v179
	s_nop 0
	v_add_f32_e32 v179, 1.0, v179
	v_rcp_f32_e32 v187, v179
	v_mul_f32_e32 v179, 0xbfb8aa3b, v185
	v_exp_f32_e32 v179, v179
	v_pk_mul_f32 v[172:173], v[172:173], v[186:187]
	v_add_f32_e32 v179, 1.0, v179
	v_rcp_f32_e32 v189, v179
	v_mul_f32_e32 v179, 0xbfb8aa3b, v170
	v_exp_f32_e32 v179, v179
	v_pk_mul_f32 v[184:185], v[184:185], v[188:189]
	v_add_f32_e32 v179, 1.0, v179
	v_rcp_f32_e32 v186, v179
	v_mul_f32_e32 v179, 0xbfb8aa3b, v182
	v_exp_f32_e32 v179, v179
	s_nop 0
	v_add_f32_e32 v179, 1.0, v179
	v_rcp_f32_e32 v188, v179
	v_mul_f32_e32 v179, 0xbfb8aa3b, v171
	v_exp_f32_e32 v179, v179
	s_nop 0
	v_add_f32_e32 v179, 1.0, v179
	v_rcp_f32_e32 v187, v179
	s_nop 0
	v_pk_mul_f32 v[186:187], v[170:171], v[186:187]
	v_mul_f32_e32 v170, 0xbfb8aa3b, v183
	v_exp_f32_e32 v170, v170
	v_cvt_pk_bf16_f32 v171, v186, v187
	v_add_f32_e32 v170, 1.0, v170
	v_rcp_f32_e32 v189, v170
	v_cvt_pk_bf16_f32 v170, v172, v173
	v_cvt_pk_bf16_f32 v172, v184, v185
	v_pk_mul_f32 v[182:183], v[182:183], v[188:189]
	s_nop 0
	v_cvt_pk_bf16_f32 v173, v182, v183
	global_store_dwordx4 v[130:131], v[170:173], off
	v_pk_mul_f32 v[182:183], v[86:87], v[180:181] op_sel_hi:[1,0]
	s_nop 0
	v_pk_mul_f32 v[172:173], v[84:85], v[180:181] op_sel_hi:[1,0]
	v_pk_mul_f32 v[170:171], v[78:79], v[180:181] op_sel_hi:[1,0]
	v_mul_f32_e32 v179, 0xbfb8aa3b, v172
	v_exp_f32_e32 v179, v179
	v_pk_mul_f32 v[180:181], v[76:77], v[180:181] op_sel_hi:[1,0]
	v_add_f32_e32 v179, 1.0, v179
	v_rcp_f32_e32 v184, v179
	v_mul_f32_e32 v179, 0xbfb8aa3b, v180
	v_exp_f32_e32 v179, v179
	s_nop 0
	v_add_f32_e32 v179, 1.0, v179
	v_rcp_f32_e32 v186, v179
	v_mul_f32_e32 v179, 0xbfb8aa3b, v173
	v_exp_f32_e32 v179, v179
	s_nop 0
	v_add_f32_e32 v179, 1.0, v179
	v_rcp_f32_e32 v185, v179
	v_mul_f32_e32 v179, 0xbfb8aa3b, v181
	v_exp_f32_e32 v179, v179
	v_pk_mul_f32 v[172:173], v[172:173], v[184:185]
	v_add_f32_e32 v179, 1.0, v179
	v_rcp_f32_e32 v187, v179
	v_mul_f32_e32 v179, 0xbfb8aa3b, v182
	v_exp_f32_e32 v179, v179
	v_pk_mul_f32 v[180:181], v[180:181], v[186:187]
	v_add_f32_e32 v179, 1.0, v179
	v_rcp_f32_e32 v184, v179
	v_mul_f32_e32 v179, 0xbfb8aa3b, v170
	v_exp_f32_e32 v179, v179
	s_nop 0
	v_add_f32_e32 v179, 1.0, v179
	v_rcp_f32_e32 v186, v179
	v_mul_f32_e32 v179, 0xbfb8aa3b, v183
	v_exp_f32_e32 v179, v179
	s_nop 0
	v_add_f32_e32 v179, 1.0, v179
	v_rcp_f32_e32 v185, v179
	v_mul_f32_e32 v179, 0xbfb8aa3b, v171
	v_exp_f32_e32 v179, v179
	v_pk_mul_f32 v[182:183], v[182:183], v[184:185]
	v_add_f32_e32 v179, 1.0, v179
	v_rcp_f32_e32 v187, v179
	s_nop 0
	v_pk_mul_f32 v[184:185], v[170:171], v[186:187]
	v_cvt_pk_bf16_f32 v170, v172, v173
	v_cvt_pk_bf16_f32 v171, v182, v183
	v_cvt_pk_bf16_f32 v172, v180, v181
	v_cvt_pk_bf16_f32 v173, v184, v185
	global_store_dwordx4 v[130:131], v[170:173], off offset:256
	v_lshl_add_u64 v[130:131], v[128:129], 0, v[154:155]
	s_nop 1
	v_mov_b32_e32 v170, v239
	v_fmamk_f32 v170, v170, 0x3a800000, v175
	v_rsq_f32_e32 v180, v170
	s_nop 0
	v_pk_mul_f32 v[172:173], v[80:81], v[180:181] op_sel_hi:[1,0]
	s_nop 0
	v_mul_f32_e32 v179, 0xbfb8aa3b, v172
	v_exp_f32_e32 v179, v179
	v_pk_mul_f32 v[184:185], v[72:73], v[180:181] op_sel_hi:[1,0]
	v_pk_mul_f32 v[170:171], v[82:83], v[180:181] op_sel_hi:[1,0]
	v_pk_mul_f32 v[182:183], v[74:75], v[180:181] op_sel_hi:[1,0]
	v_add_f32_e32 v179, 1.0, v179
	v_rcp_f32_e32 v186, v179
	v_mul_f32_e32 v179, 0xbfb8aa3b, v184
	v_exp_f32_e32 v179, v179
	s_nop 0
	v_add_f32_e32 v179, 1.0, v179
	v_rcp_f32_e32 v188, v179
	v_mul_f32_e32 v179, 0xbfb8aa3b, v173
	v_exp_f32_e32 v179, v179
	s_nop 0
	v_add_f32_e32 v179, 1.0, v179
	v_rcp_f32_e32 v187, v179
	v_mul_f32_e32 v179, 0xbfb8aa3b, v185
	v_exp_f32_e32 v179, v179
	v_pk_mul_f32 v[172:173], v[172:173], v[186:187]
	v_add_f32_e32 v179, 1.0, v179
	v_rcp_f32_e32 v189, v179
	v_mul_f32_e32 v179, 0xbfb8aa3b, v170
	v_exp_f32_e32 v179, v179
	v_pk_mul_f32 v[184:185], v[184:185], v[188:189]
	v_add_f32_e32 v179, 1.0, v179
	v_rcp_f32_e32 v186, v179
	v_mul_f32_e32 v179, 0xbfb8aa3b, v182
	v_exp_f32_e32 v179, v179
	s_nop 0
	v_add_f32_e32 v179, 1.0, v179
	v_rcp_f32_e32 v188, v179
	v_mul_f32_e32 v179, 0xbfb8aa3b, v171
	v_exp_f32_e32 v179, v179
	s_nop 0
	v_add_f32_e32 v179, 1.0, v179
	v_rcp_f32_e32 v187, v179
	s_nop 0
	v_pk_mul_f32 v[186:187], v[170:171], v[186:187]
	v_mul_f32_e32 v170, 0xbfb8aa3b, v183
	v_exp_f32_e32 v170, v170
	v_cvt_pk_bf16_f32 v171, v186, v187
	v_add_f32_e32 v170, 1.0, v170
	v_rcp_f32_e32 v189, v170
	v_cvt_pk_bf16_f32 v170, v172, v173
	v_cvt_pk_bf16_f32 v172, v184, v185
	v_pk_mul_f32 v[182:183], v[182:183], v[188:189]
	s_nop 0
	v_cvt_pk_bf16_f32 v173, v182, v183
	global_store_dwordx4 v[130:131], v[170:173], off
	v_pk_mul_f32 v[182:183], v[70:71], v[180:181] op_sel_hi:[1,0]
	s_nop 0
	v_pk_mul_f32 v[172:173], v[68:69], v[180:181] op_sel_hi:[1,0]
	v_pk_mul_f32 v[170:171], v[66:67], v[180:181] op_sel_hi:[1,0]
	v_mul_f32_e32 v179, 0xbfb8aa3b, v172
	v_exp_f32_e32 v179, v179
	v_pk_mul_f32 v[180:181], v[64:65], v[180:181] op_sel_hi:[1,0]
	v_add_f32_e32 v179, 1.0, v179
	v_rcp_f32_e32 v184, v179
	v_mul_f32_e32 v179, 0xbfb8aa3b, v180
	v_exp_f32_e32 v179, v179
	s_nop 0
	v_add_f32_e32 v179, 1.0, v179
	v_rcp_f32_e32 v186, v179
	v_mul_f32_e32 v179, 0xbfb8aa3b, v173
	v_exp_f32_e32 v179, v179
	s_nop 0
	v_add_f32_e32 v179, 1.0, v179
	v_rcp_f32_e32 v185, v179
; DI unsigned pk2(float a, float b) { f32x2 v = {a, b}; bf2_t r = __builtin_convertvector(v, bf2_t); return __builtin_bit_cast(unsigned, r); }
; DI float sigm(float x) { return __builtin_amdgcn_rcpf(1.f + __expf(-x)); }
; DI float silu_(float x) { return x * __builtin_amdgcn_rcpf(1.f + __expf(-x)); }
; template <int ACT>
; DI void epi_bf16(const f32x4 (&acc)[2][2][4][2], bf16_t* O, const int ldc, int wr, int wc, int fr, int fq, const float* ssrow = nullptr) {
;     ...
;             bf16_t* rowp = O + (size_t)(ai * HALF + wr * 64 + m * 16 + fr) * ldc + wc * 32 + 8 * fq;
;             const float rsc = ssrow ? __builtin_amdgcn_rsqf(ssrow[ai * HALF + wr * 64 + m * 16 + fr] * (1.f / 1024.f) + EPS_) : 1.f;
; #pragma unroll
;             for (int bj = 0; bj < 2; ++bj) {
;                 f32x4 v0 = acc[ai][bj][m][0] * rsc, v1 = acc[ai][bj][m][1] * rsc;
;                 if (ACT == 1) {
; #pragma unroll
;                     for (int j = 0; j < 4; ++j) { v0[j] = silu_(v0[j]); v1[j] = silu_(v1[j]); } }
;                 if (ACT == 2) {
; #pragma unroll
;                     for (int j = 0; j < 4; ++j) { v0[j] = sigm(v0[j]); v1[j] = sigm(v1[j]); } }
;                 u32x4 w; w[0] = pk2(v0[0], v0[1]); w[1] = pk2(v0[2], v0[3]); w[2] = pk2(v1[0], v1[1]); w[3] = pk2(v1[2], v1[3]);
;                 *(u32x4*)(rowp + bj * HALF) = w;
	v_mul_f32_e32 v179, 0xbfb8aa3b, v181
	v_exp_f32_e32 v179, v179
	v_pk_mul_f32 v[172:173], v[172:173], v[184:185]
	v_add_f32_e32 v179, 1.0, v179
	v_rcp_f32_e32 v187, v179
	v_mul_f32_e32 v179, 0xbfb8aa3b, v182
	v_exp_f32_e32 v179, v179
	v_pk_mul_f32 v[180:181], v[180:181], v[186:187]
	v_add_f32_e32 v179, 1.0, v179
	v_rcp_f32_e32 v184, v179
	v_mul_f32_e32 v179, 0xbfb8aa3b, v170
	v_exp_f32_e32 v179, v179
	s_nop 0
	v_add_f32_e32 v179, 1.0, v179
	v_rcp_f32_e32 v186, v179
	v_mul_f32_e32 v179, 0xbfb8aa3b, v183
	v_exp_f32_e32 v179, v179
	s_nop 0
	v_add_f32_e32 v179, 1.0, v179
	v_rcp_f32_e32 v185, v179
	v_mul_f32_e32 v179, 0xbfb8aa3b, v171
	v_exp_f32_e32 v179, v179
	v_pk_mul_f32 v[182:183], v[182:183], v[184:185]
	v_add_f32_e32 v179, 1.0, v179
	v_rcp_f32_e32 v187, v179
	s_nop 0
	v_pk_mul_f32 v[184:185], v[170:171], v[186:187]
	v_cvt_pk_bf16_f32 v170, v172, v173
	v_cvt_pk_bf16_f32 v171, v182, v183
	v_cvt_pk_bf16_f32 v172, v180, v181
	v_cvt_pk_bf16_f32 v173, v184, v185
	global_store_dwordx4 v[130:131], v[170:173], off offset:256
	v_lshl_add_u64 v[130:131], v[128:129], 0, v[156:157]
	s_nop 1
	v_mov_b32_e32 v170, v240
	v_fmamk_f32 v170, v170, 0x3a800000, v175
	v_rsq_f32_e32 v180, v170
	s_nop 0
	v_pk_mul_f32 v[172:173], v[60:61], v[180:181] op_sel_hi:[1,0]
	s_nop 0
	v_mul_f32_e32 v179, 0xbfb8aa3b, v172
	v_exp_f32_e32 v179, v179
	v_pk_mul_f32 v[184:185], v[56:57], v[180:181] op_sel_hi:[1,0]
	v_pk_mul_f32 v[170:171], v[62:63], v[180:181] op_sel_hi:[1,0]
	v_pk_mul_f32 v[182:183], v[58:59], v[180:181] op_sel_hi:[1,0]
	v_add_f32_e32 v179, 1.0, v179
	v_rcp_f32_e32 v186, v179
	v_mul_f32_e32 v179, 0xbfb8aa3b, v184
	v_exp_f32_e32 v179, v179
	s_nop 0
	v_add_f32_e32 v179, 1.0, v179
	v_rcp_f32_e32 v188, v179
	v_mul_f32_e32 v179, 0xbfb8aa3b, v173
	v_exp_f32_e32 v179, v179
	s_nop 0
	v_add_f32_e32 v179, 1.0, v179
	v_rcp_f32_e32 v187, v179
	v_mul_f32_e32 v179, 0xbfb8aa3b, v185
	v_exp_f32_e32 v179, v179
	v_pk_mul_f32 v[172:173], v[172:173], v[186:187]
	v_add_f32_e32 v179, 1.0, v179
	v_rcp_f32_e32 v189, v179
	v_mul_f32_e32 v179, 0xbfb8aa3b, v170
	v_exp_f32_e32 v179, v179
	v_pk_mul_f32 v[184:185], v[184:185], v[188:189]
	v_add_f32_e32 v179, 1.0, v179
	v_rcp_f32_e32 v186, v179
	v_mul_f32_e32 v179, 0xbfb8aa3b, v182
	v_exp_f32_e32 v179, v179
	s_nop 0
	v_add_f32_e32 v179, 1.0, v179
	v_rcp_f32_e32 v188, v179
	v_mul_f32_e32 v179, 0xbfb8aa3b, v171
	v_exp_f32_e32 v179, v179
	s_nop 0
	v_add_f32_e32 v179, 1.0, v179
	v_rcp_f32_e32 v187, v179
	s_nop 0
	v_pk_mul_f32 v[186:187], v[170:171], v[186:187]
	v_mul_f32_e32 v170, 0xbfb8aa3b, v183
	v_exp_f32_e32 v170, v170
	v_cvt_pk_bf16_f32 v171, v186, v187
	v_add_f32_e32 v170, 1.0, v170
	v_rcp_f32_e32 v189, v170
	v_cvt_pk_bf16_f32 v170, v172, v173
	v_cvt_pk_bf16_f32 v172, v184, v185
	v_pk_mul_f32 v[182:183], v[182:183], v[188:189]
	s_nop 0
	v_cvt_pk_bf16_f32 v173, v182, v183
	global_store_dwordx4 v[130:131], v[170:173], off
	v_pk_mul_f32 v[182:183], v[54:55], v[180:181] op_sel_hi:[1,0]
	s_nop 0
	v_pk_mul_f32 v[172:173], v[52:53], v[180:181] op_sel_hi:[1,0]
	v_pk_mul_f32 v[170:171], v[46:47], v[180:181] op_sel_hi:[1,0]
	v_mul_f32_e32 v179, 0xbfb8aa3b, v172
	v_exp_f32_e32 v179, v179
	v_pk_mul_f32 v[180:181], v[44:45], v[180:181] op_sel_hi:[1,0]
	v_add_f32_e32 v179, 1.0, v179
	v_rcp_f32_e32 v184, v179
	v_mul_f32_e32 v179, 0xbfb8aa3b, v180
	v_exp_f32_e32 v179, v179
	s_nop 0
	v_add_f32_e32 v179, 1.0, v179
	v_rcp_f32_e32 v186, v179
	v_mul_f32_e32 v179, 0xbfb8aa3b, v173
	v_exp_f32_e32 v179, v179
	s_nop 0
	v_add_f32_e32 v179, 1.0, v179
	v_rcp_f32_e32 v185, v179
	v_mul_f32_e32 v179, 0xbfb8aa3b, v181
	v_exp_f32_e32 v179, v179
	v_pk_mul_f32 v[172:173], v[172:173], v[184:185]
	v_add_f32_e32 v179, 1.0, v179
	v_rcp_f32_e32 v187, v179
	v_mul_f32_e32 v179, 0xbfb8aa3b, v182
	v_exp_f32_e32 v179, v179
	v_pk_mul_f32 v[180:181], v[180:181], v[186:187]
	v_add_f32_e32 v179, 1.0, v179
	v_rcp_f32_e32 v184, v179
	v_mul_f32_e32 v179, 0xbfb8aa3b, v170
	v_exp_f32_e32 v179, v179
	s_nop 0
	v_add_f32_e32 v179, 1.0, v179
	v_rcp_f32_e32 v186, v179
	v_mul_f32_e32 v179, 0xbfb8aa3b, v183
	v_exp_f32_e32 v179, v179
	s_nop 0
	v_add_f32_e32 v179, 1.0, v179
	v_rcp_f32_e32 v185, v179
	v_mul_f32_e32 v179, 0xbfb8aa3b, v171
	v_exp_f32_e32 v179, v179
	v_pk_mul_f32 v[182:183], v[182:183], v[184:185]
	v_add_f32_e32 v179, 1.0, v179
	v_rcp_f32_e32 v187, v179
	s_nop 0
	v_pk_mul_f32 v[184:185], v[170:171], v[186:187]
	v_cvt_pk_bf16_f32 v170, v172, v173
	v_cvt_pk_bf16_f32 v171, v182, v183
	v_cvt_pk_bf16_f32 v172, v180, v181
	v_cvt_pk_bf16_f32 v173, v184, v185
	global_store_dwordx4 v[130:131], v[170:173], off offset:256
	v_lshl_add_u64 v[130:131], v[128:129], 0, v[158:159]
	s_nop 1
	v_mov_b32_e32 v170, v241
	v_fmamk_f32 v170, v170, 0x3a800000, v175
	v_rsq_f32_e32 v180, v170
	s_nop 0
	v_pk_mul_f32 v[172:173], v[48:49], v[180:181] op_sel_hi:[1,0]
	s_nop 0
	v_mul_f32_e32 v179, 0xbfb8aa3b, v172
	v_exp_f32_e32 v179, v179
	v_pk_mul_f32 v[184:185], v[40:41], v[180:181] op_sel_hi:[1,0]
	v_pk_mul_f32 v[170:171], v[50:51], v[180:181] op_sel_hi:[1,0]
	v_pk_mul_f32 v[182:183], v[42:43], v[180:181] op_sel_hi:[1,0]
	v_add_f32_e32 v179, 1.0, v179
	v_rcp_f32_e32 v186, v179
	v_mul_f32_e32 v179, 0xbfb8aa3b, v184
	v_exp_f32_e32 v179, v179
	s_nop 0
	v_add_f32_e32 v179, 1.0, v179
	v_rcp_f32_e32 v188, v179
	v_mul_f32_e32 v179, 0xbfb8aa3b, v173
	v_exp_f32_e32 v179, v179
	s_nop 0
	v_add_f32_e32 v179, 1.0, v179
	v_rcp_f32_e32 v187, v179
	v_mul_f32_e32 v179, 0xbfb8aa3b, v185
	v_exp_f32_e32 v179, v179
	v_pk_mul_f32 v[172:173], v[172:173], v[186:187]
	v_add_f32_e32 v179, 1.0, v179
	v_rcp_f32_e32 v189, v179
	v_mul_f32_e32 v179, 0xbfb8aa3b, v170
	v_exp_f32_e32 v179, v179
	v_pk_mul_f32 v[184:185], v[184:185], v[188:189]
; DI unsigned pk2(float a, float b) { f32x2 v = {a, b}; bf2_t r = __builtin_convertvector(v, bf2_t); return __builtin_bit_cast(unsigned, r); }
; DI float sigm(float x) { return __builtin_amdgcn_rcpf(1.f + __expf(-x)); }
; DI float silu_(float x) { return x * __builtin_amdgcn_rcpf(1.f + __expf(-x)); }
; template <int ACT>
; DI void epi_bf16(const f32x4 (&acc)[2][2][4][2], bf16_t* O, const int ldc, int wr, int wc, int fr, int fq, const float* ssrow = nullptr) {
;     ...
;             bf16_t* rowp = O + (size_t)(ai * HALF + wr * 64 + m * 16 + fr) * ldc + wc * 32 + 8 * fq;
;             const float rsc = ssrow ? __builtin_amdgcn_rsqf(ssrow[ai * HALF + wr * 64 + m * 16 + fr] * (1.f / 1024.f) + EPS_) : 1.f;
; #pragma unroll
;             for (int bj = 0; bj < 2; ++bj) {
;                 f32x4 v0 = acc[ai][bj][m][0] * rsc, v1 = acc[ai][bj][m][1] * rsc;
;                 if (ACT == 1) {
; #pragma unroll
;                     for (int j = 0; j < 4; ++j) { v0[j] = silu_(v0[j]); v1[j] = silu_(v1[j]); } }
;                 if (ACT == 2) {
; #pragma unroll
;                     for (int j = 0; j < 4; ++j) { v0[j] = sigm(v0[j]); v1[j] = sigm(v1[j]); } }
;                 u32x4 w; w[0] = pk2(v0[0], v0[1]); w[1] = pk2(v0[2], v0[3]); w[2] = pk2(v1[0], v1[1]); w[3] = pk2(v1[2], v1[3]);
;                 *(u32x4*)(rowp + bj * HALF) = w;
	v_add_f32_e32 v179, 1.0, v179
	v_rcp_f32_e32 v186, v179
	v_mul_f32_e32 v179, 0xbfb8aa3b, v182
	v_exp_f32_e32 v179, v179
	s_nop 0
	v_add_f32_e32 v179, 1.0, v179
	v_rcp_f32_e32 v188, v179
	v_mul_f32_e32 v179, 0xbfb8aa3b, v171
	v_exp_f32_e32 v179, v179
	s_nop 0
	v_add_f32_e32 v179, 1.0, v179
	v_rcp_f32_e32 v187, v179
	s_nop 0
	v_pk_mul_f32 v[186:187], v[170:171], v[186:187]
	v_mul_f32_e32 v170, 0xbfb8aa3b, v183
	v_exp_f32_e32 v170, v170
	v_cvt_pk_bf16_f32 v171, v186, v187
	v_add_f32_e32 v170, 1.0, v170
	v_rcp_f32_e32 v189, v170
	v_cvt_pk_bf16_f32 v170, v172, v173
	v_cvt_pk_bf16_f32 v172, v184, v185
	v_pk_mul_f32 v[182:183], v[182:183], v[188:189]
	s_nop 0
	v_cvt_pk_bf16_f32 v173, v182, v183
	global_store_dwordx4 v[130:131], v[170:173], off
	v_pk_mul_f32 v[182:183], v[38:39], v[180:181] op_sel_hi:[1,0]
	s_nop 0
	v_pk_mul_f32 v[172:173], v[36:37], v[180:181] op_sel_hi:[1,0]
	v_pk_mul_f32 v[170:171], v[30:31], v[180:181] op_sel_hi:[1,0]
	v_mul_f32_e32 v179, 0xbfb8aa3b, v172
	v_exp_f32_e32 v179, v179
	v_pk_mul_f32 v[180:181], v[28:29], v[180:181] op_sel_hi:[1,0]
	v_add_f32_e32 v179, 1.0, v179
	v_rcp_f32_e32 v184, v179
	v_mul_f32_e32 v179, 0xbfb8aa3b, v180
	v_exp_f32_e32 v179, v179
	s_nop 0
	v_add_f32_e32 v179, 1.0, v179
	v_rcp_f32_e32 v186, v179
	v_mul_f32_e32 v179, 0xbfb8aa3b, v173
	v_exp_f32_e32 v179, v179
	s_nop 0
	v_add_f32_e32 v179, 1.0, v179
	v_rcp_f32_e32 v185, v179
	v_mul_f32_e32 v179, 0xbfb8aa3b, v181
	v_exp_f32_e32 v179, v179
	v_pk_mul_f32 v[172:173], v[172:173], v[184:185]
	v_add_f32_e32 v179, 1.0, v179
	v_rcp_f32_e32 v187, v179
	v_mul_f32_e32 v179, 0xbfb8aa3b, v182
	v_exp_f32_e32 v179, v179
	v_pk_mul_f32 v[180:181], v[180:181], v[186:187]
	v_add_f32_e32 v179, 1.0, v179
	v_rcp_f32_e32 v184, v179
	v_mul_f32_e32 v179, 0xbfb8aa3b, v170
	v_exp_f32_e32 v179, v179
	s_nop 0
	v_add_f32_e32 v179, 1.0, v179
	v_rcp_f32_e32 v186, v179
	v_mul_f32_e32 v179, 0xbfb8aa3b, v183
	v_exp_f32_e32 v179, v179
	s_nop 0
	v_add_f32_e32 v179, 1.0, v179
	v_rcp_f32_e32 v185, v179
	v_mul_f32_e32 v179, 0xbfb8aa3b, v171
	v_exp_f32_e32 v179, v179
	v_pk_mul_f32 v[182:183], v[182:183], v[184:185]
	v_add_f32_e32 v179, 1.0, v179
	v_rcp_f32_e32 v187, v179
	s_nop 0
	v_pk_mul_f32 v[184:185], v[170:171], v[186:187]
	v_cvt_pk_bf16_f32 v170, v172, v173
	v_cvt_pk_bf16_f32 v171, v182, v183
	v_cvt_pk_bf16_f32 v172, v180, v181
	v_cvt_pk_bf16_f32 v173, v184, v185
	global_store_dwordx4 v[130:131], v[170:173], off offset:256
	v_lshl_add_u64 v[130:131], v[128:129], 0, v[160:161]
	s_nop 1
	v_mov_b32_e32 v170, v242
	v_fmamk_f32 v170, v170, 0x3a800000, v175
	v_rsq_f32_e32 v180, v170
	s_nop 0
	v_pk_mul_f32 v[172:173], v[32:33], v[180:181] op_sel_hi:[1,0]
	s_nop 0
	v_mul_f32_e32 v179, 0xbfb8aa3b, v172
	v_exp_f32_e32 v179, v179
	v_pk_mul_f32 v[184:185], v[24:25], v[180:181] op_sel_hi:[1,0]
	v_pk_mul_f32 v[170:171], v[34:35], v[180:181] op_sel_hi:[1,0]
	v_pk_mul_f32 v[182:183], v[26:27], v[180:181] op_sel_hi:[1,0]
	v_add_f32_e32 v179, 1.0, v179
	v_rcp_f32_e32 v186, v179
	v_mul_f32_e32 v179, 0xbfb8aa3b, v184
	v_exp_f32_e32 v179, v179
	s_nop 0
	v_add_f32_e32 v179, 1.0, v179
	v_rcp_f32_e32 v188, v179
	v_mul_f32_e32 v179, 0xbfb8aa3b, v173
	v_exp_f32_e32 v179, v179
	s_nop 0
	v_add_f32_e32 v179, 1.0, v179
	v_rcp_f32_e32 v187, v179
	v_mul_f32_e32 v179, 0xbfb8aa3b, v185
	v_exp_f32_e32 v179, v179
	v_pk_mul_f32 v[172:173], v[172:173], v[186:187]
	v_add_f32_e32 v179, 1.0, v179
	v_rcp_f32_e32 v189, v179
	v_mul_f32_e32 v179, 0xbfb8aa3b, v170
	v_exp_f32_e32 v179, v179
	v_pk_mul_f32 v[184:185], v[184:185], v[188:189]
	v_add_f32_e32 v179, 1.0, v179
	v_rcp_f32_e32 v186, v179
	v_mul_f32_e32 v179, 0xbfb8aa3b, v182
	v_exp_f32_e32 v179, v179
	s_nop 0
	v_add_f32_e32 v179, 1.0, v179
	v_rcp_f32_e32 v188, v179
	v_mul_f32_e32 v179, 0xbfb8aa3b, v171
	v_exp_f32_e32 v179, v179
	s_nop 0
	v_add_f32_e32 v179, 1.0, v179
	v_rcp_f32_e32 v187, v179
	s_nop 0
	v_pk_mul_f32 v[186:187], v[170:171], v[186:187]
	v_mul_f32_e32 v170, 0xbfb8aa3b, v183
	v_exp_f32_e32 v170, v170
	v_cvt_pk_bf16_f32 v171, v186, v187
	v_add_f32_e32 v170, 1.0, v170
	v_rcp_f32_e32 v189, v170
	v_cvt_pk_bf16_f32 v170, v172, v173
	v_cvt_pk_bf16_f32 v172, v184, v185
	v_pk_mul_f32 v[182:183], v[182:183], v[188:189]
	s_nop 0
	v_cvt_pk_bf16_f32 v173, v182, v183
	global_store_dwordx4 v[130:131], v[170:173], off
	v_pk_mul_f32 v[182:183], v[22:23], v[180:181] op_sel_hi:[1,0]
	s_nop 0
	v_pk_mul_f32 v[172:173], v[20:21], v[180:181] op_sel_hi:[1,0]
	v_pk_mul_f32 v[170:171], v[14:15], v[180:181] op_sel_hi:[1,0]
	v_mul_f32_e32 v179, 0xbfb8aa3b, v172
	v_exp_f32_e32 v179, v179
	v_pk_mul_f32 v[180:181], v[12:13], v[180:181] op_sel_hi:[1,0]
	v_add_f32_e32 v179, 1.0, v179
	v_rcp_f32_e32 v184, v179
	v_mul_f32_e32 v179, 0xbfb8aa3b, v180
; DI unsigned pk2(float a, float b) { f32x2 v = {a, b}; bf2_t r = __builtin_convertvector(v, bf2_t); return __builtin_bit_cast(unsigned, r); }
; DI float sigm(float x) { return __builtin_amdgcn_rcpf(1.f + __expf(-x)); }
; DI float silu_(float x) { return x * __builtin_amdgcn_rcpf(1.f + __expf(-x)); }
; template <int ACT>
; DI void epi_bf16(const f32x4 (&acc)[2][2][4][2], bf16_t* O, const int ldc, int wr, int wc, int fr, int fq, const float* ssrow = nullptr) {
;     ...
;             bf16_t* rowp = O + (size_t)(ai * HALF + wr * 64 + m * 16 + fr) * ldc + wc * 32 + 8 * fq;
;             const float rsc = ssrow ? __builtin_amdgcn_rsqf(ssrow[ai * HALF + wr * 64 + m * 16 + fr] * (1.f / 1024.f) + EPS_) : 1.f;
; #pragma unroll
;             for (int bj = 0; bj < 2; ++bj) {
;                 f32x4 v0 = acc[ai][bj][m][0] * rsc, v1 = acc[ai][bj][m][1] * rsc;
;                 if (ACT == 1) {
; #pragma unroll
;                     for (int j = 0; j < 4; ++j) { v0[j] = silu_(v0[j]); v1[j] = silu_(v1[j]); } }
;                 if (ACT == 2) {
; #pragma unroll
;                     for (int j = 0; j < 4; ++j) { v0[j] = sigm(v0[j]); v1[j] = sigm(v1[j]); } }
;                 u32x4 w; w[0] = pk2(v0[0], v0[1]); w[1] = pk2(v0[2], v0[3]); w[2] = pk2(v1[0], v1[1]); w[3] = pk2(v1[2], v1[3]);
;                 *(u32x4*)(rowp + bj * HALF) = w;
	v_exp_f32_e32 v179, v179
	s_nop 0
	v_add_f32_e32 v179, 1.0, v179
	v_rcp_f32_e32 v186, v179
	v_mul_f32_e32 v179, 0xbfb8aa3b, v173
	v_exp_f32_e32 v179, v179
	s_nop 0
	v_add_f32_e32 v179, 1.0, v179
	v_rcp_f32_e32 v185, v179
	v_mul_f32_e32 v179, 0xbfb8aa3b, v181
	v_exp_f32_e32 v179, v179
	v_pk_mul_f32 v[172:173], v[172:173], v[184:185]
	v_add_f32_e32 v179, 1.0, v179
	v_rcp_f32_e32 v187, v179
	v_mul_f32_e32 v179, 0xbfb8aa3b, v182
	v_exp_f32_e32 v179, v179
	v_pk_mul_f32 v[180:181], v[180:181], v[186:187]
	v_add_f32_e32 v179, 1.0, v179
	v_rcp_f32_e32 v184, v179
	v_mul_f32_e32 v179, 0xbfb8aa3b, v170
	v_exp_f32_e32 v179, v179
	s_nop 0
	v_add_f32_e32 v179, 1.0, v179
	v_rcp_f32_e32 v186, v179
	v_mul_f32_e32 v179, 0xbfb8aa3b, v183
	v_exp_f32_e32 v179, v179
	s_nop 0
	v_add_f32_e32 v179, 1.0, v179
	v_rcp_f32_e32 v185, v179
	v_mul_f32_e32 v179, 0xbfb8aa3b, v171
	v_exp_f32_e32 v179, v179
	v_pk_mul_f32 v[182:183], v[182:183], v[184:185]
	v_add_f32_e32 v179, 1.0, v179
	v_rcp_f32_e32 v187, v179
	s_nop 0
	v_pk_mul_f32 v[184:185], v[170:171], v[186:187]
	v_cvt_pk_bf16_f32 v170, v172, v173
	v_cvt_pk_bf16_f32 v171, v182, v183
	v_cvt_pk_bf16_f32 v172, v180, v181
	v_cvt_pk_bf16_f32 v173, v184, v185
	global_store_dwordx4 v[130:131], v[170:173], off offset:256
	s_nop 1
	v_mov_b32_e32 v130, v243
	v_fmamk_f32 v130, v130, 0x3a800000, v175
	v_rsq_f32_e32 v170, v130
	v_lshl_add_u64 v[172:173], v[128:129], 0, v[162:163]
	v_pk_mul_f32 v[130:131], v[16:17], v[170:171] op_sel_hi:[1,0]
	v_pk_mul_f32 v[128:129], v[18:19], v[170:171] op_sel_hi:[1,0]
	v_pk_mul_f32 v[180:181], v[10:11], v[170:171] op_sel_hi:[1,0]
	v_pk_mul_f32 v[182:183], v[8:9], v[170:171] op_sel_hi:[1,0]
	v_mul_f32_e32 v171, 0xbfb8aa3b, v130
	v_exp_f32_e32 v171, v171
	s_nop 0
	v_add_f32_e32 v171, 1.0, v171
	v_rcp_f32_e32 v184, v171
	v_mul_f32_e32 v171, 0xbfb8aa3b, v182
	v_exp_f32_e32 v171, v171
	s_nop 0
	v_add_f32_e32 v171, 1.0, v171
	v_rcp_f32_e32 v186, v171
	v_mul_f32_e32 v171, 0xbfb8aa3b, v131
	v_exp_f32_e32 v171, v171
	s_nop 0
	v_add_f32_e32 v171, 1.0, v171
	v_rcp_f32_e32 v185, v171
	v_mul_f32_e32 v171, 0xbfb8aa3b, v183
	v_exp_f32_e32 v171, v171
	v_pk_mul_f32 v[130:131], v[130:131], v[184:185]
	v_add_f32_e32 v171, 1.0, v171
	v_rcp_f32_e32 v187, v171
	v_mul_f32_e32 v171, 0xbfb8aa3b, v128
	v_exp_f32_e32 v171, v171
	v_pk_mul_f32 v[182:183], v[182:183], v[186:187]
	v_add_f32_e32 v171, 1.0, v171
	v_rcp_f32_e32 v184, v171
	v_mul_f32_e32 v171, 0xbfb8aa3b, v180
	v_exp_f32_e32 v171, v171
	s_nop 0
	v_add_f32_e32 v171, 1.0, v171
	v_rcp_f32_e32 v186, v171
	v_mul_f32_e32 v171, 0xbfb8aa3b, v129
	v_exp_f32_e32 v171, v171
	s_nop 0
	v_add_f32_e32 v171, 1.0, v171
	v_rcp_f32_e32 v185, v171
	s_nop 0
	v_pk_mul_f32 v[184:185], v[128:129], v[184:185]
	v_mul_f32_e32 v128, 0xbfb8aa3b, v181
	v_exp_f32_e32 v128, v128
	v_cvt_pk_bf16_f32 v129, v184, v185
	v_add_f32_e32 v128, 1.0, v128
	v_rcp_f32_e32 v187, v128
	v_cvt_pk_bf16_f32 v128, v130, v131
	v_cvt_pk_bf16_f32 v130, v182, v183
	v_pk_mul_f32 v[180:181], v[180:181], v[186:187]
	s_nop 0
	v_cvt_pk_bf16_f32 v131, v180, v181
	global_store_dwordx4 v[172:173], v[128:131], off
	v_pk_mul_f32 v[172:173], v[6:7], v[170:171] op_sel_hi:[1,0]
	s_nop 0
	v_pk_mul_f32 v[130:131], v[4:5], v[170:171] op_sel_hi:[1,0]
	v_pk_mul_f32 v[128:129], v[2:3], v[170:171] op_sel_hi:[1,0]
	v_mul_f32_e32 v179, 0xbfb8aa3b, v130
	v_exp_f32_e32 v179, v179
	v_pk_mul_f32 v[170:171], v[0:1], v[170:171] op_sel_hi:[1,0]
	v_add_f32_e32 v179, 1.0, v179
	v_rcp_f32_e32 v180, v179
	v_mul_f32_e32 v179, 0xbfb8aa3b, v170
	v_exp_f32_e32 v179, v179
	s_nop 0
	v_add_f32_e32 v179, 1.0, v179
	v_rcp_f32_e32 v182, v179
	v_mul_f32_e32 v179, 0xbfb8aa3b, v131
	v_exp_f32_e32 v179, v179
	s_nop 0
	v_add_f32_e32 v179, 1.0, v179
	v_rcp_f32_e32 v181, v179
	v_mul_f32_e32 v179, 0xbfb8aa3b, v171
	v_exp_f32_e32 v179, v179
	v_pk_mul_f32 v[130:131], v[130:131], v[180:181]
	v_add_f32_e32 v179, 1.0, v179
	v_rcp_f32_e32 v183, v179
	s_nop 0
	v_pk_mul_f32 v[180:181], v[170:171], v[182:183]
	v_mul_f32_e32 v171, 0xbfb8aa3b, v128
	v_exp_f32_e32 v171, v171
	v_mul_f32_e32 v170, 0xbfb8aa3b, v172
	v_exp_f32_e32 v170, v170
	v_add_f32_e32 v171, 1.0, v171
	v_rcp_f32_e32 v182, v171
	v_mul_f32_e32 v171, 0xbfb8aa3b, v173
	v_exp_f32_e32 v171, v171
	v_add_f32_e32 v170, 1.0, v170
	v_rcp_f32_e32 v170, v170
	v_add_f32_e32 v171, 1.0, v171
	v_rcp_f32_e32 v171, v171
	s_nop 0
	v_pk_mul_f32 v[172:173], v[172:173], v[170:171]
	v_mul_f32_e32 v170, 0xbfb8aa3b, v129
	v_exp_f32_e32 v170, v170
	s_nop 0
	v_add_f32_e32 v170, 1.0, v170
	v_rcp_f32_e32 v183, v170
	s_nop 0
	v_pk_mul_f32 v[170:171], v[128:129], v[182:183]
	v_cvt_pk_bf16_f32 v128, v130, v131
	v_cvt_pk_bf16_f32 v129, v172, v173
	v_cvt_pk_bf16_f32 v130, v180, v181

; #define G_STAGE(bufoff, gbase, voff) do { _Pragma("unroll") for (int _i = 0; _i < 2; ++_i) \
;         __builtin_amdgcn_global_load_lds((const unsigned*)((const char*)(gbase) + (voff)[_i]), (LAS unsigned*)(lds + (bufoff) + ldsw + _i * 8192), 16, 0, 0); } while (0)
; #define G_WAIT_V(n) asm volatile("s_waitcnt vmcnt(" #n ")" ::: "memory")
; #define G_BAR __builtin_amdgcn_s_barrier()
; template <bool PERM, class Dec, class Epi>
; DI void gemm_phase(LAS unsigned char* lds, const int nM, const int nN, const int K, const int lda, const int ldb, const Dec& dec, const Epi& epi, const int vb, const int panel = -1) {
;     ...
;     for (int i = 0; i < 2; ++i) { int R, C; stage_rc(tid * 16 + i * 8192, R, C); const int Rb = PERM ? ((R & ~31) + perm32(R & 31)) : R;
;         voffA[i] = (unsigned)(R * lda + C) * 2u; voffB[i] = (unsigned)(Rb * ldb + C) * 2u; }
;     const size_t kstep = (size_t)(BK * 2);
;     const size_t hstepA = (size_t)HALF * lda * 2, hstepB = (size_t)HALF * ldb * 2;
;     const unsigned ldsw = (unsigned)wid * 1024u;
;     const int aoff = lds_byte(wr * 64 + fr, fq * 8), boff = lds_byte(wc * 32 + fr, fq * 8);
;     ...
;     int cpm, cpn, npm, npn, ui = 0;
;     if (panel >= 0) { cpm = panel; cpn = 0; } else if (!unit_next(0, nM, nN, vb, cpm, cpn)) return;
;     f32x4 acc[2][2][4][2];
; #pragma unroll
;     for (int a = 0; a < 2; ++a)
; #pragma unroll
;         for (int b = 0; b < 2; ++b)
; #pragma unroll
;             for (int m = 0; m < 4; ++m)
; #pragma unroll
;                 for (int n = 0; n < 2; ++n) acc[a][b][m][n] = (f32x4){0.f, 0.f, 0.f, 0.f};
;     bf16x8 At[4][2], B0[2][2], B1[2][2];
;     const char* cA; const char* cB; dec(cpm, cpn, cA, cB);
;     G_STAGE(G_SB(0, 0), cB, voffB); G_STAGE(G_SA(0, 0), cA, voffA); G_STAGE(G_SB(0, 1), cB + hstepB, voffB); G_STAGE(G_SA(0, 1), cA + hstepA, voffA);
;     if (wr == 1) G_BAR;
;     G_WAIT_V(4); G_BAR;
;     G_STAGE(G_SB(1, 0), cB + kstep, voffB); G_STAGE(G_SA(1, 0), cA + kstep, voffA); G_STAGE(G_SB(1, 1), cB + hstepB + kstep, voffB);
;     G_WAIT_V(6); G_BAR;
.LBB0_914:
	s_lshl_b32 s1, s1, 5
	s_and_b32 s1, s1, 0x60
	s_add_i32 m0, s39, 0x18000
	v_lshl_add_u64 v[6:7], v[6:7], 0, s[2:3]
	s_lshl_b32 s12, s0, 13
	s_lshl_b32 s13, s1, 7
	s_waitcnt vmcnt(4)
	s_barrier
	global_load_lds_dwordx4 v[6:7], off
	v_lshl_add_u64 v[4:5], v[4:5], 0, s[2:3]
	s_add_i32 m0, s39, 0x1a000
	s_add_i32 s43, s39, 0x8000
	s_add_i32 s44, s39, 0xa000
	global_load_lds_dwordx4 v[4:5], off
	v_lshl_add_u64 v[2:3], v[2:3], 0, s[2:3]
	s_mov_b32 m0, s43
	s_add_u32 s10, s22, 0x60080
	global_load_lds_dwordx4 v[2:3], off
	v_lshl_add_u64 v[0:1], v[0:1], 0, s[2:3]
	s_mov_b32 m0, s44
	s_addc_u32 s11, s23, 0
	global_load_lds_dwordx4 v[0:1], off
	s_add_i32 m0, s39, 0x1c000
	v_lshl_add_u64 v[0:1], s[10:11], 0, v[128:129]
	global_load_lds_dwordx4 v[0:1], off
	v_lshl_add_u64 v[0:1], s[10:11], 0, v[132:133]
	s_add_i32 m0, s39, 0x1e000
	v_lshlrev_b32_e32 v4, 2, v9
	global_load_lds_dwordx4 v[0:1], off
	v_and_b32_e32 v0, 15, v9
	v_bfe_u32 v1, v9, 4, 2
	v_lshl_or_b32 v143, s0, 6, v0
	v_lshlrev_b32_e32 v2, 4, v1
	v_lshl_or_b32 v0, v0, 6, v2
	v_lshlrev_b32_e32 v2, 2, v143
	v_and_b32_e32 v3, 32, v2
	v_and_b32_e32 v4, 32, v4
	v_bitop3_b32 v3, v0, s12, v3 bitop3:0xde
	v_bitop3_b32 v144, v0, s13, v4 bitop3:0xde
	v_lshl_or_b32 v134, v1, 2, s1
	v_cmp_eq_u32_e64 s[0:1], 0, v1
	v_lshrrev_b32_e32 v1, 1, v8
	v_mul_lo_u32 v0, v10, s30
	v_mad_u64_u32 v[0:1], s[10:11], v1, s31, v[0:1]
	v_or_b32_e32 v0, v0, v11
	v_add_lshl_u32 v0, v0, v12, 1
	v_mov_b32_e32 v1, v129
	v_lshl_add_u64 v[136:137], v[0:1], 0, s[4:5]
	v_lshrrev_b32_e32 v1, 1, v13
	v_mul_lo_u32 v0, v14, s30
	v_mad_u64_u32 v[0:1], s[10:11], v1, s31, v[0:1]
	s_waitcnt vmcnt(0)
	v_or_b32_e32 v0, v0, v15
	v_or_b32_e32 v146, 16, v143
	v_or_b32_e32 v148, 32, v143
	v_or_b32_e32 v150, 48, v143
	v_add_u32_e32 v152, 0x80, v143
	v_add_u32_e32 v154, 0x90, v143
	v_add_u32_e32 v156, 0xa0, v143
	v_add_u32_e32 v158, 0xb0, v143
	v_add_lshl_u32 v0, v0, v16, 1
	v_mov_b32_e32 v1, v129
	s_mov_b32 s24, 0
	v_add_u32_e32 v145, s35, v2
	v_lshl_add_u32 v147, v146, 2, s35
	v_lshl_add_u32 v149, v148, 2, s35
	v_lshl_add_u32 v151, v150, 2, s35
	v_lshl_add_u32 v153, v152, 2, s35
	v_lshl_add_u32 v155, v154, 2, s35
	v_lshl_add_u32 v157, v156, 2, s35
	v_lshl_add_u32 v159, v158, 2, s35
	v_lshl_add_u64 v[138:139], v[0:1], 0, s[4:5]
	v_add_u32_e32 v160, 0, v3
	s_barrier
	s_branch .LBB0_916

; #define G_STAGE(bufoff, gbase, voff) do { _Pragma("unroll") for (int _i = 0; _i < 2; ++_i) \
;         __builtin_amdgcn_global_load_lds((const unsigned*)((const char*)(gbase) + (voff)[_i]), (LAS unsigned*)(lds + (bufoff) + ldsw + _i * 8192), 16, 0, 0); } while (0)
; #define G_LDA(dst, b, h) do { _Pragma("unroll") for (int m = 0; m < 4; ++m) _Pragma("unroll") for (int k = 0; k < 2; ++k) dst[m][k] = *(const LAS bf16x8*)(lds + G_SA(b, h) + aoff + m * 2048 + k * 1024); } while (0)
; #define G_LDB(dst, b, h) do { _Pragma("unroll") for (int n = 0; n < 2; ++n) _Pragma("unroll") for (int k = 0; k < 2; ++k) dst[n][k] = *(const LAS bf16x8*)(lds + G_SB(b, h) + boff + n * 2048 + k * 1024); } while (0)
; #define G_MMA(ai, bj, At, Bt) do { __builtin_amdgcn_s_setprio(1); _Pragma("unroll") for (int m = 0; m < 4; ++m) _Pragma("unroll") for (int n = 0; n < 2; ++n) _Pragma("unroll") for (int k = 0; k < 2; ++k) \
;         acc[ai][bj][m][n] = __builtin_amdgcn_mfma_f32_16x16x32_bf16(Bt[n][k], At[m][k], acc[ai][bj][m][n], 0, 0, 0); __builtin_amdgcn_s_setprio(0); } while (0)
; #define G_WAIT_L(n) asm volatile("s_waitcnt lgkmcnt(" #n ")" ::: "memory")
; template <bool PERM, class Dec, class Epi>
; DI void gemm_phase(LAS unsigned char* lds, const int nM, const int nN, const int K, const int lda, const int ldb, const Dec& dec, const Epi& epi, const int vb, const int panel = -1) {
;     ...
;         for (int t = 0; t < nt; t += 2) {
;             const bool last = (t == nt - 2);
;             const char* a1 = cA + (size_t)(t + 1) * kstep;
;             const char* a2 = last ? nA : cA + (size_t)(t + 2) * kstep; const char* b2 = last ? nB : cB + (size_t)(t + 2) * kstep;
;             const char* a3 = a2 + kstep; const char* b3 = b2 + kstep;
;             G_LDB(B0, 0, 0); G_SCHED; G_LDA(At, 0, 0); G_STAGE(G_SA(1, 1), a1 + hstepA, voffA);
;             G_WAIT_L(8); G_BAR; G_WAIT_L(0); G_MMA(0, 0, At, B0); G_BAR; G_SCHED;
;             G_LDB(B1, 0, 1); G_STAGE(G_SB(0, 0), b2, voffB);
;             G_BAR; G_WAIT_L(0); G_MMA(0, 1, At, B1); G_BAR;
;     ...
; #pragma unroll
;         for (int a = 0; a < 2; ++a)
; #pragma unroll
;             for (int b = 0; b < 2; ++b)
; #pragma unroll
;                 for (int m = 0; m < 4; ++m)
; #pragma unroll
;                     for (int n = 0; n < 2; ++n) acc[a][b][m][n] = (f32x4){0.f, 0.f, 0.f, 0.f};
;         cpm = npm; cpn = npn; cA = nA; cB = nB; ++ui;
.LBB0_923:
	s_add_u32 s50, s22, 0x100
	v_mov_b32_e32 v0, 0
	s_addc_u32 s51, s23, 0
	s_mov_b32 s52, -2
	s_waitcnt lgkmcnt(0)
	v_mov_b32_e32 v1, v0
	v_mov_b32_e32 v2, v0
	v_mov_b32_e32 v3, v0
	v_mov_b32_e32 v4, v0
	v_mov_b32_e32 v5, v0
	v_mov_b32_e32 v6, v0
	v_mov_b32_e32 v7, v0
	v_mov_b32_e32 v16, v0
	v_mov_b32_e32 v17, v0
	v_mov_b32_e32 v18, v0
	v_mov_b32_e32 v19, v0
	v_mov_b32_e32 v20, v0
	v_mov_b32_e32 v21, v0
	v_mov_b32_e32 v22, v0
	v_mov_b32_e32 v23, v0
	v_mov_b32_e32 v32, v0
	v_mov_b32_e32 v33, v0
	v_mov_b32_e32 v34, v0
	v_mov_b32_e32 v35, v0
	v_mov_b32_e32 v36, v0
	v_mov_b32_e32 v37, v0
	v_mov_b32_e32 v38, v0
	v_mov_b32_e32 v39, v0
	v_mov_b32_e32 v48, v0
	v_mov_b32_e32 v49, v0
	v_mov_b32_e32 v50, v0
	v_mov_b32_e32 v51, v0
	v_mov_b32_e32 v52, v0
	v_mov_b32_e32 v53, v0
	v_mov_b32_e32 v54, v0
	v_mov_b32_e32 v55, v0
	v_mov_b32_e32 v8, v0
	v_mov_b32_e32 v9, v0
	v_mov_b32_e32 v10, v0
	v_mov_b32_e32 v11, v0
	v_mov_b32_e32 v12, v0
	v_mov_b32_e32 v13, v0
	v_mov_b32_e32 v14, v0
	v_mov_b32_e32 v15, v0
	v_mov_b32_e32 v24, v0
	v_mov_b32_e32 v25, v0
	v_mov_b32_e32 v26, v0
	v_mov_b32_e32 v27, v0
	v_mov_b32_e32 v28, v0
	v_mov_b32_e32 v29, v0
	v_mov_b32_e32 v30, v0
	v_mov_b32_e32 v31, v0
	v_mov_b32_e32 v40, v0
	v_mov_b32_e32 v41, v0
	v_mov_b32_e32 v42, v0
	v_mov_b32_e32 v43, v0
	v_mov_b32_e32 v44, v0
	v_mov_b32_e32 v45, v0
	v_mov_b32_e32 v46, v0
	v_mov_b32_e32 v47, v0
	v_mov_b32_e32 v56, v0
	v_mov_b32_e32 v57, v0
	v_mov_b32_e32 v58, v0
	v_mov_b32_e32 v59, v0
	v_mov_b32_e32 v60, v0
	v_mov_b32_e32 v61, v0
	v_mov_b32_e32 v62, v0
	v_mov_b32_e32 v63, v0
	v_mov_b32_e32 v64, v0
	v_mov_b32_e32 v65, v0
	v_mov_b32_e32 v66, v0
	v_mov_b32_e32 v67, v0
	v_mov_b32_e32 v68, v0
	v_mov_b32_e32 v69, v0
	v_mov_b32_e32 v70, v0
	v_mov_b32_e32 v71, v0
	v_mov_b32_e32 v80, v0
	v_mov_b32_e32 v81, v0
	v_mov_b32_e32 v82, v0
	v_mov_b32_e32 v83, v0
	v_mov_b32_e32 v84, v0
	v_mov_b32_e32 v85, v0
	v_mov_b32_e32 v86, v0
	v_mov_b32_e32 v87, v0
	v_mov_b32_e32 v96, v0
	v_mov_b32_e32 v97, v0
	v_mov_b32_e32 v98, v0
	v_mov_b32_e32 v99, v0
	v_mov_b32_e32 v100, v0
	v_mov_b32_e32 v101, v0
	v_mov_b32_e32 v102, v0
	v_mov_b32_e32 v103, v0
	v_mov_b32_e32 v112, v0
	v_mov_b32_e32 v113, v0
	v_mov_b32_e32 v114, v0
	v_mov_b32_e32 v115, v0
	v_mov_b32_e32 v116, v0
	v_mov_b32_e32 v117, v0
	v_mov_b32_e32 v118, v0
	v_mov_b32_e32 v119, v0
	v_mov_b32_e32 v72, v0
	v_mov_b32_e32 v73, v0
	v_mov_b32_e32 v74, v0
	v_mov_b32_e32 v75, v0
	v_mov_b32_e32 v76, v0
	v_mov_b32_e32 v77, v0
	v_mov_b32_e32 v78, v0
	v_mov_b32_e32 v79, v0
	v_mov_b32_e32 v88, v0
	v_mov_b32_e32 v89, v0
	v_mov_b32_e32 v90, v0
	v_mov_b32_e32 v91, v0
	v_mov_b32_e32 v92, v0
	v_mov_b32_e32 v93, v0
	v_mov_b32_e32 v94, v0
	v_mov_b32_e32 v95, v0
	v_mov_b32_e32 v104, v0
	v_mov_b32_e32 v105, v0
	v_mov_b32_e32 v106, v0
	v_mov_b32_e32 v107, v0
	v_mov_b32_e32 v108, v0
	v_mov_b32_e32 v109, v0
	v_mov_b32_e32 v110, v0
	v_mov_b32_e32 v111, v0
	v_mov_b32_e32 v120, v0
	v_mov_b32_e32 v121, v0
	v_mov_b32_e32 v122, v0
	v_mov_b32_e32 v123, v0
	v_mov_b32_e32 v124, v0
	v_mov_b32_e32 v125, v0
	v_mov_b32_e32 v126, v0
	v_mov_b32_e32 v127, v0
.LBB0_924:
	s_add_u32 s22, s18, 0x100
	s_addc_u32 s23, s19, 0
	s_add_i32 s53, 0, 0x10000
	v_add_u32_e32 v140, s53, v144
	ds_read_b128 v[162:165], v140
	ds_read_b128 v[166:169], v140 offset:1024
	ds_read_b128 v[170:173], v140 offset:2048
	ds_read_b128 v[176:179], v140 offset:3072
	s_cmp_eq_u32 s52, 20
	s_cselect_b32 s29, s13, s23
	s_cselect_b32 s28, s12, s22
	s_cselect_b32 s25, s17, s51
	s_cselect_b32 s24, s16, s50
	v_lshl_add_u64 v[140:141], s[18:19], 0, v[136:137]
	s_add_i32 m0, s39, 0xc000
	ds_read_b128 v[180:183], v160
	ds_read_b128 v[184:187], v160 offset:1024
	ds_read_b128 v[188:191], v160 offset:2048
	ds_read_b128 v[194:197], v160 offset:3072
	ds_read_b128 v[198:201], v160 offset:4096
	ds_read_b128 v[202:205], v160 offset:5120
	ds_read_b128 v[206:209], v160 offset:6144
	ds_read_b128 v[210:213], v160 offset:7168
	global_load_lds_dwordx4 v[140:141], off
	v_lshl_add_u64 v[140:141], s[18:19], 0, v[138:139]
	s_add_i32 m0, s39, 0xe000
	s_nop 0
	global_load_lds_dwordx4 v[140:141], off
	s_waitcnt lgkmcnt(8)
	s_barrier
	s_waitcnt lgkmcnt(0)
	s_setprio 1
	s_waitcnt lgkmcnt(0)
	v_mfma_f32_16x16x32_bf16 v[124:127], v[162:165], v[180:183], v[124:127]
	v_mfma_f32_16x16x32_bf16 v[120:123], v[170:173], v[180:183], v[120:123]
	v_mfma_f32_16x16x32_bf16 v[108:111], v[162:165], v[188:191], v[108:111]
	v_mfma_f32_16x16x32_bf16 v[104:107], v[170:173], v[188:191], v[104:107]
	v_mfma_f32_16x16x32_bf16 v[92:95], v[162:165], v[198:201], v[92:95]
	v_mfma_f32_16x16x32_bf16 v[88:91], v[170:173], v[198:201], v[88:91]
	v_mfma_f32_16x16x32_bf16 v[76:79], v[162:165], v[206:209], v[76:79]
	v_mfma_f32_16x16x32_bf16 v[72:75], v[170:173], v[206:209], v[72:75]
	v_mfma_f32_16x16x32_bf16 v[124:127], v[166:169], v[184:187], v[124:127]
	v_mfma_f32_16x16x32_bf16 v[120:123], v[176:179], v[184:187], v[120:123]
	v_mfma_f32_16x16x32_bf16 v[108:111], v[166:169], v[194:197], v[108:111]
	v_mfma_f32_16x16x32_bf16 v[104:107], v[176:179], v[194:197], v[104:107]
	v_mfma_f32_16x16x32_bf16 v[92:95], v[166:169], v[202:205], v[92:95]
	v_mfma_f32_16x16x32_bf16 v[88:91], v[176:179], v[202:205], v[88:91]
	v_mfma_f32_16x16x32_bf16 v[76:79], v[166:169], v[210:213], v[76:79]
	v_mfma_f32_16x16x32_bf16 v[72:75], v[176:179], v[210:213], v[72:75]
	s_setprio 0
	s_barrier
	s_add_i32 s54, 0, 0x14000
	v_add_u32_e32 v140, s54, v144
	s_add_i32 s18, s53, s38
	ds_read_b128 v[214:217], v140
	ds_read_b128 v[218:221], v140 offset:1024
	ds_read_b128 v[222:225], v140 offset:2048
	ds_read_b128 v[226:229], v140 offset:3072
	v_lshl_add_u64 v[140:141], s[24:25], 0, v[128:129]
	s_mov_b32 m0, s18
	v_lshl_add_u64 v[230:231], s[24:25], 0, v[132:133]
	global_load_lds_dwordx4 v[140:141], off
	s_add_i32 m0, s18, 0x2000
	s_nop 0
	global_load_lds_dwordx4 v[230:231], off
	s_barrier
; #define G_STAGE(bufoff, gbase, voff) do { _Pragma("unroll") for (int _i = 0; _i < 2; ++_i) \
;         __builtin_amdgcn_global_load_lds((const unsigned*)((const char*)(gbase) + (voff)[_i]), (LAS unsigned*)(lds + (bufoff) + ldsw + _i * 8192), 16, 0, 0); } while (0)
; #define G_LDA(dst, b, h) do { _Pragma("unroll") for (int m = 0; m < 4; ++m) _Pragma("unroll") for (int k = 0; k < 2; ++k) dst[m][k] = *(const LAS bf16x8*)(lds + G_SA(b, h) + aoff + m * 2048 + k * 1024); } while (0)
; #define G_LDB(dst, b, h) do { _Pragma("unroll") for (int n = 0; n < 2; ++n) _Pragma("unroll") for (int k = 0; k < 2; ++k) dst[n][k] = *(const LAS bf16x8*)(lds + G_SB(b, h) + boff + n * 2048 + k * 1024); } while (0)
; #define G_MMA(ai, bj, At, Bt) do { __builtin_amdgcn_s_setprio(1); _Pragma("unroll") for (int m = 0; m < 4; ++m) _Pragma("unroll") for (int n = 0; n < 2; ++n) _Pragma("unroll") for (int k = 0; k < 2; ++k) \
;         acc[ai][bj][m][n] = __builtin_amdgcn_mfma_f32_16x16x32_bf16(Bt[n][k], At[m][k], acc[ai][bj][m][n], 0, 0, 0); __builtin_amdgcn_s_setprio(0); } while (0)
; #define G_WAIT_V(n) asm volatile("s_waitcnt vmcnt(" #n ")" ::: "memory")
; #define G_WAIT_L(n) asm volatile("s_waitcnt lgkmcnt(" #n ")" ::: "memory")
; #define G_BAR __builtin_amdgcn_s_barrier()
; #define G_SCHED __builtin_amdgcn_sched_barrier(0)
; template <bool PERM, class Dec, class Epi>
; DI void gemm_phase(LAS unsigned char* lds, const int nM, const int nN, const int K, const int lda, const int ldb, const Dec& dec, const Epi& epi, const int vb, const int panel = -1) {
;     ...
;             G_BAR; G_WAIT_L(0); G_MMA(0, 1, At, B1); G_BAR;
;             G_LDA(At, 0, 1); G_STAGE(G_SA(0, 0), a2, voffA);
;             G_BAR; G_WAIT_L(0); G_MMA(1, 0, At, B0); G_BAR; G_SCHED;
;             G_STAGE(G_SB(0, 1), b2 + hstepB, voffB);
;             G_WAIT_V(6); G_BAR; G_MMA(1, 1, At, B1); G_BAR;
;             G_LDB(B0, 1, 0); G_SCHED; G_LDA(At, 1, 0); G_STAGE(G_SA(0, 1), a2 + hstepA, voffA);
;             G_WAIT_L(8); G_BAR; G_WAIT_L(0); G_MMA(0, 0, At, B0); G_BAR; G_SCHED;
	s_waitcnt lgkmcnt(0)
	s_setprio 1
	s_waitcnt lgkmcnt(0)
	v_mfma_f32_16x16x32_bf16 v[116:119], v[214:217], v[180:183], v[116:119]
	v_mfma_f32_16x16x32_bf16 v[112:115], v[222:225], v[180:183], v[112:115]
	v_mfma_f32_16x16x32_bf16 v[100:103], v[214:217], v[188:191], v[100:103]
	v_mfma_f32_16x16x32_bf16 v[96:99], v[222:225], v[188:191], v[96:99]
	v_mfma_f32_16x16x32_bf16 v[84:87], v[214:217], v[198:201], v[84:87]
	v_mfma_f32_16x16x32_bf16 v[80:83], v[222:225], v[198:201], v[80:83]
	v_mfma_f32_16x16x32_bf16 v[68:71], v[214:217], v[206:209], v[68:71]
	v_mfma_f32_16x16x32_bf16 v[64:67], v[222:225], v[206:209], v[64:67]
	v_mfma_f32_16x16x32_bf16 v[116:119], v[218:221], v[184:187], v[116:119]
	v_mfma_f32_16x16x32_bf16 v[112:115], v[226:229], v[184:187], v[112:115]
	v_mfma_f32_16x16x32_bf16 v[100:103], v[218:221], v[194:197], v[100:103]
	v_mfma_f32_16x16x32_bf16 v[96:99], v[226:229], v[194:197], v[96:99]
	v_mfma_f32_16x16x32_bf16 v[84:87], v[218:221], v[202:205], v[84:87]
	v_mfma_f32_16x16x32_bf16 v[80:83], v[226:229], v[202:205], v[80:83]
	v_mfma_f32_16x16x32_bf16 v[68:71], v[218:221], v[210:213], v[68:71]
	v_mfma_f32_16x16x32_bf16 v[64:67], v[226:229], v[210:213], v[64:67]
	s_setprio 0
	s_mov_b32 m0, s39
	v_lshl_add_u64 v[232:233], s[28:29], 0, v[128:129]
	s_barrier
	ds_read_b128 v[180:183], v160 offset:16384
	ds_read_b128 v[184:187], v160 offset:17408
	ds_read_b128 v[188:191], v160 offset:18432
	ds_read_b128 v[194:197], v160 offset:19456
	ds_read_b128 v[198:201], v160 offset:20480
	ds_read_b128 v[202:205], v160 offset:21504
	ds_read_b128 v[206:209], v160 offset:22528
	ds_read_b128 v[210:213], v160 offset:23552
	global_load_lds_dwordx4 v[232:233], off
	v_lshl_add_u64 v[234:235], s[28:29], 0, v[132:133]
	s_mov_b32 m0, s40
	s_nop 0
	global_load_lds_dwordx4 v[234:235], off
	s_barrier
	s_waitcnt lgkmcnt(0)
	s_setprio 1
	s_waitcnt lgkmcnt(0)
	v_mfma_f32_16x16x32_bf16 v[60:63], v[162:165], v[180:183], v[60:63]
	v_mfma_f32_16x16x32_bf16 v[56:59], v[170:173], v[180:183], v[56:59]
	v_mfma_f32_16x16x32_bf16 v[44:47], v[162:165], v[188:191], v[44:47]
	v_mfma_f32_16x16x32_bf16 v[40:43], v[170:173], v[188:191], v[40:43]
	v_mfma_f32_16x16x32_bf16 v[28:31], v[162:165], v[198:201], v[28:31]
	v_mfma_f32_16x16x32_bf16 v[24:27], v[170:173], v[198:201], v[24:27]
	v_mfma_f32_16x16x32_bf16 v[12:15], v[162:165], v[206:209], v[12:15]
	v_mfma_f32_16x16x32_bf16 v[8:11], v[170:173], v[206:209], v[8:11]
	v_mfma_f32_16x16x32_bf16 v[60:63], v[166:169], v[184:187], v[60:63]
	v_mfma_f32_16x16x32_bf16 v[56:59], v[176:179], v[184:187], v[56:59]
	v_mfma_f32_16x16x32_bf16 v[44:47], v[166:169], v[194:197], v[44:47]
	v_mfma_f32_16x16x32_bf16 v[40:43], v[176:179], v[194:197], v[40:43]
	v_mfma_f32_16x16x32_bf16 v[28:31], v[166:169], v[202:205], v[28:31]
	v_mfma_f32_16x16x32_bf16 v[24:27], v[176:179], v[202:205], v[24:27]
	v_mfma_f32_16x16x32_bf16 v[12:15], v[166:169], v[210:213], v[12:15]
	v_mfma_f32_16x16x32_bf16 v[8:11], v[176:179], v[210:213], v[8:11]
	s_setprio 0
	s_barrier
	s_add_u32 s18, s24, 0x60000
	s_addc_u32 s19, s25, 0
	s_add_i32 s53, s54, s38
	v_lshl_add_u64 v[162:163], s[18:19], 0, v[128:129]
	s_mov_b32 m0, s53
	s_nop 0
	global_load_lds_dwordx4 v[162:163], off
	v_lshl_add_u64 v[162:163], s[18:19], 0, v[132:133]
	s_add_i32 m0, s53, 0x2000
	s_nop 0
	global_load_lds_dwordx4 v[162:163], off
	s_cmp_eq_u32 s52, -2
	s_cbranch_scc1 .Lfi4_924
	s_waitcnt vmcnt(6)
.Lfi4_924:
	s_barrier
	s_setprio 1
	v_mfma_f32_16x16x32_bf16 v[52:55], v[214:217], v[180:183], v[52:55]
	v_mfma_f32_16x16x32_bf16 v[48:51], v[222:225], v[180:183], v[48:51]
	v_mfma_f32_16x16x32_bf16 v[36:39], v[214:217], v[188:191], v[36:39]
	v_mfma_f32_16x16x32_bf16 v[32:35], v[222:225], v[188:191], v[32:35]
	v_mfma_f32_16x16x32_bf16 v[20:23], v[214:217], v[198:201], v[20:23]
	v_mfma_f32_16x16x32_bf16 v[16:19], v[222:225], v[198:201], v[16:19]
	v_mfma_f32_16x16x32_bf16 v[4:7], v[214:217], v[206:209], v[4:7]
	v_mfma_f32_16x16x32_bf16 v[0:3], v[222:225], v[206:209], v[0:3]
	v_mfma_f32_16x16x32_bf16 v[52:55], v[218:221], v[184:187], v[52:55]
	v_mfma_f32_16x16x32_bf16 v[48:51], v[226:229], v[184:187], v[48:51]
	v_mfma_f32_16x16x32_bf16 v[36:39], v[218:221], v[194:197], v[36:39]
	v_mfma_f32_16x16x32_bf16 v[32:35], v[226:229], v[194:197], v[32:35]
	v_mfma_f32_16x16x32_bf16 v[20:23], v[218:221], v[202:205], v[20:23]
	v_mfma_f32_16x16x32_bf16 v[16:19], v[226:229], v[202:205], v[16:19]
	v_mfma_f32_16x16x32_bf16 v[4:7], v[218:221], v[210:213], v[4:7]
	v_mfma_f32_16x16x32_bf16 v[0:3], v[226:229], v[210:213], v[0:3]
	s_setprio 0
	s_add_i32 s53, 0, 0x18000
	v_add_u32_e32 v161, s53, v144
	s_barrier
	ds_read_b128 v[162:165], v161
	ds_read_b128 v[166:169], v161 offset:1024
	ds_read_b128 v[170:173], v161 offset:2048
	ds_read_b128 v[176:179], v161 offset:3072
	s_add_u32 s18, s28, 0x60000
	s_addc_u32 s19, s29, 0
	s_mov_b32 m0, s41
	v_lshl_add_u64 v[214:215], s[18:19], 0, v[128:129]
	ds_read_b128 v[180:183], v160 offset:32768
	ds_read_b128 v[184:187], v160 offset:33792
	ds_read_b128 v[188:191], v160 offset:34816
	ds_read_b128 v[194:197], v160 offset:35840
	ds_read_b128 v[198:201], v160 offset:36864
	ds_read_b128 v[202:205], v160 offset:37888
	ds_read_b128 v[206:209], v160 offset:38912
	ds_read_b128 v[210:213], v160 offset:39936
	global_load_lds_dwordx4 v[214:215], off
	v_lshl_add_u64 v[214:215], s[18:19], 0, v[132:133]
	s_mov_b32 m0, s42
	s_nop 0
	global_load_lds_dwordx4 v[214:215], off
	s_waitcnt lgkmcnt(8)
	s_barrier
; #define G_STAGE(bufoff, gbase, voff) do { _Pragma("unroll") for (int _i = 0; _i < 2; ++_i) \
;         __builtin_amdgcn_global_load_lds((const unsigned*)((const char*)(gbase) + (voff)[_i]), (LAS unsigned*)(lds + (bufoff) + ldsw + _i * 8192), 16, 0, 0); } while (0)
; #define G_LDA(dst, b, h) do { _Pragma("unroll") for (int m = 0; m < 4; ++m) _Pragma("unroll") for (int k = 0; k < 2; ++k) dst[m][k] = *(const LAS bf16x8*)(lds + G_SA(b, h) + aoff + m * 2048 + k * 1024); } while (0)
; #define G_LDB(dst, b, h) do { _Pragma("unroll") for (int n = 0; n < 2; ++n) _Pragma("unroll") for (int k = 0; k < 2; ++k) dst[n][k] = *(const LAS bf16x8*)(lds + G_SB(b, h) + boff + n * 2048 + k * 1024); } while (0)
; #define G_MMA(ai, bj, At, Bt) do { __builtin_amdgcn_s_setprio(1); _Pragma("unroll") for (int m = 0; m < 4; ++m) _Pragma("unroll") for (int n = 0; n < 2; ++n) _Pragma("unroll") for (int k = 0; k < 2; ++k) \
;         acc[ai][bj][m][n] = __builtin_amdgcn_mfma_f32_16x16x32_bf16(Bt[n][k], At[m][k], acc[ai][bj][m][n], 0, 0, 0); __builtin_amdgcn_s_setprio(0); } while (0)
; #define G_WAIT_V(n) asm volatile("s_waitcnt vmcnt(" #n ")" ::: "memory")
; #define G_WAIT_L(n) asm volatile("s_waitcnt lgkmcnt(" #n ")" ::: "memory")
; #define G_BAR __builtin_amdgcn_s_barrier()
; #define G_SCHED __builtin_amdgcn_sched_barrier(0)
; template <bool PERM, class Dec, class Epi>
; DI void gemm_phase(LAS unsigned char* lds, const int nM, const int nN, const int K, const int lda, const int ldb, const Dec& dec, const Epi& epi, const int vb, const int panel = -1) {
;     ...
;             G_WAIT_L(8); G_BAR; G_WAIT_L(0); G_MMA(0, 0, At, B0); G_BAR; G_SCHED;
;             G_LDB(B1, 1, 1); G_STAGE(G_SB(1, 0), b3, voffB);
;             G_BAR; G_WAIT_L(0); G_MMA(0, 1, At, B1); G_BAR;
;             G_LDA(At, 1, 1); G_STAGE(G_SA(1, 0), a3, voffA);
;             G_BAR; G_WAIT_L(0); G_MMA(1, 0, At, B0); G_BAR; G_SCHED;
;             G_STAGE(G_SB(1, 1), b3 + hstepB, voffB);
;             G_WAIT_V(6); G_BAR; G_MMA(1, 1, At, B1); G_BAR;
	s_waitcnt lgkmcnt(0)
	s_setprio 1
	s_waitcnt lgkmcnt(0)
	v_mfma_f32_16x16x32_bf16 v[124:127], v[162:165], v[180:183], v[124:127]
	v_mfma_f32_16x16x32_bf16 v[120:123], v[170:173], v[180:183], v[120:123]
	v_mfma_f32_16x16x32_bf16 v[108:111], v[162:165], v[188:191], v[108:111]
	v_mfma_f32_16x16x32_bf16 v[104:107], v[170:173], v[188:191], v[104:107]
	v_mfma_f32_16x16x32_bf16 v[92:95], v[162:165], v[198:201], v[92:95]
	v_mfma_f32_16x16x32_bf16 v[88:91], v[170:173], v[198:201], v[88:91]
	v_mfma_f32_16x16x32_bf16 v[76:79], v[162:165], v[206:209], v[76:79]
	v_mfma_f32_16x16x32_bf16 v[72:75], v[170:173], v[206:209], v[72:75]
	v_mfma_f32_16x16x32_bf16 v[124:127], v[166:169], v[184:187], v[124:127]
	v_mfma_f32_16x16x32_bf16 v[120:123], v[176:179], v[184:187], v[120:123]
	v_mfma_f32_16x16x32_bf16 v[108:111], v[166:169], v[194:197], v[108:111]
	v_mfma_f32_16x16x32_bf16 v[104:107], v[176:179], v[194:197], v[104:107]
	v_mfma_f32_16x16x32_bf16 v[92:95], v[166:169], v[202:205], v[92:95]
	v_mfma_f32_16x16x32_bf16 v[88:91], v[176:179], v[202:205], v[88:91]
	v_mfma_f32_16x16x32_bf16 v[76:79], v[166:169], v[210:213], v[76:79]
	v_mfma_f32_16x16x32_bf16 v[72:75], v[176:179], v[210:213], v[72:75]
	s_setprio 0
	s_barrier
	s_add_i32 s28, 0, 0x1c000
	s_add_i32 s18, s53, s38
	v_add_u32_e32 v161, s28, v144
	v_lshl_add_u64 v[140:141], v[140:141], 0, s[2:3]
	s_mov_b32 m0, s18
	ds_read_b128 v[214:217], v161
	ds_read_b128 v[218:221], v161 offset:1024
	ds_read_b128 v[222:225], v161 offset:2048
	ds_read_b128 v[226:229], v161 offset:3072
	global_load_lds_dwordx4 v[140:141], off
	v_lshl_add_u64 v[140:141], v[230:231], 0, s[2:3]
	s_add_i32 m0, s18, 0x2000
	s_nop 0
	global_load_lds_dwordx4 v[140:141], off
	s_cmp_lg_u32 s52, -2
	s_cbranch_scc1 .Lfi6_924
	s_waitcnt vmcnt(10)
.Lfi6_924:
	s_barrier
	s_waitcnt lgkmcnt(0)
	s_setprio 1
	s_waitcnt lgkmcnt(0)
	v_mfma_f32_16x16x32_bf16 v[116:119], v[214:217], v[180:183], v[116:119]
	v_mfma_f32_16x16x32_bf16 v[112:115], v[222:225], v[180:183], v[112:115]
	v_mfma_f32_16x16x32_bf16 v[100:103], v[214:217], v[188:191], v[100:103]
	v_mfma_f32_16x16x32_bf16 v[96:99], v[222:225], v[188:191], v[96:99]
	v_mfma_f32_16x16x32_bf16 v[84:87], v[214:217], v[198:201], v[84:87]
	v_mfma_f32_16x16x32_bf16 v[80:83], v[222:225], v[198:201], v[80:83]
	v_mfma_f32_16x16x32_bf16 v[68:71], v[214:217], v[206:209], v[68:71]
	v_mfma_f32_16x16x32_bf16 v[64:67], v[222:225], v[206:209], v[64:67]
	v_mfma_f32_16x16x32_bf16 v[116:119], v[218:221], v[184:187], v[116:119]
	v_mfma_f32_16x16x32_bf16 v[112:115], v[226:229], v[184:187], v[112:115]
	v_mfma_f32_16x16x32_bf16 v[100:103], v[218:221], v[194:197], v[100:103]
	v_mfma_f32_16x16x32_bf16 v[96:99], v[226:229], v[194:197], v[96:99]
	v_mfma_f32_16x16x32_bf16 v[84:87], v[218:221], v[202:205], v[84:87]
	v_mfma_f32_16x16x32_bf16 v[80:83], v[226:229], v[202:205], v[80:83]
	v_mfma_f32_16x16x32_bf16 v[68:71], v[218:221], v[210:213], v[68:71]
	v_mfma_f32_16x16x32_bf16 v[64:67], v[226:229], v[210:213], v[64:67]
	s_setprio 0
	s_mov_b32 m0, s43
	v_lshl_add_u64 v[140:141], v[232:233], 0, s[2:3]
	s_barrier
	ds_read_b128 v[180:183], v160 offset:49152
	ds_read_b128 v[184:187], v160 offset:50176
	ds_read_b128 v[188:191], v160 offset:51200
	ds_read_b128 v[194:197], v160 offset:52224
	ds_read_b128 v[198:201], v160 offset:53248
	ds_read_b128 v[202:205], v160 offset:54272
	ds_read_b128 v[206:209], v160 offset:55296
	ds_read_b128 v[210:213], v160 offset:56320
	global_load_lds_dwordx4 v[140:141], off
	v_lshl_add_u64 v[140:141], v[234:235], 0, s[2:3]
	s_mov_b32 m0, s44
	s_nop 0
	global_load_lds_dwordx4 v[140:141], off
	s_barrier
	s_waitcnt lgkmcnt(0)
	s_setprio 1
	s_waitcnt lgkmcnt(0)
	v_mfma_f32_16x16x32_bf16 v[60:63], v[162:165], v[180:183], v[60:63]
	v_mfma_f32_16x16x32_bf16 v[56:59], v[170:173], v[180:183], v[56:59]
	v_mfma_f32_16x16x32_bf16 v[44:47], v[162:165], v[188:191], v[44:47]
	v_mfma_f32_16x16x32_bf16 v[40:43], v[170:173], v[188:191], v[40:43]
	v_mfma_f32_16x16x32_bf16 v[28:31], v[162:165], v[198:201], v[28:31]
	v_mfma_f32_16x16x32_bf16 v[24:27], v[170:173], v[198:201], v[24:27]
	v_mfma_f32_16x16x32_bf16 v[12:15], v[162:165], v[206:209], v[12:15]
	v_mfma_f32_16x16x32_bf16 v[8:11], v[170:173], v[206:209], v[8:11]
	v_mfma_f32_16x16x32_bf16 v[60:63], v[166:169], v[184:187], v[60:63]
	v_mfma_f32_16x16x32_bf16 v[56:59], v[176:179], v[184:187], v[56:59]
	v_mfma_f32_16x16x32_bf16 v[44:47], v[166:169], v[194:197], v[44:47]
	v_mfma_f32_16x16x32_bf16 v[40:43], v[176:179], v[194:197], v[40:43]
	v_mfma_f32_16x16x32_bf16 v[28:31], v[166:169], v[202:205], v[28:31]
	v_mfma_f32_16x16x32_bf16 v[24:27], v[176:179], v[202:205], v[24:27]
	v_mfma_f32_16x16x32_bf16 v[12:15], v[166:169], v[210:213], v[12:15]
	v_mfma_f32_16x16x32_bf16 v[8:11], v[176:179], v[210:213], v[8:11]
	s_setprio 0
	s_barrier
	s_add_u32 s18, s24, 0x60080
	s_addc_u32 s19, s25, 0
	s_add_i32 s24, s28, s38
	v_lshl_add_u64 v[140:141], s[18:19], 0, v[128:129]
	s_mov_b32 m0, s24
	s_nop 0
	global_load_lds_dwordx4 v[140:141], off
	v_lshl_add_u64 v[140:141], s[18:19], 0, v[132:133]
	s_add_i32 m0, s24, 0x2000
	s_nop 0
	global_load_lds_dwordx4 v[140:141], off
	s_waitcnt vmcnt(6)
	s_barrier
; DI unsigned pk2(float a, float b) { f32x2 v = {a, b}; bf2_t r = __builtin_convertvector(v, bf2_t); return __builtin_bit_cast(unsigned, r); }
; DI float bflo(unsigned u) { return __uint_as_float(u << 16); }
; DI float bfhi(unsigned u) { return __uint_as_float(u & 0xffff0000u); }
; #define G_MMA(ai, bj, At, Bt) do { __builtin_amdgcn_s_setprio(1); _Pragma("unroll") for (int m = 0; m < 4; ++m) _Pragma("unroll") for (int n = 0; n < 2; ++n) _Pragma("unroll") for (int k = 0; k < 2; ++k) \
;         acc[ai][bj][m][n] = __builtin_amdgcn_mfma_f32_16x16x32_bf16(Bt[n][k], At[m][k], acc[ai][bj][m][n], 0, 0, 0); __builtin_amdgcn_s_setprio(0); } while (0)
; #define G_WAIT_V(n) asm volatile("s_waitcnt vmcnt(" #n ")" ::: "memory")
; #define G_BAR __builtin_amdgcn_s_barrier()
; template <bool PERM, class Dec, class Epi>
; DI void gemm_phase(LAS unsigned char* lds, const int nM, const int nN, const int K, const int lda, const int ldb, const Dec& dec, const Epi& epi, const int vb, const int panel = -1) {
;     ...
;             G_WAIT_V(6); G_BAR; G_MMA(1, 1, At, B1); G_BAR;
;         }
; __global__ void __launch_bounds__(512) hybrid_fwd(Params p) {
;     ...
;               [=](const f32x4 (&acc)[2][2][4][2], int pm, int pn, int wr, int wc, int fr, int fq) {
; #pragma unroll
;                   for (int ai = 0; ai < 2; ++ai)
; #pragma unroll
;                       for (int m = 0; m < 4; ++m) { const int rl = ai * 128 + wr * 64 + m * 16 + fr; const size_t ro = (size_t)(pm * 256 + rl) * 1024 + pn * 256 + wc * 32 + 4 * fq;
;                           float ssq = 0.f;
; #pragma unroll
;                           for (int bj = 0; bj < 2; ++bj)
; #pragma unroll
;                               for (int n = 0; n < 2; ++n) { const size_t o = ro + bj * 128 + n * 16; const u32x2 xb = *(const u32x2*)(U + o);
;                                   const f32x4 v = (f32x4){bflo(xb[0]), bfhi(xb[0]), bflo(xb[1]), bfhi(xb[1])} + acc[ai][bj][m][n];
;                                   u32x2 wv; wv[0] = pk2(v[0], v[1]); wv[1] = pk2(v[2], v[3]); *(u32x2*)(X2B + o) = wv;
;                                   ssq += v[0] * v[0] + v[1] * v[1] + v[2] * v[2] + v[3] * v[3]; }
	s_setprio 1
	v_mfma_f32_16x16x32_bf16 v[52:55], v[214:217], v[180:183], v[52:55]
	v_mfma_f32_16x16x32_bf16 v[48:51], v[222:225], v[180:183], v[48:51]
	v_mfma_f32_16x16x32_bf16 v[36:39], v[214:217], v[188:191], v[36:39]
	v_mfma_f32_16x16x32_bf16 v[32:35], v[222:225], v[188:191], v[32:35]
	v_mfma_f32_16x16x32_bf16 v[20:23], v[214:217], v[198:201], v[20:23]
	v_mfma_f32_16x16x32_bf16 v[16:19], v[222:225], v[198:201], v[16:19]
	v_mfma_f32_16x16x32_bf16 v[4:7], v[214:217], v[206:209], v[4:7]
	v_mfma_f32_16x16x32_bf16 v[0:3], v[222:225], v[206:209], v[0:3]
	v_mfma_f32_16x16x32_bf16 v[52:55], v[218:221], v[184:187], v[52:55]
	v_mfma_f32_16x16x32_bf16 v[48:51], v[226:229], v[184:187], v[48:51]
	v_mfma_f32_16x16x32_bf16 v[36:39], v[218:221], v[194:197], v[36:39]
	v_mfma_f32_16x16x32_bf16 v[32:35], v[226:229], v[194:197], v[32:35]
	v_mfma_f32_16x16x32_bf16 v[20:23], v[218:221], v[202:205], v[20:23]
	v_mfma_f32_16x16x32_bf16 v[16:19], v[226:229], v[202:205], v[16:19]
	v_mfma_f32_16x16x32_bf16 v[4:7], v[218:221], v[210:213], v[4:7]
	v_mfma_f32_16x16x32_bf16 v[0:3], v[226:229], v[210:213], v[0:3]
	s_setprio 0
	s_add_i32 s52, s52, 2
	s_add_u32 s50, s50, 0x100
	s_addc_u32 s51, s51, 0
	s_cmp_gt_u32 s52, 21
	s_mov_b64 s[18:19], s[22:23]
	s_barrier
	s_cbranch_scc0 .LBB0_924
	s_lshl_b32 s22, s49, 8
	s_lshl_b32 s18, s48, 8
	v_add_u32_e32 v162, s22, v143
	s_ashr_i32 s19, s18, 31
	v_ashrrev_i32_e32 v163, 31, v162
	v_mov_b32_e32 v141, s19
	v_or_b32_e32 v140, s18, v134
	v_lshlrev_b64 v[162:163], 10, v[162:163]
	v_lshl_add_u64 v[162:163], v[140:141], 0, v[162:163]
	v_lshlrev_b64 v[164:165], 1, v[162:163]
	v_lshl_add_u64 v[162:163], s[20:21], 0, v[164:165]
	v_or_b32_e32 v168, 32, v164
	v_mov_b32_e32 v169, v165
	v_add_u32_e32 v230, s22, v143
	v_ashrrev_i32_e32 v231, 31, v230
	v_lshlrev_b64 v[230:231], 10, v[230:231]
	v_lshl_add_u64 v[230:231], v[140:141], 0, v[230:231]
	v_lshlrev_b64 v[230:231], 1, v[230:231]
	v_lshl_add_u64 v[230:231], s[20:21], 0, v[230:231]
	global_load_dwordx2 v[194:195], v[230:231], off
	global_load_dwordx2 v[196:197], v[230:231], off offset:32
	global_load_dwordx2 v[198:199], v[230:231], off offset:256
	global_load_dwordx2 v[200:201], v[230:231], off offset:288
	v_add_u32_e32 v230, s22, v146
	v_ashrrev_i32_e32 v231, 31, v230
	v_lshlrev_b64 v[230:231], 10, v[230:231]
	v_lshl_add_u64 v[230:231], v[140:141], 0, v[230:231]
	v_lshlrev_b64 v[230:231], 1, v[230:231]
	v_lshl_add_u64 v[230:231], s[20:21], 0, v[230:231]
	global_load_dwordx2 v[202:203], v[230:231], off
	global_load_dwordx2 v[204:205], v[230:231], off offset:32
	global_load_dwordx2 v[206:207], v[230:231], off offset:256
	global_load_dwordx2 v[208:209], v[230:231], off offset:288
	v_add_u32_e32 v230, s22, v148
	v_ashrrev_i32_e32 v231, 31, v230
	v_lshlrev_b64 v[230:231], 10, v[230:231]
	v_lshl_add_u64 v[230:231], v[140:141], 0, v[230:231]
	v_lshlrev_b64 v[230:231], 1, v[230:231]
	v_lshl_add_u64 v[230:231], s[20:21], 0, v[230:231]
	global_load_dwordx2 v[210:211], v[230:231], off
	global_load_dwordx2 v[212:213], v[230:231], off offset:32
	global_load_dwordx2 v[214:215], v[230:231], off offset:256
	global_load_dwordx2 v[216:217], v[230:231], off offset:288
	v_add_u32_e32 v230, s22, v150
	v_ashrrev_i32_e32 v231, 31, v230
	v_lshlrev_b64 v[230:231], 10, v[230:231]
	v_lshl_add_u64 v[230:231], v[140:141], 0, v[230:231]
	v_lshlrev_b64 v[230:231], 1, v[230:231]
	v_lshl_add_u64 v[230:231], s[20:21], 0, v[230:231]
	global_load_dwordx2 v[218:219], v[230:231], off
	global_load_dwordx2 v[220:221], v[230:231], off offset:32
	global_load_dwordx2 v[222:223], v[230:231], off offset:256
	global_load_dwordx2 v[224:225], v[230:231], off offset:288
	s_waitcnt vmcnt(12)
	v_lshlrev_b32_e32 v226, 16, v194
	v_and_b32_e32 v227, 0xffff0000, v194
	v_lshlrev_b32_e32 v228, 16, v195
	v_and_b32_e32 v229, 0xffff0000, v195
	v_pk_add_f32 v[124:125], v[124:125], v[226:227]
	v_pk_add_f32 v[126:127], v[126:127], v[228:229]
	v_lshlrev_b32_e32 v226, 16, v196
	v_and_b32_e32 v227, 0xffff0000, v196
	v_lshlrev_b32_e32 v228, 16, v197
	v_and_b32_e32 v229, 0xffff0000, v197
	v_pk_add_f32 v[120:121], v[120:121], v[226:227]
	v_pk_add_f32 v[122:123], v[122:123], v[228:229]
	v_lshlrev_b32_e32 v226, 16, v198
	v_and_b32_e32 v227, 0xffff0000, v198
	v_lshlrev_b32_e32 v228, 16, v199
	v_and_b32_e32 v229, 0xffff0000, v199
	v_pk_add_f32 v[116:117], v[116:117], v[226:227]
	v_pk_add_f32 v[118:119], v[118:119], v[228:229]
	v_lshlrev_b32_e32 v226, 16, v200
	v_and_b32_e32 v227, 0xffff0000, v200
	v_lshlrev_b32_e32 v228, 16, v201
	v_and_b32_e32 v229, 0xffff0000, v201
	v_pk_add_f32 v[112:113], v[112:113], v[226:227]
	v_pk_add_f32 v[114:115], v[114:115], v[228:229]
	v_add_u32_e32 v230, s22, v152
	v_ashrrev_i32_e32 v231, 31, v230
	v_lshlrev_b64 v[230:231], 10, v[230:231]
	v_lshl_add_u64 v[230:231], v[140:141], 0, v[230:231]
	v_lshlrev_b64 v[230:231], 1, v[230:231]
	v_lshl_add_u64 v[230:231], s[20:21], 0, v[230:231]
	global_load_dwordx2 v[194:195], v[230:231], off
	global_load_dwordx2 v[196:197], v[230:231], off offset:32
	global_load_dwordx2 v[198:199], v[230:231], off offset:256
	global_load_dwordx2 v[200:201], v[230:231], off offset:288
	s_waitcnt vmcnt(12)
; DI unsigned pk2(float a, float b) { f32x2 v = {a, b}; bf2_t r = __builtin_convertvector(v, bf2_t); return __builtin_bit_cast(unsigned, r); }
; DI float bflo(unsigned u) { return __uint_as_float(u << 16); }
; DI float bfhi(unsigned u) { return __uint_as_float(u & 0xffff0000u); }
; __global__ void __launch_bounds__(512) hybrid_fwd(Params p) {
;     ...
;                               for (int n = 0; n < 2; ++n) { const size_t o = ro + bj * 128 + n * 16; const u32x2 xb = *(const u32x2*)(U + o);
;                                   const f32x4 v = (f32x4){bflo(xb[0]), bfhi(xb[0]), bflo(xb[1]), bfhi(xb[1])} + acc[ai][bj][m][n];
;                                   u32x2 wv; wv[0] = pk2(v[0], v[1]); wv[1] = pk2(v[2], v[3]); *(u32x2*)(X2B + o) = wv;
;                                   ssq += v[0] * v[0] + v[1] * v[1] + v[2] * v[2] + v[3] * v[3]; }
	v_lshlrev_b32_e32 v226, 16, v202
	v_and_b32_e32 v227, 0xffff0000, v202
	v_lshlrev_b32_e32 v228, 16, v203
	v_and_b32_e32 v229, 0xffff0000, v203
	v_pk_add_f32 v[108:109], v[108:109], v[226:227]
	v_pk_add_f32 v[110:111], v[110:111], v[228:229]
	v_lshlrev_b32_e32 v226, 16, v204
	v_and_b32_e32 v227, 0xffff0000, v204
	v_lshlrev_b32_e32 v228, 16, v205
	v_and_b32_e32 v229, 0xffff0000, v205
	v_pk_add_f32 v[104:105], v[104:105], v[226:227]
	v_pk_add_f32 v[106:107], v[106:107], v[228:229]
	v_lshlrev_b32_e32 v226, 16, v206
	v_and_b32_e32 v227, 0xffff0000, v206
	v_lshlrev_b32_e32 v228, 16, v207
	v_and_b32_e32 v229, 0xffff0000, v207
	v_pk_add_f32 v[100:101], v[100:101], v[226:227]
	v_pk_add_f32 v[102:103], v[102:103], v[228:229]
	v_lshlrev_b32_e32 v226, 16, v208
	v_and_b32_e32 v227, 0xffff0000, v208
	v_lshlrev_b32_e32 v228, 16, v209
	v_and_b32_e32 v229, 0xffff0000, v209
	v_pk_add_f32 v[96:97], v[96:97], v[226:227]
	v_pk_add_f32 v[98:99], v[98:99], v[228:229]
	v_add_u32_e32 v230, s22, v154
	v_ashrrev_i32_e32 v231, 31, v230
	v_lshlrev_b64 v[230:231], 10, v[230:231]
	v_lshl_add_u64 v[230:231], v[140:141], 0, v[230:231]
	v_lshlrev_b64 v[230:231], 1, v[230:231]
	v_lshl_add_u64 v[230:231], s[20:21], 0, v[230:231]
	global_load_dwordx2 v[202:203], v[230:231], off
	global_load_dwordx2 v[204:205], v[230:231], off offset:32
	global_load_dwordx2 v[206:207], v[230:231], off offset:256
	global_load_dwordx2 v[208:209], v[230:231], off offset:288
	s_waitcnt vmcnt(12)
	v_lshlrev_b32_e32 v226, 16, v210
	v_and_b32_e32 v227, 0xffff0000, v210
	v_lshlrev_b32_e32 v228, 16, v211
	v_and_b32_e32 v229, 0xffff0000, v211
	v_pk_add_f32 v[92:93], v[92:93], v[226:227]
	v_pk_add_f32 v[94:95], v[94:95], v[228:229]
	v_lshlrev_b32_e32 v226, 16, v212
	v_and_b32_e32 v227, 0xffff0000, v212
	v_lshlrev_b32_e32 v228, 16, v213
	v_and_b32_e32 v229, 0xffff0000, v213
	v_pk_add_f32 v[88:89], v[88:89], v[226:227]
	v_pk_add_f32 v[90:91], v[90:91], v[228:229]
	v_lshlrev_b32_e32 v226, 16, v214
	v_and_b32_e32 v227, 0xffff0000, v214
	v_lshlrev_b32_e32 v228, 16, v215
	v_and_b32_e32 v229, 0xffff0000, v215
	v_pk_add_f32 v[84:85], v[84:85], v[226:227]
	v_pk_add_f32 v[86:87], v[86:87], v[228:229]
	v_lshlrev_b32_e32 v226, 16, v216
	v_and_b32_e32 v227, 0xffff0000, v216
	v_lshlrev_b32_e32 v228, 16, v217
	v_and_b32_e32 v229, 0xffff0000, v217
	v_pk_add_f32 v[80:81], v[80:81], v[226:227]
	v_pk_add_f32 v[82:83], v[82:83], v[228:229]
	v_add_u32_e32 v230, s22, v156
	v_ashrrev_i32_e32 v231, 31, v230
	v_lshlrev_b64 v[230:231], 10, v[230:231]
	v_lshl_add_u64 v[230:231], v[140:141], 0, v[230:231]
	v_lshlrev_b64 v[230:231], 1, v[230:231]
	v_lshl_add_u64 v[230:231], s[20:21], 0, v[230:231]
	global_load_dwordx2 v[210:211], v[230:231], off
	global_load_dwordx2 v[212:213], v[230:231], off offset:32
	global_load_dwordx2 v[214:215], v[230:231], off offset:256
	global_load_dwordx2 v[216:217], v[230:231], off offset:288
	s_waitcnt vmcnt(12)
	v_lshlrev_b32_e32 v226, 16, v218
	v_and_b32_e32 v227, 0xffff0000, v218
	v_lshlrev_b32_e32 v228, 16, v219
	v_and_b32_e32 v229, 0xffff0000, v219
	v_pk_add_f32 v[76:77], v[76:77], v[226:227]
	v_pk_add_f32 v[78:79], v[78:79], v[228:229]
	v_lshlrev_b32_e32 v226, 16, v220
	v_and_b32_e32 v227, 0xffff0000, v220
	v_lshlrev_b32_e32 v228, 16, v221
	v_and_b32_e32 v229, 0xffff0000, v221
	v_pk_add_f32 v[72:73], v[72:73], v[226:227]
	v_pk_add_f32 v[74:75], v[74:75], v[228:229]
	v_lshlrev_b32_e32 v226, 16, v222
	v_and_b32_e32 v227, 0xffff0000, v222
	v_lshlrev_b32_e32 v228, 16, v223
	v_and_b32_e32 v229, 0xffff0000, v223
	v_pk_add_f32 v[68:69], v[68:69], v[226:227]
	v_pk_add_f32 v[70:71], v[70:71], v[228:229]
	v_lshlrev_b32_e32 v226, 16, v224
	v_and_b32_e32 v227, 0xffff0000, v224
	v_lshlrev_b32_e32 v228, 16, v225
	v_and_b32_e32 v229, 0xffff0000, v225
	v_pk_add_f32 v[64:65], v[64:65], v[226:227]
	v_pk_add_f32 v[66:67], v[66:67], v[228:229]
	v_add_u32_e32 v230, s22, v158
	v_ashrrev_i32_e32 v231, 31, v230
	v_lshlrev_b64 v[230:231], 10, v[230:231]
	v_lshl_add_u64 v[230:231], v[140:141], 0, v[230:231]
	v_lshlrev_b64 v[230:231], 1, v[230:231]
	v_lshl_add_u64 v[230:231], s[20:21], 0, v[230:231]
	global_load_dwordx2 v[218:219], v[230:231], off
	global_load_dwordx2 v[220:221], v[230:231], off offset:32
	global_load_dwordx2 v[222:223], v[230:231], off offset:256
	global_load_dwordx2 v[224:225], v[230:231], off offset:288
	s_waitcnt vmcnt(12)
	v_lshlrev_b32_e32 v226, 16, v194
	v_and_b32_e32 v227, 0xffff0000, v194
	v_lshlrev_b32_e32 v228, 16, v195
	v_and_b32_e32 v229, 0xffff0000, v195
	v_pk_add_f32 v[60:61], v[60:61], v[226:227]
	v_pk_add_f32 v[62:63], v[62:63], v[228:229]
	v_lshlrev_b32_e32 v226, 16, v196
	v_and_b32_e32 v227, 0xffff0000, v196
	v_lshlrev_b32_e32 v228, 16, v197
	v_and_b32_e32 v229, 0xffff0000, v197
	v_pk_add_f32 v[56:57], v[56:57], v[226:227]
	v_pk_add_f32 v[58:59], v[58:59], v[228:229]
	v_lshlrev_b32_e32 v226, 16, v198
	v_and_b32_e32 v227, 0xffff0000, v198
	v_lshlrev_b32_e32 v228, 16, v199
	v_and_b32_e32 v229, 0xffff0000, v199
	v_pk_add_f32 v[52:53], v[52:53], v[226:227]
	v_pk_add_f32 v[54:55], v[54:55], v[228:229]
	v_lshlrev_b32_e32 v226, 16, v200
	v_and_b32_e32 v227, 0xffff0000, v200
	v_lshlrev_b32_e32 v228, 16, v201
	v_and_b32_e32 v229, 0xffff0000, v201
	v_pk_add_f32 v[48:49], v[48:49], v[226:227]
	v_pk_add_f32 v[50:51], v[50:51], v[228:229]
	s_waitcnt vmcnt(8)
; DI unsigned pk2(float a, float b) { f32x2 v = {a, b}; bf2_t r = __builtin_convertvector(v, bf2_t); return __builtin_bit_cast(unsigned, r); }
; DI float bflo(unsigned u) { return __uint_as_float(u << 16); }
; DI float bfhi(unsigned u) { return __uint_as_float(u & 0xffff0000u); }
; __global__ void __launch_bounds__(512) hybrid_fwd(Params p) {
;     ...
;               [=](const f32x4 (&acc)[2][2][4][2], int pm, int pn, int wr, int wc, int fr, int fq) {
; #pragma unroll
;                   for (int ai = 0; ai < 2; ++ai)
; #pragma unroll
;                       for (int m = 0; m < 4; ++m) { const int rl = ai * 128 + wr * 64 + m * 16 + fr; const size_t ro = (size_t)(pm * 256 + rl) * 1024 + pn * 256 + wc * 32 + 4 * fq;
;                           float ssq = 0.f;
; #pragma unroll
;                           for (int bj = 0; bj < 2; ++bj)
; #pragma unroll
;                               for (int n = 0; n < 2; ++n) { const size_t o = ro + bj * 128 + n * 16; const u32x2 xb = *(const u32x2*)(U + o);
;                                   const f32x4 v = (f32x4){bflo(xb[0]), bfhi(xb[0]), bflo(xb[1]), bfhi(xb[1])} + acc[ai][bj][m][n];
;                                   u32x2 wv; wv[0] = pk2(v[0], v[1]); wv[1] = pk2(v[2], v[3]); *(u32x2*)(X2B + o) = wv;
;                                   ssq += v[0] * v[0] + v[1] * v[1] + v[2] * v[2] + v[3] * v[3]; }
;                           ssq += __shfl_xor(ssq, 16); ssq += __shfl_xor(ssq, 32);
;                           if (fq == 0) __hip_atomic_fetch_add((float*)(shm + 131072) + rl, ssq, __ATOMIC_RELAXED, __HIP_MEMORY_SCOPE_WORKGROUP); } }, vb, panel);
	v_lshlrev_b32_e32 v226, 16, v202
	v_and_b32_e32 v227, 0xffff0000, v202
	v_lshlrev_b32_e32 v228, 16, v203
	v_and_b32_e32 v229, 0xffff0000, v203
	v_pk_add_f32 v[44:45], v[44:45], v[226:227]
	v_pk_add_f32 v[46:47], v[46:47], v[228:229]
	v_lshlrev_b32_e32 v226, 16, v204
	v_and_b32_e32 v227, 0xffff0000, v204
	v_lshlrev_b32_e32 v228, 16, v205
	v_and_b32_e32 v229, 0xffff0000, v205
	v_pk_add_f32 v[40:41], v[40:41], v[226:227]
	v_pk_add_f32 v[42:43], v[42:43], v[228:229]
	v_lshlrev_b32_e32 v226, 16, v206
	v_and_b32_e32 v227, 0xffff0000, v206
	v_lshlrev_b32_e32 v228, 16, v207
	v_and_b32_e32 v229, 0xffff0000, v207
	v_pk_add_f32 v[36:37], v[36:37], v[226:227]
	v_pk_add_f32 v[38:39], v[38:39], v[228:229]
	v_lshlrev_b32_e32 v226, 16, v208
	v_and_b32_e32 v227, 0xffff0000, v208
	v_lshlrev_b32_e32 v228, 16, v209
	v_and_b32_e32 v229, 0xffff0000, v209
	v_pk_add_f32 v[32:33], v[32:33], v[226:227]
	v_pk_add_f32 v[34:35], v[34:35], v[228:229]
	s_waitcnt vmcnt(4)
	v_lshlrev_b32_e32 v226, 16, v210
	v_and_b32_e32 v227, 0xffff0000, v210
	v_lshlrev_b32_e32 v228, 16, v211
	v_and_b32_e32 v229, 0xffff0000, v211
	v_pk_add_f32 v[28:29], v[28:29], v[226:227]
	v_pk_add_f32 v[30:31], v[30:31], v[228:229]
	v_lshlrev_b32_e32 v226, 16, v212
	v_and_b32_e32 v227, 0xffff0000, v212
	v_lshlrev_b32_e32 v228, 16, v213
	v_and_b32_e32 v229, 0xffff0000, v213
	v_pk_add_f32 v[24:25], v[24:25], v[226:227]
	v_pk_add_f32 v[26:27], v[26:27], v[228:229]
	v_lshlrev_b32_e32 v226, 16, v214
	v_and_b32_e32 v227, 0xffff0000, v214
	v_lshlrev_b32_e32 v228, 16, v215
	v_and_b32_e32 v229, 0xffff0000, v215
	v_pk_add_f32 v[20:21], v[20:21], v[226:227]
	v_pk_add_f32 v[22:23], v[22:23], v[228:229]
	v_lshlrev_b32_e32 v226, 16, v216
	v_and_b32_e32 v227, 0xffff0000, v216
	v_lshlrev_b32_e32 v228, 16, v217
	v_and_b32_e32 v229, 0xffff0000, v217
	v_pk_add_f32 v[16:17], v[16:17], v[226:227]
	v_pk_add_f32 v[18:19], v[18:19], v[228:229]
	s_waitcnt vmcnt(0)
	v_lshlrev_b32_e32 v226, 16, v218
	v_and_b32_e32 v227, 0xffff0000, v218
	v_lshlrev_b32_e32 v228, 16, v219
	v_and_b32_e32 v229, 0xffff0000, v219
	v_pk_add_f32 v[12:13], v[12:13], v[226:227]
	v_pk_add_f32 v[14:15], v[14:15], v[228:229]
	v_lshlrev_b32_e32 v226, 16, v220
	v_and_b32_e32 v227, 0xffff0000, v220
	v_lshlrev_b32_e32 v228, 16, v221
	v_and_b32_e32 v229, 0xffff0000, v221
	v_pk_add_f32 v[8:9], v[8:9], v[226:227]
	v_pk_add_f32 v[10:11], v[10:11], v[228:229]
	v_lshlrev_b32_e32 v226, 16, v222
	v_and_b32_e32 v227, 0xffff0000, v222
	v_lshlrev_b32_e32 v228, 16, v223
	v_and_b32_e32 v229, 0xffff0000, v223
	v_pk_add_f32 v[4:5], v[4:5], v[226:227]
	v_pk_add_f32 v[6:7], v[6:7], v[228:229]
	v_lshlrev_b32_e32 v226, 16, v224
	v_and_b32_e32 v227, 0xffff0000, v224
	v_lshlrev_b32_e32 v228, 16, v225
	v_and_b32_e32 v229, 0xffff0000, v225
	v_pk_add_f32 v[0:1], v[0:1], v[226:227]
	v_pk_add_f32 v[2:3], v[2:3], v[228:229]
	v_lshl_add_u64 v[162:163], s[20:21], 0, v[168:169]
	v_or_b32_e32 v172, 0x100, v164
	v_mov_b32_e32 v173, v165
	v_lshl_add_u64 v[162:163], s[20:21], 0, v[172:173]
	v_lshl_add_u64 v[178:179], s[58:59], 0, v[164:165]
	v_or_b32_e32 v164, 0x120, v164
	v_lshl_add_u64 v[162:163], s[20:21], 0, v[164:165]
	v_and_b32_e32 v162, 64, v174
	v_xor_b32_e32 v161, 16, v174
	v_add_u32_e32 v162, 64, v162
	v_xor_b32_e32 v163, 32, v174
	v_cmp_lt_i32_e32 vcc, v161, v162
	v_lshl_add_u64 v[168:169], s[58:59], 0, v[168:169]
	v_lshlrev_b32_e32 v182, 16, v166
	v_and_b32_e32 v183, 0xffff0000, v166
	v_lshlrev_b32_e32 v166, 16, v167
	v_and_b32_e32 v167, 0xffff0000, v167
	v_lshlrev_b32_e32 v166, 16, v170
	v_and_b32_e32 v167, 0xffff0000, v170
	v_lshlrev_b32_e32 v182, 16, v176
	v_and_b32_e32 v183, 0xffff0000, v176
	v_lshlrev_b32_e32 v184, 16, v180
	v_and_b32_e32 v185, 0xffff0000, v180
	v_cndmask_b32_e32 v161, v174, v161, vcc
	v_cmp_lt_i32_e32 vcc, v163, v162
	v_lshlrev_b32_e32 v170, 16, v171
	v_and_b32_e32 v171, 0xffff0000, v171
	v_cvt_pk_bf16_f32 v186, v124, v125
	v_mul_f32_e32 v125, v125, v125
	v_mov_b32_e32 v166, v112
	v_mov_b32_e32 v167, v113
	v_cvt_pk_bf16_f32 v112, v120, v121
	v_mul_f32_e32 v121, v121, v121
	v_cndmask_b32_e32 v163, v174, v163, vcc
	v_lshlrev_b32_e32 v176, 16, v177
	v_and_b32_e32 v177, 0xffff0000, v177
	v_fmac_f32_e32 v125, v124, v124
	v_mul_f32_e32 v124, v117, v117
	v_fmac_f32_e32 v121, v120, v120
	v_lshlrev_b32_e32 v162, 2, v161
	v_lshlrev_b32_e32 v161, 2, v163
	v_lshlrev_b32_e32 v180, 16, v181
	v_and_b32_e32 v181, 0xffff0000, v181
	v_mul_f32_e32 v163, v167, v167
	v_fmac_f32_e32 v125, v126, v126
	v_fmac_f32_e32 v124, v116, v116
	v_fmac_f32_e32 v121, v122, v122
	v_cvt_pk_bf16_f32 v113, v122, v123
	v_fmac_f32_e32 v163, v166, v166
	v_fmac_f32_e32 v125, v127, v127
	v_fmac_f32_e32 v124, v118, v118
	v_fmac_f32_e32 v121, v123, v123
	global_store_dwordx2 v[168:169], v[112:113], off
	v_fmac_f32_e32 v163, v114, v114
	v_fmac_f32_e32 v124, v119, v119
	v_add_f32_e32 v112, v125, v121
	v_add_f32_e32 v112, v112, v124
	v_fmac_f32_e32 v163, v115, v115
	v_add_f32_e32 v120, v112, v163
	ds_bpermute_b32 v121, v162, v120
	v_cvt_pk_bf16_f32 v112, v116, v117
	v_cvt_pk_bf16_f32 v113, v118, v119
	v_lshl_add_u64 v[116:117], s[58:59], 0, v[172:173]
	global_store_dwordx2 v[116:117], v[112:113], off
	s_waitcnt lgkmcnt(0)
	v_add_f32_e32 v112, v120, v121
	ds_bpermute_b32 v113, v161, v112
	v_cvt_pk_bf16_f32 v187, v126, v127
	v_cvt_pk_bf16_f32 v116, v166, v167
	v_cvt_pk_bf16_f32 v117, v114, v115
	v_lshl_add_u64 v[114:115], s[58:59], 0, v[164:165]
	global_store_dwordx2 v[178:179], v[186:187], off
	global_store_dwordx2 v[114:115], v[116:117], off
	s_and_saveexec_b64 s[18:19], s[0:1]
	s_cbranch_execz .LBB0_927
	s_waitcnt lgkmcnt(0)
	v_add_f32_e32 v112, v112, v113
	ds_add_f32 v145, v112
